# v46 + peeled relaxed first half K-iteration on all 10 non-slab GEMM sites
# baseline (speedup 1.0000x reference)
.LBB0_682:
	s_add_u32 s31, s40, 0x4000
	v_lshrrev_b32_e32 v18, 1, v12
	v_readlane_b32 s18, v253, 46
	s_addc_u32 s34, s41, 0
	v_and_b32_e32 v18, 24, v18
	s_lshl_b32 s0, s0, 5
	v_mov_b32_e32 v213, v203
	v_readlane_b32 s19, v253, 47
	v_and_b32_e32 v13, 15, v12
	v_lshlrev_b32_e32 v19, 1, v18
	v_lshlrev_b32_e32 v12, 2, v12
	s_and_b32 s3, s0, 0x60
	s_add_i32 m0, s27, 0x18000
	v_lshl_add_u64 v[2:3], v[2:3], 0, s[80:81]
	v_lshl_add_u64 v[14:15], s[18:19], 0, v[212:213]
	v_mov_b32_e32 v211, v203
	v_lshl_or_b32 v204, s1, 6, v13
	v_lshl_or_b32 v13, v13, 6, v19
	s_lshl_b32 s1, s1, 13
	v_and_b32_e32 v12, 32, v12
	s_lshl_b32 s0, s3, 7
	s_waitcnt vmcnt(2)
	s_barrier
	global_load_lds_dwordx4 v[2:3], off
	v_lshl_add_u64 v[2:3], v[4:5], 0, s[80:81]
	s_add_i32 m0, s27, 0x1a000
	s_add_i32 s35, s27, 0x8000
	s_add_i32 s36, s27, 0xa000
	v_lshl_add_u64 v[16:17], s[18:19], 0, v[210:211]
	v_bitop3_b32 v205, v13, s0, v12 bitop3:0xde
	v_add_u32_e32 v205, 0x10000, v205
	global_load_lds_dwordx4 v[2:3], off
	v_lshl_add_u64 v[2:3], v[14:15], 0, s[80:81]
	s_mov_b32 m0, s35
	s_add_u32 s0, s20, 0x100080
	v_bitop3_b32 v19, v13, s1, v12 bitop3:0xde
	global_load_lds_dwordx4 v[2:3], off
	v_lshl_add_u64 v[2:3], v[16:17], 0, s[80:81]
	s_mov_b32 m0, s36
	s_addc_u32 s1, s21, 0
	global_load_lds_dwordx4 v[2:3], off
	s_add_i32 m0, s27, 0x1c000
	v_lshl_add_u64 v[2:3], s[0:1], 0, v[202:203]
	global_load_lds_dwordx4 v[2:3], off
	v_lshl_add_u64 v[2:3], s[0:1], 0, v[208:209]
	s_add_i32 m0, s27, 0x1e000
	s_cmpk_lt_u32 s2, 0x100
	global_load_lds_dwordx4 v[2:3], off
	v_lshlrev_b32_e32 v2, 16, v10
	v_and_b32_e32 v2, 0xfffe0000, v2
	v_lshl_add_u32 v2, v9, 13, v2
	v_and_b32_e32 v3, 1, v10
	v_lshl_or_b32 v2, v3, 6, v2
	v_lshl_add_u32 v214, v11, 1, v2
	v_lshlrev_b32_e32 v2, 16, v6
	v_and_b32_e32 v2, 0xfffe0000, v2
	s_waitcnt vmcnt(6)
	v_lshl_add_u32 v2, v7, 13, v2
	v_and_b32_e32 v3, 1, v6
	v_lshl_or_b32 v2, v3, 6, v2
	v_readlane_b32 s0, v253, 50
	s_cselect_b64 s[6:7], -1, 0
	v_or_b32_e32 v238, s3, v18
	v_mov_b32_e32 v215, v203
	v_lshl_add_u32 v216, v8, 1, v2
	v_mov_b32_e32 v217, v203
	s_mov_b32 s37, 0
	v_add_u32_e32 v239, 0, v19
	v_readlane_b32 s39, v254, 44
	s_mov_b32 s38, s0
	s_barrier
	v_readlane_b32 s1, v253, 51
	s_mov_b32 s101, 0
	s_branch .LBB0_685

.LBB0_691:
	s_ashr_i32 s11, s10, 31
	s_lshl_b64 s[0:1], s[10:11], 21
	s_add_u32 s14, s78, s0
	s_addc_u32 s15, s79, s1
	s_and_b64 s[0:1], s[2:3], exec
	s_cselect_b32 s11, s15, s19
	s_cselect_b32 s49, s14, s18
	s_ashr_i32 s9, s8, 31
	s_lshl_b64 s[0:1], s[8:9], 21
	s_add_u32 s16, s24, s0
	s_addc_u32 s17, s25, s1
	s_and_b64 s[0:1], s[2:3], exec
	s_cselect_b32 s9, s17, s21
	s_cselect_b32 s58, s16, s20
	s_add_u32 s18, s18, 0x100080
	s_addc_u32 s19, s19, 0
	s_add_u32 s59, s20, 0x100
	v_mov_b32_e32 v2, 0
	s_addc_u32 s60, s21, 0
	s_mov_b32 s61, -2
	v_mov_b32_e32 v3, v2
	v_pk_mov_b32 v[4:5], v[2:3], v[2:3] op_sel:[0,1]
	v_pk_mov_b32 v[6:7], v[2:3], v[2:3] op_sel:[0,1]
	v_pk_mov_b32 v[8:9], v[2:3], v[2:3] op_sel:[0,1]
	v_pk_mov_b32 v[18:19], v[2:3], v[2:3] op_sel:[0,1]
	v_pk_mov_b32 v[20:21], v[2:3], v[2:3] op_sel:[0,1]
	v_pk_mov_b32 v[22:23], v[2:3], v[2:3] op_sel:[0,1]
	v_pk_mov_b32 v[24:25], v[2:3], v[2:3] op_sel:[0,1]
	v_pk_mov_b32 v[34:35], v[2:3], v[2:3] op_sel:[0,1]
	v_pk_mov_b32 v[36:37], v[2:3], v[2:3] op_sel:[0,1]
	v_pk_mov_b32 v[38:39], v[2:3], v[2:3] op_sel:[0,1]
	v_pk_mov_b32 v[40:41], v[2:3], v[2:3] op_sel:[0,1]
	v_pk_mov_b32 v[50:51], v[2:3], v[2:3] op_sel:[0,1]
	v_pk_mov_b32 v[52:53], v[2:3], v[2:3] op_sel:[0,1]
	v_pk_mov_b32 v[54:55], v[2:3], v[2:3] op_sel:[0,1]
	v_pk_mov_b32 v[56:57], v[2:3], v[2:3] op_sel:[0,1]
	v_pk_mov_b32 v[10:11], v[2:3], v[2:3] op_sel:[0,1]
	v_pk_mov_b32 v[12:13], v[2:3], v[2:3] op_sel:[0,1]
	v_pk_mov_b32 v[14:15], v[2:3], v[2:3] op_sel:[0,1]
	v_pk_mov_b32 v[16:17], v[2:3], v[2:3] op_sel:[0,1]
	v_pk_mov_b32 v[26:27], v[2:3], v[2:3] op_sel:[0,1]
	v_pk_mov_b32 v[28:29], v[2:3], v[2:3] op_sel:[0,1]
	v_pk_mov_b32 v[30:31], v[2:3], v[2:3] op_sel:[0,1]
	v_pk_mov_b32 v[32:33], v[2:3], v[2:3] op_sel:[0,1]
	v_pk_mov_b32 v[42:43], v[2:3], v[2:3] op_sel:[0,1]
	v_pk_mov_b32 v[44:45], v[2:3], v[2:3] op_sel:[0,1]
	v_pk_mov_b32 v[46:47], v[2:3], v[2:3] op_sel:[0,1]
	v_pk_mov_b32 v[48:49], v[2:3], v[2:3] op_sel:[0,1]
	v_pk_mov_b32 v[58:59], v[2:3], v[2:3] op_sel:[0,1]
	v_pk_mov_b32 v[60:61], v[2:3], v[2:3] op_sel:[0,1]
	v_pk_mov_b32 v[62:63], v[2:3], v[2:3] op_sel:[0,1]
	v_pk_mov_b32 v[64:65], v[2:3], v[2:3] op_sel:[0,1]
	v_pk_mov_b32 v[66:67], v[2:3], v[2:3] op_sel:[0,1]
	v_pk_mov_b32 v[68:69], v[2:3], v[2:3] op_sel:[0,1]
	v_pk_mov_b32 v[70:71], v[2:3], v[2:3] op_sel:[0,1]
	v_pk_mov_b32 v[72:73], v[2:3], v[2:3] op_sel:[0,1]
	v_pk_mov_b32 v[90:91], v[2:3], v[2:3] op_sel:[0,1]
	v_pk_mov_b32 v[92:93], v[2:3], v[2:3] op_sel:[0,1]
	v_pk_mov_b32 v[102:103], v[2:3], v[2:3] op_sel:[0,1]
	v_pk_mov_b32 v[104:105], v[2:3], v[2:3] op_sel:[0,1]
	v_pk_mov_b32 v[122:123], v[2:3], v[2:3] op_sel:[0,1]
	v_pk_mov_b32 v[124:125], v[2:3], v[2:3] op_sel:[0,1]
	v_pk_mov_b32 v[130:131], v[2:3], v[2:3] op_sel:[0,1]
	v_pk_mov_b32 v[132:133], v[2:3], v[2:3] op_sel:[0,1]
	v_pk_mov_b32 v[150:151], v[2:3], v[2:3] op_sel:[0,1]
	v_pk_mov_b32 v[152:153], v[2:3], v[2:3] op_sel:[0,1]
	v_pk_mov_b32 v[154:155], v[2:3], v[2:3] op_sel:[0,1]
	v_pk_mov_b32 v[156:157], v[2:3], v[2:3] op_sel:[0,1]
	v_pk_mov_b32 v[74:75], v[2:3], v[2:3] op_sel:[0,1]
	v_pk_mov_b32 v[76:77], v[2:3], v[2:3] op_sel:[0,1]
	v_pk_mov_b32 v[82:83], v[2:3], v[2:3] op_sel:[0,1]
	v_pk_mov_b32 v[84:85], v[2:3], v[2:3] op_sel:[0,1]
	v_pk_mov_b32 v[114:115], v[2:3], v[2:3] op_sel:[0,1]
	v_pk_mov_b32 v[116:117], v[2:3], v[2:3] op_sel:[0,1]
	v_pk_mov_b32 v[118:119], v[2:3], v[2:3] op_sel:[0,1]
	v_pk_mov_b32 v[120:121], v[2:3], v[2:3] op_sel:[0,1]
	v_pk_mov_b32 v[138:139], v[2:3], v[2:3] op_sel:[0,1]
	v_pk_mov_b32 v[140:141], v[2:3], v[2:3] op_sel:[0,1]
	v_pk_mov_b32 v[142:143], v[2:3], v[2:3] op_sel:[0,1]
	v_pk_mov_b32 v[144:145], v[2:3], v[2:3] op_sel:[0,1]
	v_pk_mov_b32 v[162:163], v[2:3], v[2:3] op_sel:[0,1]
	v_pk_mov_b32 v[164:165], v[2:3], v[2:3] op_sel:[0,1]
	v_pk_mov_b32 v[170:171], v[2:3], v[2:3] op_sel:[0,1]
	v_pk_mov_b32 v[172:173], v[2:3], v[2:3] op_sel:[0,1]
	s_cmp_eq_u32 s101, 0x80000001
	s_cbranch_scc0 .LBB0_692
	s_add_u32 s0, s18, 0xfff00080
	s_addc_u32 s1, s19, -1
	s_add_i32 s33, 0, 0x10000
	s_cmp_eq_u32 s61, 60
	s_cselect_b32 s23, s11, s1
	s_cselect_b32 s22, s49, s0
	s_cselect_b32 s21, s9, s60
	s_cselect_b32 s20, s58, s59
	s_add_i32 s55, 0, 0x14000
	ds_read_b128 v[78:81], v205
	ds_read_b128 v[86:89], v205 offset:1024
	ds_read_b128 v[94:97], v205 offset:2048
	ds_read_b128 v[98:101], v205 offset:3072
	ds_read_b128 v[106:109], v205 offset:16384
	ds_read_b128 v[110:113], v205 offset:17408
	ds_read_b128 v[126:129], v205 offset:18432
	ds_read_b128 v[134:137], v205 offset:19456
	s_add_i32 m0, s27, 0xc000
	ds_read_b128 v[146:149], v239
	ds_read_b128 v[158:161], v239 offset:1024
	ds_read_b128 v[166:169], v239 offset:2048
	ds_read_b128 v[174:177], v239 offset:3072
	ds_read_b128 v[178:181], v239 offset:4096
	ds_read_b128 v[182:185], v239 offset:5120
	ds_read_b128 v[186:189], v239 offset:6144
	ds_read_b128 v[190:193], v239 offset:7168
	global_load_lds_dwordx4 v214, s[18:19]
	s_add_i32 m0, s27, 0xe000
	s_nop 0
	global_load_lds_dwordx4 v216, s[18:19]
	s_waitcnt vmcnt(24)
	s_waitcnt lgkmcnt(0)
	s_setprio 1
	s_barrier
	v_mfma_f32_16x16x32_bf16 v[170:173], v[78:81], v[146:149], v[170:173]
	v_mfma_f32_16x16x32_bf16 v[162:165], v[94:97], v[146:149], v[162:165]
	v_mfma_f32_16x16x32_bf16 v[142:145], v[78:81], v[166:169], v[142:145]
	v_mfma_f32_16x16x32_bf16 v[138:141], v[94:97], v[166:169], v[138:141]
	v_mfma_f32_16x16x32_bf16 v[118:121], v[78:81], v[178:181], v[118:121]
	v_mfma_f32_16x16x32_bf16 v[114:117], v[94:97], v[178:181], v[114:117]
	v_mfma_f32_16x16x32_bf16 v[82:85], v[78:81], v[186:189], v[82:85]
	v_mfma_f32_16x16x32_bf16 v[74:77], v[94:97], v[186:189], v[74:77]
	v_mfma_f32_16x16x32_bf16 v[170:173], v[86:89], v[158:161], v[170:173]
	v_mfma_f32_16x16x32_bf16 v[162:165], v[98:101], v[158:161], v[162:165]
	v_mfma_f32_16x16x32_bf16 v[142:145], v[86:89], v[174:177], v[142:145]
	v_mfma_f32_16x16x32_bf16 v[138:141], v[98:101], v[174:177], v[138:141]
	v_mfma_f32_16x16x32_bf16 v[118:121], v[86:89], v[182:185], v[118:121]
	v_mfma_f32_16x16x32_bf16 v[114:117], v[98:101], v[182:185], v[114:117]
	v_mfma_f32_16x16x32_bf16 v[82:85], v[86:89], v[190:193], v[82:85]
	v_mfma_f32_16x16x32_bf16 v[74:77], v[98:101], v[190:193], v[74:77]
	v_mfma_f32_16x16x32_bf16 v[154:157], v[106:109], v[146:149], v[154:157]
	v_mfma_f32_16x16x32_bf16 v[130:133], v[106:109], v[166:169], v[130:133]
	v_mfma_f32_16x16x32_bf16 v[122:125], v[126:129], v[166:169], v[122:125]
	v_mfma_f32_16x16x32_bf16 v[102:105], v[106:109], v[178:181], v[102:105]
	v_mfma_f32_16x16x32_bf16 v[90:93], v[126:129], v[178:181], v[90:93]
	v_mfma_f32_16x16x32_bf16 v[70:73], v[106:109], v[186:189], v[70:73]
	v_mfma_f32_16x16x32_bf16 v[66:69], v[126:129], v[186:189], v[66:69]
	v_mfma_f32_16x16x32_bf16 v[154:157], v[110:113], v[158:161], v[154:157]
	v_mfma_f32_16x16x32_bf16 v[146:149], v[126:129], v[146:149], v[150:153]
	v_mfma_f32_16x16x32_bf16 v[130:133], v[110:113], v[174:177], v[130:133]
	v_mfma_f32_16x16x32_bf16 v[122:125], v[134:137], v[174:177], v[122:125]
	v_mfma_f32_16x16x32_bf16 v[102:105], v[110:113], v[182:185], v[102:105]
	v_mfma_f32_16x16x32_bf16 v[90:93], v[134:137], v[182:185], v[90:93]
	v_mfma_f32_16x16x32_bf16 v[70:73], v[110:113], v[190:193], v[70:73]
	v_mfma_f32_16x16x32_bf16 v[66:69], v[134:137], v[190:193], v[66:69]
	v_mfma_f32_16x16x32_bf16 v[146:149], v[134:137], v[158:161], v[146:149]
	s_barrier
	s_setprio 0
	s_add_i32 s0, s33, s26
	s_mov_b32 m0, s0
	ds_read_b128 v[150:153], v239 offset:16384
	ds_read_b128 v[158:161], v239 offset:17408
	ds_read_b128 v[166:169], v239 offset:18432
	ds_read_b128 v[174:177], v239 offset:19456
	ds_read_b128 v[178:181], v239 offset:20480
	ds_read_b128 v[182:185], v239 offset:21504
	ds_read_b128 v[186:189], v239 offset:22528
	ds_read_b128 v[190:193], v239 offset:23552
	global_load_lds_dwordx4 v202, s[20:21]
	s_add_i32 m0, s0, 0x2000
	s_add_u32 s0, s20, 0x100000
	s_addc_u32 s1, s21, 0
	s_add_i32 s33, s55, s26
	global_load_lds_dwordx4 v208, s[20:21]
	s_mov_b32 m0, s33
	s_nop 0
	global_load_lds_dwordx4 v202, s[0:1]
	s_add_i32 m0, s33, 0x2000
	s_nop 0
	global_load_lds_dwordx4 v208, s[0:1]
	s_mov_b32 m0, s27
	s_nop 0
	global_load_lds_dwordx4 v212, s[22:23]
	s_mov_b32 m0, s28
	s_nop 0
	global_load_lds_dwordx4 v210, s[22:23]
	s_waitcnt vmcnt(24)
	s_waitcnt lgkmcnt(0)
	s_setprio 1
	s_barrier
	v_mfma_f32_16x16x32_bf16 v[62:65], v[78:81], v[150:153], v[62:65]
	v_mfma_f32_16x16x32_bf16 v[58:61], v[94:97], v[150:153], v[58:61]
	v_mfma_f32_16x16x32_bf16 v[46:49], v[78:81], v[166:169], v[46:49]
	v_mfma_f32_16x16x32_bf16 v[42:45], v[94:97], v[166:169], v[42:45]
	v_mfma_f32_16x16x32_bf16 v[30:33], v[78:81], v[178:181], v[30:33]
	v_mfma_f32_16x16x32_bf16 v[26:29], v[94:97], v[178:181], v[26:29]
	v_mfma_f32_16x16x32_bf16 v[14:17], v[78:81], v[186:189], v[14:17]
	v_mfma_f32_16x16x32_bf16 v[10:13], v[94:97], v[186:189], v[10:13]
	v_mfma_f32_16x16x32_bf16 v[62:65], v[86:89], v[158:161], v[62:65]
	v_mfma_f32_16x16x32_bf16 v[58:61], v[98:101], v[158:161], v[58:61]
	v_mfma_f32_16x16x32_bf16 v[46:49], v[86:89], v[174:177], v[46:49]
	v_mfma_f32_16x16x32_bf16 v[42:45], v[98:101], v[174:177], v[42:45]
	v_mfma_f32_16x16x32_bf16 v[30:33], v[86:89], v[182:185], v[30:33]
	v_mfma_f32_16x16x32_bf16 v[26:29], v[98:101], v[182:185], v[26:29]
	v_mfma_f32_16x16x32_bf16 v[14:17], v[86:89], v[190:193], v[14:17]
	v_mfma_f32_16x16x32_bf16 v[10:13], v[98:101], v[190:193], v[10:13]
	v_mfma_f32_16x16x32_bf16 v[54:57], v[106:109], v[150:153], v[54:57]
	v_mfma_f32_16x16x32_bf16 v[50:53], v[126:129], v[150:153], v[50:53]
	v_mfma_f32_16x16x32_bf16 v[38:41], v[106:109], v[166:169], v[38:41]
	v_mfma_f32_16x16x32_bf16 v[34:37], v[126:129], v[166:169], v[34:37]
	v_mfma_f32_16x16x32_bf16 v[22:25], v[106:109], v[178:181], v[22:25]
	v_mfma_f32_16x16x32_bf16 v[18:21], v[126:129], v[178:181], v[18:21]
	v_mfma_f32_16x16x32_bf16 v[6:9], v[106:109], v[186:189], v[6:9]
	v_mfma_f32_16x16x32_bf16 v[2:5], v[126:129], v[186:189], v[2:5]
	v_mfma_f32_16x16x32_bf16 v[54:57], v[110:113], v[158:161], v[54:57]
	v_mfma_f32_16x16x32_bf16 v[50:53], v[134:137], v[158:161], v[50:53]
	v_mfma_f32_16x16x32_bf16 v[38:41], v[110:113], v[174:177], v[38:41]
	v_mfma_f32_16x16x32_bf16 v[34:37], v[134:137], v[174:177], v[34:37]
	v_mfma_f32_16x16x32_bf16 v[22:25], v[110:113], v[182:185], v[22:25]
	v_mfma_f32_16x16x32_bf16 v[18:21], v[134:137], v[182:185], v[18:21]
	v_mfma_f32_16x16x32_bf16 v[6:9], v[110:113], v[190:193], v[6:9]
	v_mfma_f32_16x16x32_bf16 v[2:5], v[134:137], v[190:193], v[2:5]
	s_barrier
	s_setprio 0
	s_branch .Lpeel_mid_1

.Lpeel_mid_1:
	s_add_i32 s33, 0, 0x18000
	s_add_i32 s55, 0, 0x1c000
	ds_read_b128 v[78:81], v205 offset:32768
	ds_read_b128 v[86:89], v205 offset:33792
	ds_read_b128 v[94:97], v205 offset:34816
	ds_read_b128 v[98:101], v205 offset:35840
	ds_read_b128 v[106:109], v205 offset:49152
	ds_read_b128 v[110:113], v205 offset:50176
	ds_read_b128 v[126:129], v205 offset:51200
	ds_read_b128 v[134:137], v205 offset:52224
	s_add_u32 s0, s22, 0x100000
	s_addc_u32 s1, s23, 0
	s_mov_b32 m0, s29
	ds_read_b128 v[150:153], v239 offset:32768
	ds_read_b128 v[158:161], v239 offset:33792
	ds_read_b128 v[166:169], v239 offset:34816
	ds_read_b128 v[174:177], v239 offset:35840
	ds_read_b128 v[178:181], v239 offset:36864
	ds_read_b128 v[182:185], v239 offset:37888
	ds_read_b128 v[186:189], v239 offset:38912
	ds_read_b128 v[190:193], v239 offset:39936
	global_load_lds_dwordx4 v212, s[0:1]
	s_mov_b32 m0, s30
	s_nop 0
	global_load_lds_dwordx4 v210, s[0:1]
	s_waitcnt vmcnt(8)
	s_waitcnt lgkmcnt(0)
	s_setprio 1
	s_barrier
	v_mfma_f32_16x16x32_bf16 v[170:173], v[78:81], v[150:153], v[170:173]
	v_mfma_f32_16x16x32_bf16 v[162:165], v[94:97], v[150:153], v[162:165]
	v_mfma_f32_16x16x32_bf16 v[142:145], v[78:81], v[166:169], v[142:145]
	v_mfma_f32_16x16x32_bf16 v[138:141], v[94:97], v[166:169], v[138:141]
	v_mfma_f32_16x16x32_bf16 v[118:121], v[78:81], v[178:181], v[118:121]
	v_mfma_f32_16x16x32_bf16 v[114:117], v[94:97], v[178:181], v[114:117]
	v_mfma_f32_16x16x32_bf16 v[82:85], v[78:81], v[186:189], v[82:85]
	v_mfma_f32_16x16x32_bf16 v[74:77], v[94:97], v[186:189], v[74:77]
	v_mfma_f32_16x16x32_bf16 v[170:173], v[86:89], v[158:161], v[170:173]
	v_mfma_f32_16x16x32_bf16 v[162:165], v[98:101], v[158:161], v[162:165]
	v_mfma_f32_16x16x32_bf16 v[142:145], v[86:89], v[174:177], v[142:145]
	v_mfma_f32_16x16x32_bf16 v[138:141], v[98:101], v[174:177], v[138:141]
	v_mfma_f32_16x16x32_bf16 v[118:121], v[86:89], v[182:185], v[118:121]
	v_mfma_f32_16x16x32_bf16 v[114:117], v[98:101], v[182:185], v[114:117]
	v_mfma_f32_16x16x32_bf16 v[82:85], v[86:89], v[190:193], v[82:85]
	v_mfma_f32_16x16x32_bf16 v[74:77], v[98:101], v[190:193], v[74:77]
	v_mfma_f32_16x16x32_bf16 v[154:157], v[106:109], v[150:153], v[154:157]
	v_mfma_f32_16x16x32_bf16 v[146:149], v[126:129], v[150:153], v[146:149]
	v_mfma_f32_16x16x32_bf16 v[130:133], v[106:109], v[166:169], v[130:133]
	v_mfma_f32_16x16x32_bf16 v[122:125], v[126:129], v[166:169], v[122:125]
	v_mfma_f32_16x16x32_bf16 v[102:105], v[106:109], v[178:181], v[102:105]
	v_mfma_f32_16x16x32_bf16 v[90:93], v[126:129], v[178:181], v[90:93]
	v_mfma_f32_16x16x32_bf16 v[70:73], v[106:109], v[186:189], v[70:73]
	v_mfma_f32_16x16x32_bf16 v[66:69], v[126:129], v[186:189], v[66:69]
	v_mfma_f32_16x16x32_bf16 v[154:157], v[110:113], v[158:161], v[154:157]
	v_mfma_f32_16x16x32_bf16 v[150:153], v[134:137], v[158:161], v[146:149]
	v_mfma_f32_16x16x32_bf16 v[130:133], v[110:113], v[174:177], v[130:133]
	v_mfma_f32_16x16x32_bf16 v[122:125], v[134:137], v[174:177], v[122:125]
	v_mfma_f32_16x16x32_bf16 v[102:105], v[110:113], v[182:185], v[102:105]
	v_mfma_f32_16x16x32_bf16 v[90:93], v[134:137], v[182:185], v[90:93]
	v_mfma_f32_16x16x32_bf16 v[70:73], v[110:113], v[190:193], v[70:73]
	v_mfma_f32_16x16x32_bf16 v[66:69], v[134:137], v[190:193], v[66:69]
	s_barrier
	s_setprio 0
	s_add_i32 s0, s33, s26
	s_add_u32 s100, s20, 0x80
	s_addc_u32 s101, s21, 0
	s_mov_b32 m0, s0
	ds_read_b128 v[146:149], v239 offset:49152
	ds_read_b128 v[158:161], v239 offset:50176
	ds_read_b128 v[166:169], v239 offset:51200
	ds_read_b128 v[174:177], v239 offset:52224
	ds_read_b128 v[178:181], v239 offset:53248
	ds_read_b128 v[182:185], v239 offset:54272
	ds_read_b128 v[186:189], v239 offset:55296
	ds_read_b128 v[190:193], v239 offset:56320
	global_load_lds_dwordx4 v202, s[100:101]
	s_add_i32 m0, s0, 0x2000
	s_add_u32 s100, s20, 0x80
	s_addc_u32 s101, s21, 0
	s_add_u32 s0, s20, 0x100080
	s_addc_u32 s1, s21, 0
	s_add_i32 s20, s55, s26
	global_load_lds_dwordx4 v208, s[100:101]
	s_mov_b32 m0, s20
	s_nop 0
	global_load_lds_dwordx4 v202, s[0:1]
	s_add_i32 m0, s20, 0x2000
	s_nop 0
	global_load_lds_dwordx4 v208, s[0:1]
	s_add_u32 s100, s22, 0x80
	s_addc_u32 s101, s23, 0
	s_mov_b32 m0, s35
	s_nop 0
	global_load_lds_dwordx4 v212, s[100:101]
	s_add_u32 s100, s22, 0x80
	s_addc_u32 s101, s23, 0
	s_mov_b32 m0, s36
	s_nop 0
	global_load_lds_dwordx4 v210, s[100:101]
	s_waitcnt vmcnt(8)
	s_waitcnt lgkmcnt(0)
	s_setprio 1
	s_barrier
	v_mfma_f32_16x16x32_bf16 v[62:65], v[78:81], v[146:149], v[62:65]
	v_mfma_f32_16x16x32_bf16 v[58:61], v[94:97], v[146:149], v[58:61]
	v_mfma_f32_16x16x32_bf16 v[46:49], v[78:81], v[166:169], v[46:49]
	v_mfma_f32_16x16x32_bf16 v[42:45], v[94:97], v[166:169], v[42:45]
	v_mfma_f32_16x16x32_bf16 v[30:33], v[78:81], v[178:181], v[30:33]
	v_mfma_f32_16x16x32_bf16 v[26:29], v[94:97], v[178:181], v[26:29]
	v_mfma_f32_16x16x32_bf16 v[14:17], v[78:81], v[186:189], v[14:17]
	v_mfma_f32_16x16x32_bf16 v[10:13], v[94:97], v[186:189], v[10:13]
	v_mfma_f32_16x16x32_bf16 v[62:65], v[86:89], v[158:161], v[62:65]
	v_mfma_f32_16x16x32_bf16 v[58:61], v[98:101], v[158:161], v[58:61]
	v_mfma_f32_16x16x32_bf16 v[46:49], v[86:89], v[174:177], v[46:49]
	v_mfma_f32_16x16x32_bf16 v[42:45], v[98:101], v[174:177], v[42:45]
	v_mfma_f32_16x16x32_bf16 v[30:33], v[86:89], v[182:185], v[30:33]
	v_mfma_f32_16x16x32_bf16 v[26:29], v[98:101], v[182:185], v[26:29]
	v_mfma_f32_16x16x32_bf16 v[14:17], v[86:89], v[190:193], v[14:17]
	v_mfma_f32_16x16x32_bf16 v[10:13], v[98:101], v[190:193], v[10:13]
	v_mfma_f32_16x16x32_bf16 v[54:57], v[106:109], v[146:149], v[54:57]
	v_mfma_f32_16x16x32_bf16 v[50:53], v[126:129], v[146:149], v[50:53]
	v_mfma_f32_16x16x32_bf16 v[38:41], v[106:109], v[166:169], v[38:41]
	v_mfma_f32_16x16x32_bf16 v[34:37], v[126:129], v[166:169], v[34:37]
	v_mfma_f32_16x16x32_bf16 v[22:25], v[106:109], v[178:181], v[22:25]
	v_mfma_f32_16x16x32_bf16 v[18:21], v[126:129], v[178:181], v[18:21]
	v_mfma_f32_16x16x32_bf16 v[6:9], v[106:109], v[186:189], v[6:9]
	v_mfma_f32_16x16x32_bf16 v[2:5], v[126:129], v[186:189], v[2:5]
	v_mfma_f32_16x16x32_bf16 v[54:57], v[110:113], v[158:161], v[54:57]
	v_mfma_f32_16x16x32_bf16 v[50:53], v[134:137], v[158:161], v[50:53]
	v_mfma_f32_16x16x32_bf16 v[38:41], v[110:113], v[174:177], v[38:41]
	v_mfma_f32_16x16x32_bf16 v[34:37], v[134:137], v[174:177], v[34:37]
	v_mfma_f32_16x16x32_bf16 v[22:25], v[110:113], v[182:185], v[22:25]
	v_mfma_f32_16x16x32_bf16 v[18:21], v[134:137], v[182:185], v[18:21]
	v_mfma_f32_16x16x32_bf16 v[6:9], v[110:113], v[190:193], v[6:9]
	v_mfma_f32_16x16x32_bf16 v[2:5], v[134:137], v[190:193], v[2:5]
	s_barrier
	s_setprio 0
	s_add_i32 s61, s61, 2
	s_add_u32 s18, s18, 0x100
	s_addc_u32 s19, s19, 0
	s_add_u32 s59, s59, 0x100
	s_addc_u32 s60, s60, 0
	s_cmp_gt_u32 s61, 61
	s_cbranch_scc0 .LBB0_692
	s_mov_b32 s101, 0x80000001
	s_and_b64 vcc, exec, s[6:7]
	s_cbranch_vccz .LBB0_695
	s_barrier

.LBB0_956:
	s_add_u32 s29, s40, 0xa000
	v_lshrrev_b32_e32 v20, 1, v14
	v_readlane_b32 s4, v253, 52
	s_addc_u32 s30, s41, 0
	v_and_b32_e32 v20, 24, v20
	s_lshl_b32 s0, s0, 5
	v_mov_b32_e32 v213, v203
	v_readlane_b32 s5, v253, 53
	v_and_b32_e32 v15, 15, v14
	v_lshlrev_b32_e32 v21, 1, v20
	v_lshlrev_b32_e32 v14, 2, v14
	s_and_b32 s3, s0, 0x60
	s_add_i32 m0, s25, 0x18000
	v_lshl_add_u64 v[2:3], v[2:3], 0, s[80:81]
	v_lshl_add_u64 v[16:17], s[4:5], 0, v[212:213]
	v_mov_b32_e32 v211, v203
	v_lshl_or_b32 v204, s1, 6, v15
	v_lshl_or_b32 v15, v15, 6, v21
	s_lshl_b32 s1, s1, 13
	v_and_b32_e32 v14, 32, v14
	s_lshl_b32 s0, s3, 7
	s_waitcnt vmcnt(2)
	s_barrier
	global_load_lds_dwordx4 v[2:3], off
	v_lshl_add_u64 v[2:3], v[4:5], 0, s[80:81]
	s_add_i32 m0, s25, 0x1a000
	s_add_i32 s31, s25, 0x8000
	s_add_i32 s34, s25, 0xa000
	v_lshl_add_u64 v[18:19], s[4:5], 0, v[210:211]
	v_bitop3_b32 v205, v15, s0, v14 bitop3:0xde
	v_add_u32_e32 v205, 0x10000, v205
	global_load_lds_dwordx4 v[2:3], off
	v_lshl_add_u64 v[2:3], v[16:17], 0, s[80:81]
	s_mov_b32 m0, s31
	s_add_u32 s0, s16, 0x160080
	v_bitop3_b32 v21, v15, s1, v14 bitop3:0xde
	global_load_lds_dwordx4 v[2:3], off
	v_lshl_add_u64 v[2:3], v[18:19], 0, s[80:81]
	s_mov_b32 m0, s34
	s_addc_u32 s1, s17, 0
	global_load_lds_dwordx4 v[2:3], off
	s_add_i32 m0, s25, 0x1c000
	v_lshl_add_u64 v[2:3], s[0:1], 0, v[202:203]
	global_load_lds_dwordx4 v[2:3], off
	v_lshl_add_u64 v[2:3], s[0:1], 0, v[208:209]
	s_add_i32 m0, s25, 0x1e000
	v_or_b32_e32 v238, s3, v20
	global_load_lds_dwordx4 v[2:3], off
	s_movk_i32 s3, 0x1600
	s_cmpk_lt_u32 s2, 0x100
	v_lshrrev_b32_e32 v3, 1, v11
	v_mul_lo_u32 v2, v10, s3
	s_mov_b32 s2, 0x16000
	v_mad_u64_u32 v[2:3], s[0:1], v3, s2, v[2:3]
	v_or_b32_e32 v2, v2, v12
	v_add_lshl_u32 v2, v2, v13, 1
	v_mov_b32_e32 v3, v203
	s_mov_b64 s[6:7], 0x160080
	v_lshl_add_u64 v[214:215], v[2:3], 0, s[6:7]
	v_lshrrev_b32_e32 v3, 1, v6
	v_mul_lo_u32 v2, v7, s3
	v_mad_u64_u32 v[2:3], s[0:1], v3, s2, v[2:3]
	s_waitcnt vmcnt(6)
	v_or_b32_e32 v2, v2, v8
	v_add_lshl_u32 v2, v2, v9, 1
	v_mov_b32_e32 v3, v203
	v_readlane_b32 s0, v253, 50
	s_cselect_b64 s[10:11], -1, 0
	v_lshl_add_u64 v[216:217], v[2:3], 0, s[6:7]
	s_mov_b32 s35, 0
	v_add_u32_e32 v239, 0, v21
	v_readlane_b32 s39, v254, 44
	s_mov_b32 s38, s0
	s_mov_b64 s[2:3], s[4:5]
	s_barrier
	v_readlane_b32 s1, v253, 51
	s_mov_b32 s101, 0
	s_branch .LBB0_959

.LBB0_969:
	s_add_u32 s49, s16, 0x100
	v_mov_b32_e32 v2, 0
	s_addc_u32 s58, s17, 0
	s_mov_b32 s59, -2
	v_mov_b32_e32 v3, v2
	v_pk_mov_b32 v[4:5], v[2:3], v[2:3] op_sel:[0,1]
	v_pk_mov_b32 v[6:7], v[2:3], v[2:3] op_sel:[0,1]
	v_pk_mov_b32 v[8:9], v[2:3], v[2:3] op_sel:[0,1]
	v_pk_mov_b32 v[18:19], v[2:3], v[2:3] op_sel:[0,1]
	v_pk_mov_b32 v[20:21], v[2:3], v[2:3] op_sel:[0,1]
	v_pk_mov_b32 v[22:23], v[2:3], v[2:3] op_sel:[0,1]
	v_pk_mov_b32 v[24:25], v[2:3], v[2:3] op_sel:[0,1]
	v_pk_mov_b32 v[34:35], v[2:3], v[2:3] op_sel:[0,1]
	v_pk_mov_b32 v[36:37], v[2:3], v[2:3] op_sel:[0,1]
	v_pk_mov_b32 v[38:39], v[2:3], v[2:3] op_sel:[0,1]
	v_pk_mov_b32 v[40:41], v[2:3], v[2:3] op_sel:[0,1]
	v_pk_mov_b32 v[50:51], v[2:3], v[2:3] op_sel:[0,1]
	v_pk_mov_b32 v[52:53], v[2:3], v[2:3] op_sel:[0,1]
	v_pk_mov_b32 v[54:55], v[2:3], v[2:3] op_sel:[0,1]
	v_pk_mov_b32 v[56:57], v[2:3], v[2:3] op_sel:[0,1]
	v_pk_mov_b32 v[10:11], v[2:3], v[2:3] op_sel:[0,1]
	v_pk_mov_b32 v[12:13], v[2:3], v[2:3] op_sel:[0,1]
	v_pk_mov_b32 v[14:15], v[2:3], v[2:3] op_sel:[0,1]
	v_pk_mov_b32 v[16:17], v[2:3], v[2:3] op_sel:[0,1]
	v_pk_mov_b32 v[26:27], v[2:3], v[2:3] op_sel:[0,1]
	v_pk_mov_b32 v[28:29], v[2:3], v[2:3] op_sel:[0,1]
	v_pk_mov_b32 v[30:31], v[2:3], v[2:3] op_sel:[0,1]
	v_pk_mov_b32 v[32:33], v[2:3], v[2:3] op_sel:[0,1]
	v_pk_mov_b32 v[42:43], v[2:3], v[2:3] op_sel:[0,1]
	v_pk_mov_b32 v[44:45], v[2:3], v[2:3] op_sel:[0,1]
	v_pk_mov_b32 v[46:47], v[2:3], v[2:3] op_sel:[0,1]
	v_pk_mov_b32 v[48:49], v[2:3], v[2:3] op_sel:[0,1]
	v_pk_mov_b32 v[58:59], v[2:3], v[2:3] op_sel:[0,1]
	v_pk_mov_b32 v[60:61], v[2:3], v[2:3] op_sel:[0,1]
	v_pk_mov_b32 v[62:63], v[2:3], v[2:3] op_sel:[0,1]
	v_pk_mov_b32 v[64:65], v[2:3], v[2:3] op_sel:[0,1]
	v_pk_mov_b32 v[66:67], v[2:3], v[2:3] op_sel:[0,1]
	v_pk_mov_b32 v[68:69], v[2:3], v[2:3] op_sel:[0,1]
	v_pk_mov_b32 v[70:71], v[2:3], v[2:3] op_sel:[0,1]
	v_pk_mov_b32 v[72:73], v[2:3], v[2:3] op_sel:[0,1]
	v_pk_mov_b32 v[90:91], v[2:3], v[2:3] op_sel:[0,1]
	v_pk_mov_b32 v[92:93], v[2:3], v[2:3] op_sel:[0,1]
	v_pk_mov_b32 v[102:103], v[2:3], v[2:3] op_sel:[0,1]
	v_pk_mov_b32 v[104:105], v[2:3], v[2:3] op_sel:[0,1]
	v_pk_mov_b32 v[122:123], v[2:3], v[2:3] op_sel:[0,1]
	v_pk_mov_b32 v[124:125], v[2:3], v[2:3] op_sel:[0,1]
	v_pk_mov_b32 v[130:131], v[2:3], v[2:3] op_sel:[0,1]
	v_pk_mov_b32 v[132:133], v[2:3], v[2:3] op_sel:[0,1]
	v_pk_mov_b32 v[150:151], v[2:3], v[2:3] op_sel:[0,1]
	v_pk_mov_b32 v[152:153], v[2:3], v[2:3] op_sel:[0,1]
	v_pk_mov_b32 v[154:155], v[2:3], v[2:3] op_sel:[0,1]
	v_pk_mov_b32 v[156:157], v[2:3], v[2:3] op_sel:[0,1]
	v_pk_mov_b32 v[74:75], v[2:3], v[2:3] op_sel:[0,1]
	v_pk_mov_b32 v[76:77], v[2:3], v[2:3] op_sel:[0,1]
	v_pk_mov_b32 v[86:87], v[2:3], v[2:3] op_sel:[0,1]
	v_pk_mov_b32 v[88:89], v[2:3], v[2:3] op_sel:[0,1]
	v_pk_mov_b32 v[114:115], v[2:3], v[2:3] op_sel:[0,1]
	v_pk_mov_b32 v[116:117], v[2:3], v[2:3] op_sel:[0,1]
	v_pk_mov_b32 v[118:119], v[2:3], v[2:3] op_sel:[0,1]
	v_pk_mov_b32 v[120:121], v[2:3], v[2:3] op_sel:[0,1]
	v_pk_mov_b32 v[138:139], v[2:3], v[2:3] op_sel:[0,1]
	v_pk_mov_b32 v[140:141], v[2:3], v[2:3] op_sel:[0,1]
	v_pk_mov_b32 v[142:143], v[2:3], v[2:3] op_sel:[0,1]
	v_pk_mov_b32 v[144:145], v[2:3], v[2:3] op_sel:[0,1]
	v_pk_mov_b32 v[162:163], v[2:3], v[2:3] op_sel:[0,1]
	v_pk_mov_b32 v[164:165], v[2:3], v[2:3] op_sel:[0,1]
	v_pk_mov_b32 v[170:171], v[2:3], v[2:3] op_sel:[0,1]
	v_pk_mov_b32 v[172:173], v[2:3], v[2:3] op_sel:[0,1]
	s_cmp_eq_u32 s101, 0x80000001
	s_cbranch_scc0 .LBB0_970
	s_add_u32 s16, s2, 0x100
	s_addc_u32 s17, s3, 0
	s_add_i32 s0, 0, 0x10000
	s_cmpk_eq_i32 s59, 0x54
	s_cselect_b32 s21, s7, s17
	s_cselect_b32 s20, s6, s16
	s_cselect_b32 s19, s15, s58
	s_cselect_b32 s18, s14, s49
	s_add_i32 s33, 0, 0x14000
	ds_read_b128 v[78:81], v205
	ds_read_b128 v[82:85], v205 offset:1024
	ds_read_b128 v[94:97], v205 offset:2048
	ds_read_b128 v[98:101], v205 offset:3072
	ds_read_b128 v[106:109], v205 offset:16384
	ds_read_b128 v[110:113], v205 offset:17408
	ds_read_b128 v[126:129], v205 offset:18432
	ds_read_b128 v[134:137], v205 offset:19456
	s_add_i32 m0, s25, 0xc000
	ds_read_b128 v[146:149], v239
	ds_read_b128 v[158:161], v239 offset:1024
	ds_read_b128 v[166:169], v239 offset:2048
	ds_read_b128 v[174:177], v239 offset:3072
	ds_read_b128 v[178:181], v239 offset:4096
	ds_read_b128 v[182:185], v239 offset:5120
	ds_read_b128 v[186:189], v239 offset:6144
	ds_read_b128 v[190:193], v239 offset:7168
	global_load_lds_dwordx4 v214, s[2:3]
	s_add_i32 m0, s25, 0xe000
	s_nop 0
	global_load_lds_dwordx4 v216, s[2:3]
	s_waitcnt vmcnt(24)
	s_waitcnt lgkmcnt(0)
	s_setprio 1
	s_barrier
	v_mfma_f32_16x16x32_bf16 v[170:173], v[78:81], v[146:149], v[170:173]
	v_mfma_f32_16x16x32_bf16 v[162:165], v[94:97], v[146:149], v[162:165]
	v_mfma_f32_16x16x32_bf16 v[142:145], v[78:81], v[166:169], v[142:145]
	v_mfma_f32_16x16x32_bf16 v[138:141], v[94:97], v[166:169], v[138:141]
	v_mfma_f32_16x16x32_bf16 v[118:121], v[78:81], v[178:181], v[118:121]
	v_mfma_f32_16x16x32_bf16 v[114:117], v[94:97], v[178:181], v[114:117]
	v_mfma_f32_16x16x32_bf16 v[86:89], v[78:81], v[186:189], v[86:89]
	v_mfma_f32_16x16x32_bf16 v[74:77], v[94:97], v[186:189], v[74:77]
	v_mfma_f32_16x16x32_bf16 v[170:173], v[82:85], v[158:161], v[170:173]
	v_mfma_f32_16x16x32_bf16 v[162:165], v[98:101], v[158:161], v[162:165]
	v_mfma_f32_16x16x32_bf16 v[142:145], v[82:85], v[174:177], v[142:145]
	v_mfma_f32_16x16x32_bf16 v[138:141], v[98:101], v[174:177], v[138:141]
	v_mfma_f32_16x16x32_bf16 v[118:121], v[82:85], v[182:185], v[118:121]
	v_mfma_f32_16x16x32_bf16 v[114:117], v[98:101], v[182:185], v[114:117]
	v_mfma_f32_16x16x32_bf16 v[86:89], v[82:85], v[190:193], v[86:89]
	v_mfma_f32_16x16x32_bf16 v[74:77], v[98:101], v[190:193], v[74:77]
	v_mfma_f32_16x16x32_bf16 v[154:157], v[106:109], v[146:149], v[154:157]
	v_mfma_f32_16x16x32_bf16 v[130:133], v[106:109], v[166:169], v[130:133]
	v_mfma_f32_16x16x32_bf16 v[122:125], v[126:129], v[166:169], v[122:125]
	v_mfma_f32_16x16x32_bf16 v[102:105], v[106:109], v[178:181], v[102:105]
	v_mfma_f32_16x16x32_bf16 v[90:93], v[126:129], v[178:181], v[90:93]
	v_mfma_f32_16x16x32_bf16 v[70:73], v[106:109], v[186:189], v[70:73]
	v_mfma_f32_16x16x32_bf16 v[66:69], v[126:129], v[186:189], v[66:69]
	v_mfma_f32_16x16x32_bf16 v[154:157], v[110:113], v[158:161], v[154:157]
	v_mfma_f32_16x16x32_bf16 v[146:149], v[126:129], v[146:149], v[150:153]
	v_mfma_f32_16x16x32_bf16 v[130:133], v[110:113], v[174:177], v[130:133]
	v_mfma_f32_16x16x32_bf16 v[122:125], v[134:137], v[174:177], v[122:125]
	v_mfma_f32_16x16x32_bf16 v[102:105], v[110:113], v[182:185], v[102:105]
	v_mfma_f32_16x16x32_bf16 v[90:93], v[134:137], v[182:185], v[90:93]
	v_mfma_f32_16x16x32_bf16 v[70:73], v[110:113], v[190:193], v[70:73]
	v_mfma_f32_16x16x32_bf16 v[66:69], v[134:137], v[190:193], v[66:69]
	v_mfma_f32_16x16x32_bf16 v[146:149], v[134:137], v[158:161], v[146:149]
	s_barrier
	s_setprio 0
	s_add_i32 s0, s0, s24
	s_mov_b32 m0, s0
	ds_read_b128 v[150:153], v239 offset:16384
	ds_read_b128 v[158:161], v239 offset:17408
	ds_read_b128 v[166:169], v239 offset:18432
	ds_read_b128 v[174:177], v239 offset:19456
	ds_read_b128 v[178:181], v239 offset:20480
	ds_read_b128 v[182:185], v239 offset:21504
	ds_read_b128 v[186:189], v239 offset:22528
	ds_read_b128 v[190:193], v239 offset:23552
	global_load_lds_dwordx4 v202, s[18:19]
	s_add_i32 m0, s0, 0x2000
	s_add_u32 s0, s18, 0x160000
	s_addc_u32 s1, s19, 0
	s_add_i32 s2, s33, s24
	global_load_lds_dwordx4 v208, s[18:19]
	s_mov_b32 m0, s2
	s_nop 0
	global_load_lds_dwordx4 v202, s[0:1]
	s_add_i32 m0, s2, 0x2000
	s_nop 0
	global_load_lds_dwordx4 v208, s[0:1]
	s_mov_b32 m0, s25
	s_nop 0
	global_load_lds_dwordx4 v212, s[20:21]
	s_mov_b32 m0, s26
	s_nop 0
	global_load_lds_dwordx4 v210, s[20:21]
	s_waitcnt vmcnt(24)
	s_waitcnt lgkmcnt(0)
	s_setprio 1
	s_barrier
	v_mfma_f32_16x16x32_bf16 v[62:65], v[78:81], v[150:153], v[62:65]
	v_mfma_f32_16x16x32_bf16 v[58:61], v[94:97], v[150:153], v[58:61]
	v_mfma_f32_16x16x32_bf16 v[46:49], v[78:81], v[166:169], v[46:49]
	v_mfma_f32_16x16x32_bf16 v[42:45], v[94:97], v[166:169], v[42:45]
	v_mfma_f32_16x16x32_bf16 v[30:33], v[78:81], v[178:181], v[30:33]
	v_mfma_f32_16x16x32_bf16 v[26:29], v[94:97], v[178:181], v[26:29]
	v_mfma_f32_16x16x32_bf16 v[14:17], v[78:81], v[186:189], v[14:17]
	v_mfma_f32_16x16x32_bf16 v[10:13], v[94:97], v[186:189], v[10:13]
	v_mfma_f32_16x16x32_bf16 v[62:65], v[82:85], v[158:161], v[62:65]
	v_mfma_f32_16x16x32_bf16 v[58:61], v[98:101], v[158:161], v[58:61]
	v_mfma_f32_16x16x32_bf16 v[46:49], v[82:85], v[174:177], v[46:49]
	v_mfma_f32_16x16x32_bf16 v[42:45], v[98:101], v[174:177], v[42:45]
	v_mfma_f32_16x16x32_bf16 v[30:33], v[82:85], v[182:185], v[30:33]
	v_mfma_f32_16x16x32_bf16 v[26:29], v[98:101], v[182:185], v[26:29]
	v_mfma_f32_16x16x32_bf16 v[14:17], v[82:85], v[190:193], v[14:17]
	v_mfma_f32_16x16x32_bf16 v[10:13], v[98:101], v[190:193], v[10:13]
	v_mfma_f32_16x16x32_bf16 v[54:57], v[106:109], v[150:153], v[54:57]
	v_mfma_f32_16x16x32_bf16 v[50:53], v[126:129], v[150:153], v[50:53]
	v_mfma_f32_16x16x32_bf16 v[38:41], v[106:109], v[166:169], v[38:41]
	v_mfma_f32_16x16x32_bf16 v[34:37], v[126:129], v[166:169], v[34:37]
	v_mfma_f32_16x16x32_bf16 v[22:25], v[106:109], v[178:181], v[22:25]
	v_mfma_f32_16x16x32_bf16 v[18:21], v[126:129], v[178:181], v[18:21]
	v_mfma_f32_16x16x32_bf16 v[6:9], v[106:109], v[186:189], v[6:9]
	v_mfma_f32_16x16x32_bf16 v[2:5], v[126:129], v[186:189], v[2:5]
	v_mfma_f32_16x16x32_bf16 v[54:57], v[110:113], v[158:161], v[54:57]
	v_mfma_f32_16x16x32_bf16 v[50:53], v[134:137], v[158:161], v[50:53]
	v_mfma_f32_16x16x32_bf16 v[38:41], v[110:113], v[174:177], v[38:41]
	v_mfma_f32_16x16x32_bf16 v[34:37], v[134:137], v[174:177], v[34:37]
	v_mfma_f32_16x16x32_bf16 v[22:25], v[110:113], v[182:185], v[22:25]
	v_mfma_f32_16x16x32_bf16 v[18:21], v[134:137], v[182:185], v[18:21]
	v_mfma_f32_16x16x32_bf16 v[6:9], v[110:113], v[190:193], v[6:9]
	v_mfma_f32_16x16x32_bf16 v[2:5], v[134:137], v[190:193], v[2:5]
	s_barrier
	s_setprio 0
	s_branch .Lpeel_mid_4

.Lpeel_mid_4:
	s_add_i32 s2, 0, 0x18000
	s_add_i32 s3, 0, 0x1c000
	ds_read_b128 v[78:81], v205 offset:32768
	ds_read_b128 v[82:85], v205 offset:33792
	ds_read_b128 v[94:97], v205 offset:34816
	ds_read_b128 v[98:101], v205 offset:35840
	ds_read_b128 v[106:109], v205 offset:49152
	ds_read_b128 v[110:113], v205 offset:50176
	ds_read_b128 v[126:129], v205 offset:51200
	ds_read_b128 v[134:137], v205 offset:52224
	s_add_u32 s0, s20, 0x160000
	s_addc_u32 s1, s21, 0
	s_mov_b32 m0, s27
	ds_read_b128 v[150:153], v239 offset:32768
	ds_read_b128 v[158:161], v239 offset:33792
	ds_read_b128 v[166:169], v239 offset:34816
	ds_read_b128 v[174:177], v239 offset:35840
	ds_read_b128 v[178:181], v239 offset:36864
	ds_read_b128 v[182:185], v239 offset:37888
	ds_read_b128 v[186:189], v239 offset:38912
	ds_read_b128 v[190:193], v239 offset:39936
	global_load_lds_dwordx4 v212, s[0:1]
	s_mov_b32 m0, s28
	s_nop 0
	global_load_lds_dwordx4 v210, s[0:1]
	s_waitcnt vmcnt(8)
	s_waitcnt lgkmcnt(0)
	s_setprio 1
	s_barrier
	v_mfma_f32_16x16x32_bf16 v[170:173], v[78:81], v[150:153], v[170:173]
	v_mfma_f32_16x16x32_bf16 v[162:165], v[94:97], v[150:153], v[162:165]
	v_mfma_f32_16x16x32_bf16 v[142:145], v[78:81], v[166:169], v[142:145]
	v_mfma_f32_16x16x32_bf16 v[138:141], v[94:97], v[166:169], v[138:141]
	v_mfma_f32_16x16x32_bf16 v[118:121], v[78:81], v[178:181], v[118:121]
	v_mfma_f32_16x16x32_bf16 v[114:117], v[94:97], v[178:181], v[114:117]
	v_mfma_f32_16x16x32_bf16 v[86:89], v[78:81], v[186:189], v[86:89]
	v_mfma_f32_16x16x32_bf16 v[74:77], v[94:97], v[186:189], v[74:77]
	v_mfma_f32_16x16x32_bf16 v[170:173], v[82:85], v[158:161], v[170:173]
	v_mfma_f32_16x16x32_bf16 v[162:165], v[98:101], v[158:161], v[162:165]
	v_mfma_f32_16x16x32_bf16 v[142:145], v[82:85], v[174:177], v[142:145]
	v_mfma_f32_16x16x32_bf16 v[138:141], v[98:101], v[174:177], v[138:141]
	v_mfma_f32_16x16x32_bf16 v[118:121], v[82:85], v[182:185], v[118:121]
	v_mfma_f32_16x16x32_bf16 v[114:117], v[98:101], v[182:185], v[114:117]
	v_mfma_f32_16x16x32_bf16 v[86:89], v[82:85], v[190:193], v[86:89]
	v_mfma_f32_16x16x32_bf16 v[74:77], v[98:101], v[190:193], v[74:77]
	v_mfma_f32_16x16x32_bf16 v[154:157], v[106:109], v[150:153], v[154:157]
	v_mfma_f32_16x16x32_bf16 v[146:149], v[126:129], v[150:153], v[146:149]
	v_mfma_f32_16x16x32_bf16 v[130:133], v[106:109], v[166:169], v[130:133]
	v_mfma_f32_16x16x32_bf16 v[122:125], v[126:129], v[166:169], v[122:125]
	v_mfma_f32_16x16x32_bf16 v[102:105], v[106:109], v[178:181], v[102:105]
	v_mfma_f32_16x16x32_bf16 v[90:93], v[126:129], v[178:181], v[90:93]
	v_mfma_f32_16x16x32_bf16 v[70:73], v[106:109], v[186:189], v[70:73]
	v_mfma_f32_16x16x32_bf16 v[66:69], v[126:129], v[186:189], v[66:69]
	v_mfma_f32_16x16x32_bf16 v[154:157], v[110:113], v[158:161], v[154:157]
	v_mfma_f32_16x16x32_bf16 v[150:153], v[134:137], v[158:161], v[146:149]
	v_mfma_f32_16x16x32_bf16 v[130:133], v[110:113], v[174:177], v[130:133]
	v_mfma_f32_16x16x32_bf16 v[122:125], v[134:137], v[174:177], v[122:125]
	v_mfma_f32_16x16x32_bf16 v[102:105], v[110:113], v[182:185], v[102:105]
	v_mfma_f32_16x16x32_bf16 v[90:93], v[134:137], v[182:185], v[90:93]
	v_mfma_f32_16x16x32_bf16 v[70:73], v[110:113], v[190:193], v[70:73]
	v_mfma_f32_16x16x32_bf16 v[66:69], v[134:137], v[190:193], v[66:69]
	s_barrier
	s_setprio 0
	s_add_i32 s0, s2, s24
	s_add_u32 s100, s18, 0x80
	s_addc_u32 s101, s19, 0
	s_mov_b32 m0, s0
	ds_read_b128 v[146:149], v239 offset:49152
	ds_read_b128 v[158:161], v239 offset:50176
	ds_read_b128 v[166:169], v239 offset:51200
	ds_read_b128 v[174:177], v239 offset:52224
	ds_read_b128 v[178:181], v239 offset:53248
	ds_read_b128 v[182:185], v239 offset:54272
	ds_read_b128 v[186:189], v239 offset:55296
	ds_read_b128 v[190:193], v239 offset:56320
	global_load_lds_dwordx4 v202, s[100:101]
	s_add_i32 m0, s0, 0x2000
	s_add_u32 s100, s18, 0x80
	s_addc_u32 s101, s19, 0
	s_add_u32 s0, s18, 0x160080
	s_addc_u32 s1, s19, 0
	s_add_i32 s2, s3, s24
	global_load_lds_dwordx4 v208, s[100:101]
	s_mov_b32 m0, s2
	s_nop 0
	global_load_lds_dwordx4 v202, s[0:1]
	s_add_i32 m0, s2, 0x2000
	s_nop 0
	global_load_lds_dwordx4 v208, s[0:1]
	s_add_u32 s100, s20, 0x80
	s_addc_u32 s101, s21, 0
	s_mov_b32 m0, s31
	s_nop 0
	global_load_lds_dwordx4 v212, s[100:101]
	s_add_u32 s100, s20, 0x80
	s_addc_u32 s101, s21, 0
	s_mov_b32 m0, s34
	s_nop 0
	global_load_lds_dwordx4 v210, s[100:101]
	s_waitcnt vmcnt(8)
	s_waitcnt lgkmcnt(0)
	s_setprio 1
	s_barrier
	v_mfma_f32_16x16x32_bf16 v[62:65], v[78:81], v[146:149], v[62:65]
	v_mfma_f32_16x16x32_bf16 v[58:61], v[94:97], v[146:149], v[58:61]
	v_mfma_f32_16x16x32_bf16 v[46:49], v[78:81], v[166:169], v[46:49]
	v_mfma_f32_16x16x32_bf16 v[42:45], v[94:97], v[166:169], v[42:45]
	v_mfma_f32_16x16x32_bf16 v[30:33], v[78:81], v[178:181], v[30:33]
	v_mfma_f32_16x16x32_bf16 v[26:29], v[94:97], v[178:181], v[26:29]
	v_mfma_f32_16x16x32_bf16 v[14:17], v[78:81], v[186:189], v[14:17]
	v_mfma_f32_16x16x32_bf16 v[10:13], v[94:97], v[186:189], v[10:13]
	v_mfma_f32_16x16x32_bf16 v[62:65], v[82:85], v[158:161], v[62:65]
	v_mfma_f32_16x16x32_bf16 v[58:61], v[98:101], v[158:161], v[58:61]
	v_mfma_f32_16x16x32_bf16 v[46:49], v[82:85], v[174:177], v[46:49]
	v_mfma_f32_16x16x32_bf16 v[42:45], v[98:101], v[174:177], v[42:45]
	v_mfma_f32_16x16x32_bf16 v[30:33], v[82:85], v[182:185], v[30:33]
	v_mfma_f32_16x16x32_bf16 v[26:29], v[98:101], v[182:185], v[26:29]
	v_mfma_f32_16x16x32_bf16 v[14:17], v[82:85], v[190:193], v[14:17]
	v_mfma_f32_16x16x32_bf16 v[10:13], v[98:101], v[190:193], v[10:13]
	v_mfma_f32_16x16x32_bf16 v[54:57], v[106:109], v[146:149], v[54:57]
	v_mfma_f32_16x16x32_bf16 v[50:53], v[126:129], v[146:149], v[50:53]
	v_mfma_f32_16x16x32_bf16 v[38:41], v[106:109], v[166:169], v[38:41]
	v_mfma_f32_16x16x32_bf16 v[34:37], v[126:129], v[166:169], v[34:37]
	v_mfma_f32_16x16x32_bf16 v[22:25], v[106:109], v[178:181], v[22:25]
	v_mfma_f32_16x16x32_bf16 v[18:21], v[126:129], v[178:181], v[18:21]
	v_mfma_f32_16x16x32_bf16 v[6:9], v[106:109], v[186:189], v[6:9]
	v_mfma_f32_16x16x32_bf16 v[2:5], v[126:129], v[186:189], v[2:5]
	v_mfma_f32_16x16x32_bf16 v[54:57], v[110:113], v[158:161], v[54:57]
	v_mfma_f32_16x16x32_bf16 v[50:53], v[134:137], v[158:161], v[50:53]
	v_mfma_f32_16x16x32_bf16 v[38:41], v[110:113], v[174:177], v[38:41]
	v_mfma_f32_16x16x32_bf16 v[34:37], v[134:137], v[174:177], v[34:37]
	v_mfma_f32_16x16x32_bf16 v[22:25], v[110:113], v[182:185], v[22:25]
	v_mfma_f32_16x16x32_bf16 v[18:21], v[134:137], v[182:185], v[18:21]
	v_mfma_f32_16x16x32_bf16 v[6:9], v[110:113], v[190:193], v[6:9]
	v_mfma_f32_16x16x32_bf16 v[2:5], v[134:137], v[190:193], v[2:5]
	s_barrier
	s_setprio 0
	s_add_i32 s59, s59, 2
	s_add_u32 s49, s49, 0x100
	s_addc_u32 s58, s58, 0
	s_cmpk_gt_u32 s59, 0x55
	s_mov_b64 s[2:3], s[16:17]
	s_cbranch_scc0 .LBB0_970
	s_mov_b32 s101, 0x80000001
	s_and_b64 vcc, exec, s[10:11]
	s_cbranch_vccz .LBB0_973
	s_barrier

.LBB0_1109:
	v_lshrrev_b32_e32 v13, 1, v12
	v_readlane_b32 s6, v254, 15
	v_and_b32_e32 v18, 24, v13
	s_lshl_b32 s0, s0, 5
	v_mov_b32_e32 v137, v203
	v_readlane_b32 s7, v254, 16
	v_and_b32_e32 v144, 15, v12
	v_lshlrev_b32_e32 v19, 1, v18
	v_lshlrev_b32_e32 v12, 2, v12
	s_and_b32 s5, s0, 0x60
	s_add_i32 m0, s27, 0x18000
	v_lshl_add_u64 v[2:3], v[2:3], 0, s[80:81]
	v_lshl_add_u64 v[14:15], s[6:7], 0, v[136:137]
	v_mov_b32_e32 v133, v203
	s_lshl_b32 s31, s1, 6
	v_lshl_or_b32 v19, v144, 6, v19
	s_lshl_b32 s1, s1, 13
	v_and_b32_e32 v12, 32, v12
	s_lshl_b32 s0, s5, 7
	s_waitcnt vmcnt(2)
	s_barrier
	global_load_lds_dwordx4 v[2:3], off
	v_lshl_add_u64 v[2:3], v[4:5], 0, s[80:81]
	s_add_i32 m0, s27, 0x1a000
	s_add_i32 s34, s27, 0x8000
	s_add_i32 s35, s27, 0xa000
	v_lshl_add_u64 v[16:17], s[6:7], 0, v[132:133]
	v_bitop3_b32 v145, v19, s0, v12 bitop3:0xde
	v_add_u32_e32 v145, 0x10000, v145
	global_load_lds_dwordx4 v[2:3], off
	v_lshl_add_u64 v[2:3], v[14:15], 0, s[80:81]
	s_mov_b32 m0, s34
	s_add_u32 s0, s2, 0x80080
	v_bitop3_b32 v20, v19, s1, v12 bitop3:0xde
	global_load_lds_dwordx4 v[2:3], off
	v_lshl_add_u64 v[2:3], v[16:17], 0, s[80:81]
	s_mov_b32 m0, s35
	s_addc_u32 s1, s3, 0
	global_load_lds_dwordx4 v[2:3], off
	s_add_i32 m0, s27, 0x1c000
	v_lshl_add_u64 v[2:3], s[0:1], 0, v[134:135]
	global_load_lds_dwordx4 v[2:3], off
	v_lshl_add_u64 v[2:3], s[0:1], 0, v[130:131]
	s_add_i32 m0, s27, 0x1e000
	v_and_b32_e32 v5, 1, v10
	global_load_lds_dwordx4 v[2:3], off
	v_lshlrev_b32_e32 v3, 15, v10
	v_and_b32_e32 v3, 0xffff0000, v3
	v_lshl_add_u32 v3, v9, 12, v3
	v_lshl_or_b32 v3, v5, 6, v3
	v_lshl_add_u32 v138, v11, 1, v3
	v_lshlrev_b32_e32 v3, 15, v6
	v_and_b32_e32 v3, 0xffff0000, v3
	s_waitcnt vmcnt(6)
	v_lshl_add_u32 v3, v7, 12, v3
	v_and_b32_e32 v5, 1, v6
	s_cmpk_lt_u32 s4, 0x100
	v_and_b32_e32 v2, 8, v13
	v_lshlrev_b32_e32 v4, 4, v144
	v_lshl_or_b32 v3, v5, 6, v3
	v_readlane_b32 s0, v254, 11
	s_cselect_b64 s[10:11], -1, 0
	v_or_b32_e32 v146, s5, v18
	v_mov_b32_e32 v139, v203
	v_lshl_add_u32 v140, v8, 1, v3
	v_mov_b32_e32 v141, v203
	s_mov_b32 s36, 0
	v_add_u32_e32 v147, 0, v20
	v_lshlrev_b32_e32 v202, 1, v4
	v_lshlrev_b32_e32 v142, 1, v2
	v_readlane_b32 s37, v254, 14
	s_mov_b32 s38, s0
	s_mov_b64 s[4:5], s[6:7]
	s_barrier
	v_readlane_b32 s1, v254, 12
	s_waitcnt vmcnt(0)
	s_mov_b32 s101, 0
	s_branch .LBB0_1112

.LBB0_1114:
	s_ashr_i32 s17, s16, 31
	s_lshl_b64 s[0:1], s[16:17], 20
	s_add_u32 s18, s42, s0
	s_addc_u32 s19, s43, s1
	s_and_b64 s[0:1], s[6:7], exec
	s_cselect_b32 s17, s19, s5
	s_cselect_b32 s39, s18, s4
	s_ashr_i32 s15, s14, 31
	s_lshl_b64 s[0:1], s[14:15], 20
	s_add_u32 s20, s24, s0
	s_addc_u32 s21, s25, s1
	s_and_b64 s[0:1], s[6:7], exec
	s_cselect_b32 s15, s21, s3
	s_cselect_b32 s40, s20, s2
	s_add_u32 s22, s4, 0x80080
	s_addc_u32 s23, s5, 0
	s_add_u32 s41, s2, 0x100
	v_mov_b32_e32 v2, 0
	s_addc_u32 s49, s3, 0
	s_mov_b32 s58, -2
	v_mov_b32_e32 v3, v2
	v_pk_mov_b32 v[4:5], v[2:3], v[2:3] op_sel:[0,1]
	v_pk_mov_b32 v[6:7], v[2:3], v[2:3] op_sel:[0,1]
	v_pk_mov_b32 v[8:9], v[2:3], v[2:3] op_sel:[0,1]
	v_pk_mov_b32 v[18:19], v[2:3], v[2:3] op_sel:[0,1]
	v_pk_mov_b32 v[20:21], v[2:3], v[2:3] op_sel:[0,1]
	v_pk_mov_b32 v[22:23], v[2:3], v[2:3] op_sel:[0,1]
	v_pk_mov_b32 v[24:25], v[2:3], v[2:3] op_sel:[0,1]
	v_pk_mov_b32 v[34:35], v[2:3], v[2:3] op_sel:[0,1]
	v_pk_mov_b32 v[36:37], v[2:3], v[2:3] op_sel:[0,1]
	v_pk_mov_b32 v[38:39], v[2:3], v[2:3] op_sel:[0,1]
	v_pk_mov_b32 v[40:41], v[2:3], v[2:3] op_sel:[0,1]
	v_pk_mov_b32 v[50:51], v[2:3], v[2:3] op_sel:[0,1]
	v_pk_mov_b32 v[52:53], v[2:3], v[2:3] op_sel:[0,1]
	v_pk_mov_b32 v[54:55], v[2:3], v[2:3] op_sel:[0,1]
	v_pk_mov_b32 v[56:57], v[2:3], v[2:3] op_sel:[0,1]
	v_pk_mov_b32 v[10:11], v[2:3], v[2:3] op_sel:[0,1]
	v_pk_mov_b32 v[12:13], v[2:3], v[2:3] op_sel:[0,1]
	v_pk_mov_b32 v[14:15], v[2:3], v[2:3] op_sel:[0,1]
	v_pk_mov_b32 v[16:17], v[2:3], v[2:3] op_sel:[0,1]
	v_pk_mov_b32 v[26:27], v[2:3], v[2:3] op_sel:[0,1]
	v_pk_mov_b32 v[28:29], v[2:3], v[2:3] op_sel:[0,1]
	v_pk_mov_b32 v[30:31], v[2:3], v[2:3] op_sel:[0,1]
	v_pk_mov_b32 v[32:33], v[2:3], v[2:3] op_sel:[0,1]
	v_pk_mov_b32 v[42:43], v[2:3], v[2:3] op_sel:[0,1]
	v_pk_mov_b32 v[44:45], v[2:3], v[2:3] op_sel:[0,1]
	v_pk_mov_b32 v[46:47], v[2:3], v[2:3] op_sel:[0,1]
	v_pk_mov_b32 v[48:49], v[2:3], v[2:3] op_sel:[0,1]
	v_pk_mov_b32 v[58:59], v[2:3], v[2:3] op_sel:[0,1]
	v_pk_mov_b32 v[60:61], v[2:3], v[2:3] op_sel:[0,1]
	v_pk_mov_b32 v[62:63], v[2:3], v[2:3] op_sel:[0,1]
	v_pk_mov_b32 v[64:65], v[2:3], v[2:3] op_sel:[0,1]
	v_pk_mov_b32 v[66:67], v[2:3], v[2:3] op_sel:[0,1]
	v_pk_mov_b32 v[68:69], v[2:3], v[2:3] op_sel:[0,1]
	v_pk_mov_b32 v[70:71], v[2:3], v[2:3] op_sel:[0,1]
	v_pk_mov_b32 v[72:73], v[2:3], v[2:3] op_sel:[0,1]
	v_pk_mov_b32 v[82:83], v[2:3], v[2:3] op_sel:[0,1]
	v_pk_mov_b32 v[84:85], v[2:3], v[2:3] op_sel:[0,1]
	v_pk_mov_b32 v[86:87], v[2:3], v[2:3] op_sel:[0,1]
	v_pk_mov_b32 v[88:89], v[2:3], v[2:3] op_sel:[0,1]
	v_pk_mov_b32 v[98:99], v[2:3], v[2:3] op_sel:[0,1]
	v_pk_mov_b32 v[100:101], v[2:3], v[2:3] op_sel:[0,1]
	v_pk_mov_b32 v[102:103], v[2:3], v[2:3] op_sel:[0,1]
	v_pk_mov_b32 v[104:105], v[2:3], v[2:3] op_sel:[0,1]
	v_pk_mov_b32 v[114:115], v[2:3], v[2:3] op_sel:[0,1]
	v_pk_mov_b32 v[116:117], v[2:3], v[2:3] op_sel:[0,1]
	v_pk_mov_b32 v[118:119], v[2:3], v[2:3] op_sel:[0,1]
	v_pk_mov_b32 v[120:121], v[2:3], v[2:3] op_sel:[0,1]
	v_pk_mov_b32 v[74:75], v[2:3], v[2:3] op_sel:[0,1]
	v_pk_mov_b32 v[76:77], v[2:3], v[2:3] op_sel:[0,1]
	v_pk_mov_b32 v[78:79], v[2:3], v[2:3] op_sel:[0,1]
	v_pk_mov_b32 v[80:81], v[2:3], v[2:3] op_sel:[0,1]
	v_pk_mov_b32 v[90:91], v[2:3], v[2:3] op_sel:[0,1]
	v_pk_mov_b32 v[92:93], v[2:3], v[2:3] op_sel:[0,1]
	v_pk_mov_b32 v[94:95], v[2:3], v[2:3] op_sel:[0,1]
	v_pk_mov_b32 v[96:97], v[2:3], v[2:3] op_sel:[0,1]
	v_pk_mov_b32 v[106:107], v[2:3], v[2:3] op_sel:[0,1]
	v_pk_mov_b32 v[108:109], v[2:3], v[2:3] op_sel:[0,1]
	v_pk_mov_b32 v[110:111], v[2:3], v[2:3] op_sel:[0,1]
	v_pk_mov_b32 v[112:113], v[2:3], v[2:3] op_sel:[0,1]
	v_pk_mov_b32 v[122:123], v[2:3], v[2:3] op_sel:[0,1]
	v_pk_mov_b32 v[124:125], v[2:3], v[2:3] op_sel:[0,1]
	v_pk_mov_b32 v[126:127], v[2:3], v[2:3] op_sel:[0,1]
	v_pk_mov_b32 v[128:129], v[2:3], v[2:3] op_sel:[0,1]
	s_cmp_eq_u32 s101, 0x80000001
	s_cbranch_scc0 .LBB0_1115
	s_add_u32 s0, s22, 0xfff80080
	s_addc_u32 s1, s23, -1
	s_add_i32 s33, 0, 0x10000
	s_cmp_eq_u32 s58, 28
	s_cselect_b32 s5, s17, s1
	s_cselect_b32 s4, s39, s0
	s_cselect_b32 s3, s15, s49
	s_cselect_b32 s2, s40, s41
	s_add_i32 s55, 0, 0x14000
	ds_read_b128 v[148:151], v145
	ds_read_b128 v[152:155], v145 offset:1024
	ds_read_b128 v[156:159], v145 offset:2048
	ds_read_b128 v[160:163], v145 offset:3072
	ds_read_b128 v[164:167], v145 offset:16384
	ds_read_b128 v[168:171], v145 offset:17408
	ds_read_b128 v[172:175], v145 offset:18432
	ds_read_b128 v[176:179], v145 offset:19456
	s_add_i32 m0, s27, 0xc000
	ds_read_b128 v[180:183], v147
	ds_read_b128 v[184:187], v147 offset:1024
	ds_read_b128 v[188:191], v147 offset:2048
	ds_read_b128 v[192:195], v147 offset:3072
	ds_read_b128 v[196:199], v147 offset:4096
	ds_read_b128 v[208:211], v147 offset:5120
	ds_read_b128 v[212:215], v147 offset:6144
	ds_read_b128 v[216:219], v147 offset:7168
	global_load_lds_dwordx4 v138, s[22:23]
	s_add_i32 m0, s27, 0xe000
	s_nop 0
	global_load_lds_dwordx4 v140, s[22:23]
	s_waitcnt vmcnt(24)
	s_waitcnt lgkmcnt(0)
	s_setprio 1
	s_barrier
	v_mfma_f32_16x16x32_bf16 v[126:129], v[148:151], v[180:183], v[126:129]
	v_mfma_f32_16x16x32_bf16 v[122:125], v[156:159], v[180:183], v[122:125]
	v_mfma_f32_16x16x32_bf16 v[110:113], v[148:151], v[188:191], v[110:113]
	v_mfma_f32_16x16x32_bf16 v[106:109], v[156:159], v[188:191], v[106:109]
	v_mfma_f32_16x16x32_bf16 v[94:97], v[148:151], v[196:199], v[94:97]
	v_mfma_f32_16x16x32_bf16 v[90:93], v[156:159], v[196:199], v[90:93]
	v_mfma_f32_16x16x32_bf16 v[78:81], v[148:151], v[212:215], v[78:81]
	v_mfma_f32_16x16x32_bf16 v[74:77], v[156:159], v[212:215], v[74:77]
	v_mfma_f32_16x16x32_bf16 v[126:129], v[152:155], v[184:187], v[126:129]
	v_mfma_f32_16x16x32_bf16 v[122:125], v[160:163], v[184:187], v[122:125]
	v_mfma_f32_16x16x32_bf16 v[110:113], v[152:155], v[192:195], v[110:113]
	v_mfma_f32_16x16x32_bf16 v[106:109], v[160:163], v[192:195], v[106:109]
	v_mfma_f32_16x16x32_bf16 v[94:97], v[152:155], v[208:211], v[94:97]
	v_mfma_f32_16x16x32_bf16 v[90:93], v[160:163], v[208:211], v[90:93]
	v_mfma_f32_16x16x32_bf16 v[78:81], v[152:155], v[216:219], v[78:81]
	v_mfma_f32_16x16x32_bf16 v[74:77], v[160:163], v[216:219], v[74:77]
	v_mfma_f32_16x16x32_bf16 v[118:121], v[164:167], v[180:183], v[118:121]
	v_mfma_f32_16x16x32_bf16 v[114:117], v[172:175], v[180:183], v[114:117]
	v_mfma_f32_16x16x32_bf16 v[102:105], v[164:167], v[188:191], v[102:105]
	v_mfma_f32_16x16x32_bf16 v[98:101], v[172:175], v[188:191], v[98:101]
	v_mfma_f32_16x16x32_bf16 v[86:89], v[164:167], v[196:199], v[86:89]
	v_mfma_f32_16x16x32_bf16 v[82:85], v[172:175], v[196:199], v[82:85]
	v_mfma_f32_16x16x32_bf16 v[70:73], v[164:167], v[212:215], v[70:73]
	v_mfma_f32_16x16x32_bf16 v[66:69], v[172:175], v[212:215], v[66:69]
	v_mfma_f32_16x16x32_bf16 v[118:121], v[168:171], v[184:187], v[118:121]
	v_mfma_f32_16x16x32_bf16 v[114:117], v[176:179], v[184:187], v[114:117]
	v_mfma_f32_16x16x32_bf16 v[102:105], v[168:171], v[192:195], v[102:105]
	v_mfma_f32_16x16x32_bf16 v[98:101], v[176:179], v[192:195], v[98:101]
	v_mfma_f32_16x16x32_bf16 v[86:89], v[168:171], v[208:211], v[86:89]
	v_mfma_f32_16x16x32_bf16 v[82:85], v[176:179], v[208:211], v[82:85]
	v_mfma_f32_16x16x32_bf16 v[70:73], v[168:171], v[216:219], v[70:73]
	v_mfma_f32_16x16x32_bf16 v[66:69], v[176:179], v[216:219], v[66:69]
	s_barrier
	s_setprio 0
	s_add_i32 s0, s33, s26
	s_mov_b32 m0, s0
	ds_read_b128 v[180:183], v147 offset:16384
	ds_read_b128 v[184:187], v147 offset:17408
	ds_read_b128 v[188:191], v147 offset:18432
	ds_read_b128 v[192:195], v147 offset:19456
	ds_read_b128 v[196:199], v147 offset:20480
	ds_read_b128 v[208:211], v147 offset:21504
	ds_read_b128 v[212:215], v147 offset:22528
	ds_read_b128 v[216:219], v147 offset:23552
	global_load_lds_dwordx4 v134, s[2:3]
	s_add_i32 m0, s0, 0x2000
	s_add_u32 s0, s2, 0x80000
	s_addc_u32 s1, s3, 0
	s_add_i32 s33, s55, s26
	global_load_lds_dwordx4 v130, s[2:3]
	s_mov_b32 m0, s33
	s_nop 0
	global_load_lds_dwordx4 v134, s[0:1]
	s_add_i32 m0, s33, 0x2000
	s_nop 0
	global_load_lds_dwordx4 v130, s[0:1]
	s_mov_b32 m0, s27
	s_nop 0
	global_load_lds_dwordx4 v136, s[4:5]
	s_mov_b32 m0, s28
	s_nop 0
	global_load_lds_dwordx4 v132, s[4:5]
	s_waitcnt vmcnt(24)
	s_waitcnt lgkmcnt(0)
	s_setprio 1
	s_barrier
	v_mfma_f32_16x16x32_bf16 v[62:65], v[148:151], v[180:183], v[62:65]
	v_mfma_f32_16x16x32_bf16 v[58:61], v[156:159], v[180:183], v[58:61]
	v_mfma_f32_16x16x32_bf16 v[46:49], v[148:151], v[188:191], v[46:49]
	v_mfma_f32_16x16x32_bf16 v[42:45], v[156:159], v[188:191], v[42:45]
	v_mfma_f32_16x16x32_bf16 v[30:33], v[148:151], v[196:199], v[30:33]
	v_mfma_f32_16x16x32_bf16 v[26:29], v[156:159], v[196:199], v[26:29]
	v_mfma_f32_16x16x32_bf16 v[14:17], v[148:151], v[212:215], v[14:17]
	v_mfma_f32_16x16x32_bf16 v[10:13], v[156:159], v[212:215], v[10:13]
	v_mfma_f32_16x16x32_bf16 v[62:65], v[152:155], v[184:187], v[62:65]
	v_mfma_f32_16x16x32_bf16 v[58:61], v[160:163], v[184:187], v[58:61]
	v_mfma_f32_16x16x32_bf16 v[46:49], v[152:155], v[192:195], v[46:49]
	v_mfma_f32_16x16x32_bf16 v[42:45], v[160:163], v[192:195], v[42:45]
	v_mfma_f32_16x16x32_bf16 v[30:33], v[152:155], v[208:211], v[30:33]
	v_mfma_f32_16x16x32_bf16 v[26:29], v[160:163], v[208:211], v[26:29]
	v_mfma_f32_16x16x32_bf16 v[14:17], v[152:155], v[216:219], v[14:17]
	v_mfma_f32_16x16x32_bf16 v[10:13], v[160:163], v[216:219], v[10:13]
	v_mfma_f32_16x16x32_bf16 v[54:57], v[164:167], v[180:183], v[54:57]
	v_mfma_f32_16x16x32_bf16 v[50:53], v[172:175], v[180:183], v[50:53]
	v_mfma_f32_16x16x32_bf16 v[38:41], v[164:167], v[188:191], v[38:41]
	v_mfma_f32_16x16x32_bf16 v[34:37], v[172:175], v[188:191], v[34:37]
	v_mfma_f32_16x16x32_bf16 v[22:25], v[164:167], v[196:199], v[22:25]
	v_mfma_f32_16x16x32_bf16 v[18:21], v[172:175], v[196:199], v[18:21]
	v_mfma_f32_16x16x32_bf16 v[6:9], v[164:167], v[212:215], v[6:9]
	v_mfma_f32_16x16x32_bf16 v[2:5], v[172:175], v[212:215], v[2:5]
	v_mfma_f32_16x16x32_bf16 v[54:57], v[168:171], v[184:187], v[54:57]
	v_mfma_f32_16x16x32_bf16 v[50:53], v[176:179], v[184:187], v[50:53]
	v_mfma_f32_16x16x32_bf16 v[38:41], v[168:171], v[192:195], v[38:41]
	v_mfma_f32_16x16x32_bf16 v[34:37], v[176:179], v[192:195], v[34:37]
	v_mfma_f32_16x16x32_bf16 v[22:25], v[168:171], v[208:211], v[22:25]
	v_mfma_f32_16x16x32_bf16 v[18:21], v[176:179], v[208:211], v[18:21]
	v_mfma_f32_16x16x32_bf16 v[6:9], v[168:171], v[216:219], v[6:9]
	v_mfma_f32_16x16x32_bf16 v[2:5], v[176:179], v[216:219], v[2:5]
	s_barrier
	s_setprio 0
	s_branch .Lpeel_mid_6

.Lpeel_mid_6:
	s_add_i32 s33, 0, 0x18000
	s_add_i32 s55, 0, 0x1c000
	ds_read_b128 v[148:151], v145 offset:32768
	ds_read_b128 v[152:155], v145 offset:33792
	ds_read_b128 v[156:159], v145 offset:34816
	ds_read_b128 v[160:163], v145 offset:35840
	ds_read_b128 v[164:167], v145 offset:49152
	ds_read_b128 v[168:171], v145 offset:50176
	ds_read_b128 v[172:175], v145 offset:51200
	ds_read_b128 v[176:179], v145 offset:52224
	s_add_u32 s0, s4, 0x80000
	s_addc_u32 s1, s5, 0
	s_mov_b32 m0, s29
	ds_read_b128 v[180:183], v147 offset:32768
	ds_read_b128 v[184:187], v147 offset:33792
	ds_read_b128 v[188:191], v147 offset:34816
	ds_read_b128 v[192:195], v147 offset:35840
	ds_read_b128 v[196:199], v147 offset:36864
	ds_read_b128 v[208:211], v147 offset:37888
	ds_read_b128 v[212:215], v147 offset:38912
	ds_read_b128 v[216:219], v147 offset:39936
	global_load_lds_dwordx4 v136, s[0:1]
	s_mov_b32 m0, s30
	s_nop 0
	global_load_lds_dwordx4 v132, s[0:1]
	s_waitcnt vmcnt(8)
	s_waitcnt lgkmcnt(0)
	s_setprio 1
	s_barrier
	v_mfma_f32_16x16x32_bf16 v[126:129], v[148:151], v[180:183], v[126:129]
	v_mfma_f32_16x16x32_bf16 v[122:125], v[156:159], v[180:183], v[122:125]
	v_mfma_f32_16x16x32_bf16 v[110:113], v[148:151], v[188:191], v[110:113]
	v_mfma_f32_16x16x32_bf16 v[106:109], v[156:159], v[188:191], v[106:109]
	v_mfma_f32_16x16x32_bf16 v[94:97], v[148:151], v[196:199], v[94:97]
	v_mfma_f32_16x16x32_bf16 v[90:93], v[156:159], v[196:199], v[90:93]
	v_mfma_f32_16x16x32_bf16 v[78:81], v[148:151], v[212:215], v[78:81]
	v_mfma_f32_16x16x32_bf16 v[74:77], v[156:159], v[212:215], v[74:77]
	v_mfma_f32_16x16x32_bf16 v[126:129], v[152:155], v[184:187], v[126:129]
	v_mfma_f32_16x16x32_bf16 v[122:125], v[160:163], v[184:187], v[122:125]
	v_mfma_f32_16x16x32_bf16 v[110:113], v[152:155], v[192:195], v[110:113]
	v_mfma_f32_16x16x32_bf16 v[106:109], v[160:163], v[192:195], v[106:109]
	v_mfma_f32_16x16x32_bf16 v[94:97], v[152:155], v[208:211], v[94:97]
	v_mfma_f32_16x16x32_bf16 v[90:93], v[160:163], v[208:211], v[90:93]
	v_mfma_f32_16x16x32_bf16 v[78:81], v[152:155], v[216:219], v[78:81]
	v_mfma_f32_16x16x32_bf16 v[74:77], v[160:163], v[216:219], v[74:77]
	v_mfma_f32_16x16x32_bf16 v[118:121], v[164:167], v[180:183], v[118:121]
	v_mfma_f32_16x16x32_bf16 v[114:117], v[172:175], v[180:183], v[114:117]
	v_mfma_f32_16x16x32_bf16 v[102:105], v[164:167], v[188:191], v[102:105]
	v_mfma_f32_16x16x32_bf16 v[98:101], v[172:175], v[188:191], v[98:101]
	v_mfma_f32_16x16x32_bf16 v[86:89], v[164:167], v[196:199], v[86:89]
	v_mfma_f32_16x16x32_bf16 v[82:85], v[172:175], v[196:199], v[82:85]
	v_mfma_f32_16x16x32_bf16 v[70:73], v[164:167], v[212:215], v[70:73]
	v_mfma_f32_16x16x32_bf16 v[66:69], v[172:175], v[212:215], v[66:69]
	v_mfma_f32_16x16x32_bf16 v[118:121], v[168:171], v[184:187], v[118:121]
	v_mfma_f32_16x16x32_bf16 v[114:117], v[176:179], v[184:187], v[114:117]
	v_mfma_f32_16x16x32_bf16 v[102:105], v[168:171], v[192:195], v[102:105]
	v_mfma_f32_16x16x32_bf16 v[98:101], v[176:179], v[192:195], v[98:101]
	v_mfma_f32_16x16x32_bf16 v[86:89], v[168:171], v[208:211], v[86:89]
	v_mfma_f32_16x16x32_bf16 v[82:85], v[176:179], v[208:211], v[82:85]
	v_mfma_f32_16x16x32_bf16 v[70:73], v[168:171], v[216:219], v[70:73]
	v_mfma_f32_16x16x32_bf16 v[66:69], v[176:179], v[216:219], v[66:69]
	s_barrier
	s_setprio 0
	s_add_i32 s0, s33, s26
	s_add_u32 s100, s2, 0x80
	s_addc_u32 s101, s3, 0
	s_mov_b32 m0, s0
	ds_read_b128 v[180:183], v147 offset:49152
	ds_read_b128 v[184:187], v147 offset:50176
	ds_read_b128 v[188:191], v147 offset:51200
	ds_read_b128 v[192:195], v147 offset:52224
	ds_read_b128 v[196:199], v147 offset:53248
	ds_read_b128 v[208:211], v147 offset:54272
	ds_read_b128 v[212:215], v147 offset:55296
	ds_read_b128 v[216:219], v147 offset:56320
	global_load_lds_dwordx4 v134, s[100:101]
	s_add_i32 m0, s0, 0x2000
	s_add_u32 s100, s2, 0x80
	s_addc_u32 s101, s3, 0
	s_add_u32 s0, s2, 0x80080
	s_addc_u32 s1, s3, 0
	s_add_i32 s2, s55, s26
	global_load_lds_dwordx4 v130, s[100:101]
	s_mov_b32 m0, s2
	s_nop 0
	global_load_lds_dwordx4 v134, s[0:1]
	s_add_i32 m0, s2, 0x2000
	s_nop 0
	global_load_lds_dwordx4 v130, s[0:1]
	s_add_u32 s100, s4, 0x80
	s_addc_u32 s101, s5, 0
	s_mov_b32 m0, s34
	s_nop 0
	global_load_lds_dwordx4 v136, s[100:101]
	s_add_u32 s100, s4, 0x80
	s_addc_u32 s101, s5, 0
	s_mov_b32 m0, s35
	s_nop 0
	global_load_lds_dwordx4 v132, s[100:101]
	s_waitcnt vmcnt(8)
	s_waitcnt lgkmcnt(0)
	s_setprio 1
	s_barrier
	v_mfma_f32_16x16x32_bf16 v[62:65], v[148:151], v[180:183], v[62:65]
	v_mfma_f32_16x16x32_bf16 v[58:61], v[156:159], v[180:183], v[58:61]
	v_mfma_f32_16x16x32_bf16 v[46:49], v[148:151], v[188:191], v[46:49]
	v_mfma_f32_16x16x32_bf16 v[42:45], v[156:159], v[188:191], v[42:45]
	v_mfma_f32_16x16x32_bf16 v[30:33], v[148:151], v[196:199], v[30:33]
	v_mfma_f32_16x16x32_bf16 v[26:29], v[156:159], v[196:199], v[26:29]
	v_mfma_f32_16x16x32_bf16 v[14:17], v[148:151], v[212:215], v[14:17]
	v_mfma_f32_16x16x32_bf16 v[10:13], v[156:159], v[212:215], v[10:13]
	v_mfma_f32_16x16x32_bf16 v[62:65], v[152:155], v[184:187], v[62:65]
	v_mfma_f32_16x16x32_bf16 v[58:61], v[160:163], v[184:187], v[58:61]
	v_mfma_f32_16x16x32_bf16 v[46:49], v[152:155], v[192:195], v[46:49]
	v_mfma_f32_16x16x32_bf16 v[42:45], v[160:163], v[192:195], v[42:45]
	v_mfma_f32_16x16x32_bf16 v[30:33], v[152:155], v[208:211], v[30:33]
	v_mfma_f32_16x16x32_bf16 v[26:29], v[160:163], v[208:211], v[26:29]
	v_mfma_f32_16x16x32_bf16 v[14:17], v[152:155], v[216:219], v[14:17]
	v_mfma_f32_16x16x32_bf16 v[10:13], v[160:163], v[216:219], v[10:13]
	v_mfma_f32_16x16x32_bf16 v[54:57], v[164:167], v[180:183], v[54:57]
	v_mfma_f32_16x16x32_bf16 v[50:53], v[172:175], v[180:183], v[50:53]
	v_mfma_f32_16x16x32_bf16 v[38:41], v[164:167], v[188:191], v[38:41]
	v_mfma_f32_16x16x32_bf16 v[34:37], v[172:175], v[188:191], v[34:37]
	v_mfma_f32_16x16x32_bf16 v[22:25], v[164:167], v[196:199], v[22:25]
	v_mfma_f32_16x16x32_bf16 v[18:21], v[172:175], v[196:199], v[18:21]
	v_mfma_f32_16x16x32_bf16 v[6:9], v[164:167], v[212:215], v[6:9]
	v_mfma_f32_16x16x32_bf16 v[2:5], v[172:175], v[212:215], v[2:5]
	v_mfma_f32_16x16x32_bf16 v[54:57], v[168:171], v[184:187], v[54:57]
	v_mfma_f32_16x16x32_bf16 v[50:53], v[176:179], v[184:187], v[50:53]
	v_mfma_f32_16x16x32_bf16 v[38:41], v[168:171], v[192:195], v[38:41]
	v_mfma_f32_16x16x32_bf16 v[34:37], v[176:179], v[192:195], v[34:37]
	v_mfma_f32_16x16x32_bf16 v[22:25], v[168:171], v[208:211], v[22:25]
	v_mfma_f32_16x16x32_bf16 v[18:21], v[176:179], v[208:211], v[18:21]
	v_mfma_f32_16x16x32_bf16 v[6:9], v[168:171], v[216:219], v[6:9]
	v_mfma_f32_16x16x32_bf16 v[2:5], v[176:179], v[216:219], v[2:5]
	s_barrier
	s_setprio 0
	s_add_i32 s58, s58, 2
	s_add_u32 s22, s22, 0x100
	s_addc_u32 s23, s23, 0
	s_add_u32 s41, s41, 0x100
	s_addc_u32 s49, s49, 0
	s_cmp_gt_u32 s58, 29
	s_cbranch_scc0 .LBB0_1115
	s_mov_b32 s101, 0x80000001
	s_and_b64 vcc, exec, s[10:11]
	s_cbranch_vccz .LBB0_1118
	s_barrier

.LBB0_1238:
	v_lshrrev_b32_e32 v12, 1, v2
	s_add_u32 s4, s6, 0x10080
	v_and_b32_e32 v12, 24, v12
	s_addc_u32 s5, s7, 0
	v_and_b32_e32 v3, 15, v2
	v_lshlrev_b32_e32 v13, 1, v12
	v_lshlrev_b32_e32 v2, 2, v2
	s_lshl_b32 s0, s0, 5
	v_lshl_or_b32 v140, s1, 6, v3
	v_lshl_or_b32 v3, v3, 6, v13
	s_lshl_b32 s1, s1, 13
	v_and_b32_e32 v2, 32, v2
	s_and_b32 s0, s0, 0x60
	v_lshl_add_u64 v[4:5], s[6:7], 0, v[202:203]
	v_mov_b32_e32 v131, v203
	v_readlane_b32 s14, v253, 28
	v_bitop3_b32 v13, v3, s1, v2 bitop3:0xde
	s_lshl_b32 s1, s0, 7
	v_lshl_add_u64 v[6:7], s[6:7], 0, v[130:131]
	v_mov_b32_e32 v135, v203
	v_readlane_b32 s15, v253, 29
	v_bitop3_b32 v141, v3, s1, v2 bitop3:0xde
	s_add_i32 m0, s37, 0x18000
	v_lshl_add_u64 v[2:3], v[4:5], 0, s[80:81]
	v_lshl_add_u64 v[8:9], s[14:15], 0, v[134:135]
	v_mov_b32_e32 v133, v203
	s_waitcnt vmcnt(2)
	s_barrier
	global_load_lds_dwordx4 v[2:3], off
	v_lshl_add_u64 v[2:3], v[6:7], 0, s[80:81]
	s_add_i32 m0, s37, 0x1a000
	s_add_i32 s41, s37, 0x8000
	v_lshl_add_u64 v[10:11], s[14:15], 0, v[132:133]
	global_load_lds_dwordx4 v[2:3], off
	v_lshl_add_u64 v[2:3], v[8:9], 0, s[80:81]
	s_mov_b32 m0, s41
	s_add_i32 s86, s37, 0xa000
	global_load_lds_dwordx4 v[2:3], off
	v_lshl_add_u64 v[2:3], v[10:11], 0, s[80:81]
	s_mov_b32 m0, s86
	s_mov_b32 s93, 0
	global_load_lds_dwordx4 v[2:3], off
	s_add_i32 m0, s37, 0x1c000
	v_lshl_add_u64 v[2:3], s[4:5], 0, v[202:203]
	global_load_lds_dwordx4 v[2:3], off
	v_lshl_add_u64 v[2:3], s[4:5], 0, v[130:131]
	s_add_i32 m0, s37, 0x1e000
	s_cmpk_lt_u32 s2, 0x100
	global_load_lds_dwordx4 v[2:3], off
	s_waitcnt vmcnt(6)
	v_or_b32_e32 v2, s0, v12
	v_readlane_b32 s0, v252, 0
	v_lshlrev_b32_e32 v2, 1, v2
	v_mov_b32_e32 v3, v203
	v_readlane_b32 s1, v252, 1
	s_cselect_b64 s[10:11], -1, 0
	v_add_u32_e32 v142, 0, v13
	v_lshl_add_u64 v[136:137], s[0:1], 0, v[2:3]
	s_mov_b32 s95, s56
	s_barrier
	s_mov_b32 s101, 0
	s_branch .LBB0_1241

.LBB0_1241:
	s_add_i32 s93, s93, 1
	s_mul_i32 s0, s93, s96
	s_mov_b32 s2, s95
	s_mov_b32 s67, s95
	s_add_i32 s95, s0, s56
	s_cmpk_lt_i32 s95, 0x200
	s_mov_b32 s3, s66
	s_cselect_b64 s[16:17], -1, 0
	s_ashr_i32 s66, s95, 2
	s_and_b64 s[0:1], s[16:17], exec
	s_cselect_b32 s2, s95, s2
	s_cselect_b32 s0, s66, s3
	s_ashr_i32 s3, s2, 31
	s_lshl_b64 s[2:3], s[2:3], 18
	s_mov_b64 s[18:19], s[14:15]
	s_add_u32 s14, s78, s2
	s_addc_u32 s15, s79, s3
	s_and_b64 s[2:3], s[16:17], exec
	s_cselect_b32 s49, s15, s19
	s_cselect_b32 s58, s14, s18
	s_ashr_i32 s1, s0, 31
	s_lshl_b64 s[0:1], s[0:1], 17
	s_mov_b64 s[20:21], s[6:7]
	s_add_u32 s6, s34, s0
	s_addc_u32 s7, s35, s1
	s_and_b64 s[0:1], s[16:17], exec
	v_mov_b32_e32 v2, 0
	s_mov_b32 s72, s56
	s_cselect_b32 s59, s7, s21
	s_cselect_b32 s60, s6, s20
	s_mov_b64 s[4:5], 0
	s_mov_b64 s[22:23], -1
	s_mov_b64 s[2:3], 0
	v_mov_b32_e32 v3, v2
	v_pk_mov_b32 v[4:5], v[2:3], v[2:3] op_sel:[0,1]
	v_pk_mov_b32 v[6:7], v[2:3], v[2:3] op_sel:[0,1]
	v_pk_mov_b32 v[8:9], v[2:3], v[2:3] op_sel:[0,1]
	v_pk_mov_b32 v[10:11], v[2:3], v[2:3] op_sel:[0,1]
	v_pk_mov_b32 v[12:13], v[2:3], v[2:3] op_sel:[0,1]
	v_pk_mov_b32 v[18:19], v[2:3], v[2:3] op_sel:[0,1]
	v_pk_mov_b32 v[20:21], v[2:3], v[2:3] op_sel:[0,1]
	v_pk_mov_b32 v[26:27], v[2:3], v[2:3] op_sel:[0,1]
	v_pk_mov_b32 v[28:29], v[2:3], v[2:3] op_sel:[0,1]
	v_pk_mov_b32 v[34:35], v[2:3], v[2:3] op_sel:[0,1]
	v_pk_mov_b32 v[36:37], v[2:3], v[2:3] op_sel:[0,1]
	v_pk_mov_b32 v[42:43], v[2:3], v[2:3] op_sel:[0,1]
	v_pk_mov_b32 v[44:45], v[2:3], v[2:3] op_sel:[0,1]
	v_pk_mov_b32 v[50:51], v[2:3], v[2:3] op_sel:[0,1]
	v_pk_mov_b32 v[52:53], v[2:3], v[2:3] op_sel:[0,1]
	v_pk_mov_b32 v[14:15], v[2:3], v[2:3] op_sel:[0,1]
	v_pk_mov_b32 v[16:17], v[2:3], v[2:3] op_sel:[0,1]
	v_pk_mov_b32 v[22:23], v[2:3], v[2:3] op_sel:[0,1]
	v_pk_mov_b32 v[24:25], v[2:3], v[2:3] op_sel:[0,1]
	v_pk_mov_b32 v[30:31], v[2:3], v[2:3] op_sel:[0,1]
	v_pk_mov_b32 v[32:33], v[2:3], v[2:3] op_sel:[0,1]
	v_pk_mov_b32 v[38:39], v[2:3], v[2:3] op_sel:[0,1]
	v_pk_mov_b32 v[40:41], v[2:3], v[2:3] op_sel:[0,1]
	v_pk_mov_b32 v[46:47], v[2:3], v[2:3] op_sel:[0,1]
	v_pk_mov_b32 v[48:49], v[2:3], v[2:3] op_sel:[0,1]
	v_pk_mov_b32 v[54:55], v[2:3], v[2:3] op_sel:[0,1]
	v_pk_mov_b32 v[56:57], v[2:3], v[2:3] op_sel:[0,1]
	v_pk_mov_b32 v[58:59], v[2:3], v[2:3] op_sel:[0,1]
	v_pk_mov_b32 v[60:61], v[2:3], v[2:3] op_sel:[0,1]
	v_pk_mov_b32 v[62:63], v[2:3], v[2:3] op_sel:[0,1]
	v_pk_mov_b32 v[64:65], v[2:3], v[2:3] op_sel:[0,1]
	v_pk_mov_b32 v[66:67], v[2:3], v[2:3] op_sel:[0,1]
	v_pk_mov_b32 v[68:69], v[2:3], v[2:3] op_sel:[0,1]
	v_pk_mov_b32 v[70:71], v[2:3], v[2:3] op_sel:[0,1]
	v_pk_mov_b32 v[72:73], v[2:3], v[2:3] op_sel:[0,1]
	v_pk_mov_b32 v[74:75], v[2:3], v[2:3] op_sel:[0,1]
	v_pk_mov_b32 v[76:77], v[2:3], v[2:3] op_sel:[0,1]
	v_pk_mov_b32 v[82:83], v[2:3], v[2:3] op_sel:[0,1]
	v_pk_mov_b32 v[84:85], v[2:3], v[2:3] op_sel:[0,1]
	v_pk_mov_b32 v[90:91], v[2:3], v[2:3] op_sel:[0,1]
	v_pk_mov_b32 v[92:93], v[2:3], v[2:3] op_sel:[0,1]
	v_pk_mov_b32 v[98:99], v[2:3], v[2:3] op_sel:[0,1]
	v_pk_mov_b32 v[100:101], v[2:3], v[2:3] op_sel:[0,1]
	v_pk_mov_b32 v[106:107], v[2:3], v[2:3] op_sel:[0,1]
	v_pk_mov_b32 v[108:109], v[2:3], v[2:3] op_sel:[0,1]
	v_pk_mov_b32 v[114:115], v[2:3], v[2:3] op_sel:[0,1]
	v_pk_mov_b32 v[116:117], v[2:3], v[2:3] op_sel:[0,1]
	v_pk_mov_b32 v[78:79], v[2:3], v[2:3] op_sel:[0,1]
	v_pk_mov_b32 v[80:81], v[2:3], v[2:3] op_sel:[0,1]
	v_pk_mov_b32 v[86:87], v[2:3], v[2:3] op_sel:[0,1]
	v_pk_mov_b32 v[88:89], v[2:3], v[2:3] op_sel:[0,1]
	v_pk_mov_b32 v[94:95], v[2:3], v[2:3] op_sel:[0,1]
	v_pk_mov_b32 v[96:97], v[2:3], v[2:3] op_sel:[0,1]
	v_pk_mov_b32 v[102:103], v[2:3], v[2:3] op_sel:[0,1]
	v_pk_mov_b32 v[104:105], v[2:3], v[2:3] op_sel:[0,1]
	v_pk_mov_b32 v[110:111], v[2:3], v[2:3] op_sel:[0,1]
	v_pk_mov_b32 v[112:113], v[2:3], v[2:3] op_sel:[0,1]
	v_pk_mov_b32 v[118:119], v[2:3], v[2:3] op_sel:[0,1]
	v_pk_mov_b32 v[120:121], v[2:3], v[2:3] op_sel:[0,1]
	v_pk_mov_b32 v[122:123], v[2:3], v[2:3] op_sel:[0,1]
	v_pk_mov_b32 v[124:125], v[2:3], v[2:3] op_sel:[0,1]
	v_pk_mov_b32 v[126:127], v[2:3], v[2:3] op_sel:[0,1]
	v_pk_mov_b32 v[128:129], v[2:3], v[2:3] op_sel:[0,1]
	s_cmp_eq_u32 s101, 0x80000001
	s_cbranch_scc0 .LBB0_1242
	s_add_u32 s28, s18, s4
	s_addc_u32 s29, s19, s5
	s_add_u32 s24, s28, 0x100
	s_addc_u32 s25, s29, 0
	s_and_b64 s[0:1], s[2:3], exec
	s_cselect_b32 s25, s49, s25
	s_cselect_b32 s24, s58, s24
	s_add_u32 s0, s20, s4
	s_addc_u32 s1, s21, s5
	s_add_u32 s4, s0, 0x100
	s_addc_u32 s5, s1, 0
	s_add_i32 s55, 0, 0x10000
	s_and_b64 s[0:1], s[2:3], exec
	s_cselect_b32 s27, s59, s5
	s_cselect_b32 s26, s60, s4
	s_add_i32 s0, 0, 0x14000
	s_add_u32 s30, s28, 0x20080
	s_addc_u32 s31, s29, 0
	s_add_i32 s57, s55, s36
	s_add_i32 m0, s37, 0xc000
	s_add_i32 s1, s37, 0xe000
	s_add_i32 s63, s57, 0x2000
	v_add_u32_e32 v138, s55, v141
	s_add_u32 s28, s26, 0x10000
	ds_read_b128 v[144:147], v138
	ds_read_b128 v[148:151], v138 offset:1024
	ds_read_b128 v[152:155], v138 offset:2048
	ds_read_b128 v[156:159], v138 offset:3072
	v_add_u32_e32 v138, s0, v141
	s_addc_u32 s29, s27, 0
	s_add_i32 s33, s0, s36
	ds_read_b128 v[160:163], v138
	ds_read_b128 v[164:167], v138 offset:1024
	ds_read_b128 v[168:171], v138 offset:2048
	ds_read_b128 v[172:175], v138 offset:3072
	s_add_i32 s56, s33, 0x2000
	s_add_i32 vcc_lo, 0, 0x18000
	s_add_i32 vcc_hi, 0, 0x1c000
	s_add_u32 s4, s24, 0x20000
	s_addc_u32 s5, s25, 0
	s_add_i32 s61, vcc_lo, s36
	s_add_i32 s62, s61, 0x2000
	s_add_u32 s2, s26, 0x10080
	s_addc_u32 s3, s27, 0
	s_add_i32 s55, vcc_hi, s36
	s_add_i32 s0, s55, 0x2000
	ds_read_b128 v[176:179], v142
	ds_read_b128 v[180:183], v142 offset:1024
	ds_read_b128 v[184:187], v142 offset:2048
	ds_read_b128 v[188:191], v142 offset:3072
	ds_read_b128 v[192:195], v142 offset:4096
	ds_read_b128 v[196:199], v142 offset:5120
	ds_read_b128 v[208:211], v142 offset:6144
	ds_read_b128 v[212:215], v142 offset:7168
	global_load_lds_dwordx4 v134, s[30:31]
	s_mov_b32 m0, s1
	s_nop 0
	global_load_lds_dwordx4 v132, s[30:31]
	s_waitcnt vmcnt(24)
	s_waitcnt lgkmcnt(0)
	s_setprio 1
	s_barrier
	v_mfma_f32_16x16x32_bf16 v[126:129], v[144:147], v[176:179], v[126:129]
	v_mfma_f32_16x16x32_bf16 v[122:125], v[152:155], v[176:179], v[122:125]
	v_mfma_f32_16x16x32_bf16 v[118:121], v[144:147], v[184:187], v[118:121]
	v_mfma_f32_16x16x32_bf16 v[110:113], v[152:155], v[184:187], v[110:113]
	v_mfma_f32_16x16x32_bf16 v[102:105], v[144:147], v[192:195], v[102:105]
	v_mfma_f32_16x16x32_bf16 v[94:97], v[152:155], v[192:195], v[94:97]
	v_mfma_f32_16x16x32_bf16 v[86:89], v[144:147], v[208:211], v[86:89]
	v_mfma_f32_16x16x32_bf16 v[78:81], v[152:155], v[208:211], v[78:81]
	v_mfma_f32_16x16x32_bf16 v[126:129], v[148:151], v[180:183], v[126:129]
	v_mfma_f32_16x16x32_bf16 v[122:125], v[156:159], v[180:183], v[122:125]
	v_mfma_f32_16x16x32_bf16 v[118:121], v[148:151], v[188:191], v[118:121]
	v_mfma_f32_16x16x32_bf16 v[110:113], v[156:159], v[188:191], v[110:113]
	v_mfma_f32_16x16x32_bf16 v[102:105], v[148:151], v[196:199], v[102:105]
	v_mfma_f32_16x16x32_bf16 v[94:97], v[156:159], v[196:199], v[94:97]
	v_mfma_f32_16x16x32_bf16 v[86:89], v[148:151], v[212:215], v[86:89]
	v_mfma_f32_16x16x32_bf16 v[78:81], v[156:159], v[212:215], v[78:81]
	v_mfma_f32_16x16x32_bf16 v[114:117], v[160:163], v[176:179], v[114:117]
	v_mfma_f32_16x16x32_bf16 v[106:109], v[168:171], v[176:179], v[106:109]
	v_mfma_f32_16x16x32_bf16 v[98:101], v[160:163], v[184:187], v[98:101]
	v_mfma_f32_16x16x32_bf16 v[90:93], v[168:171], v[184:187], v[90:93]
	v_mfma_f32_16x16x32_bf16 v[82:85], v[160:163], v[192:195], v[82:85]
	v_mfma_f32_16x16x32_bf16 v[74:77], v[168:171], v[192:195], v[74:77]
	v_mfma_f32_16x16x32_bf16 v[70:73], v[160:163], v[208:211], v[70:73]
	v_mfma_f32_16x16x32_bf16 v[66:69], v[168:171], v[208:211], v[66:69]
	v_mfma_f32_16x16x32_bf16 v[114:117], v[164:167], v[180:183], v[114:117]
	v_mfma_f32_16x16x32_bf16 v[106:109], v[172:175], v[180:183], v[106:109]
	v_mfma_f32_16x16x32_bf16 v[98:101], v[164:167], v[188:191], v[98:101]
	v_mfma_f32_16x16x32_bf16 v[90:93], v[172:175], v[188:191], v[90:93]
	v_mfma_f32_16x16x32_bf16 v[82:85], v[164:167], v[196:199], v[82:85]
	v_mfma_f32_16x16x32_bf16 v[74:77], v[172:175], v[196:199], v[74:77]
	v_mfma_f32_16x16x32_bf16 v[70:73], v[164:167], v[212:215], v[70:73]
	v_mfma_f32_16x16x32_bf16 v[66:69], v[172:175], v[212:215], v[66:69]
	s_barrier
	s_setprio 0
	s_mov_b32 m0, s57
	ds_read_b128 v[176:179], v142 offset:16384
	ds_read_b128 v[180:183], v142 offset:17408
	ds_read_b128 v[184:187], v142 offset:18432
	ds_read_b128 v[188:191], v142 offset:19456
	ds_read_b128 v[192:195], v142 offset:20480
	ds_read_b128 v[196:199], v142 offset:21504
	ds_read_b128 v[208:211], v142 offset:22528
	ds_read_b128 v[212:215], v142 offset:23552
	global_load_lds_dwordx4 v202, s[26:27]
	s_mov_b32 m0, s63
	s_nop 0
	global_load_lds_dwordx4 v130, s[26:27]
	s_mov_b32 m0, s33
	s_nop 0
	global_load_lds_dwordx4 v202, s[28:29]
	s_mov_b32 m0, s56
	s_nop 0
	global_load_lds_dwordx4 v130, s[28:29]
	s_mov_b32 m0, s37
	s_nop 0
	global_load_lds_dwordx4 v134, s[24:25]
	s_mov_b32 m0, s38
	s_nop 0
	global_load_lds_dwordx4 v132, s[24:25]
	s_waitcnt vmcnt(24)
	s_waitcnt lgkmcnt(0)
	s_setprio 1
	s_barrier
	v_mfma_f32_16x16x32_bf16 v[62:65], v[144:147], v[176:179], v[62:65]
	v_mfma_f32_16x16x32_bf16 v[58:61], v[152:155], v[176:179], v[58:61]
	v_mfma_f32_16x16x32_bf16 v[54:57], v[144:147], v[184:187], v[54:57]
	v_mfma_f32_16x16x32_bf16 v[46:49], v[152:155], v[184:187], v[46:49]
	v_mfma_f32_16x16x32_bf16 v[38:41], v[144:147], v[192:195], v[38:41]
	v_mfma_f32_16x16x32_bf16 v[30:33], v[152:155], v[192:195], v[30:33]
	v_mfma_f32_16x16x32_bf16 v[22:25], v[144:147], v[208:211], v[22:25]
	v_mfma_f32_16x16x32_bf16 v[14:17], v[152:155], v[208:211], v[14:17]
	v_mfma_f32_16x16x32_bf16 v[62:65], v[148:151], v[180:183], v[62:65]
	v_mfma_f32_16x16x32_bf16 v[58:61], v[156:159], v[180:183], v[58:61]
	v_mfma_f32_16x16x32_bf16 v[54:57], v[148:151], v[188:191], v[54:57]
	v_mfma_f32_16x16x32_bf16 v[46:49], v[156:159], v[188:191], v[46:49]
	v_mfma_f32_16x16x32_bf16 v[38:41], v[148:151], v[196:199], v[38:41]
	v_mfma_f32_16x16x32_bf16 v[30:33], v[156:159], v[196:199], v[30:33]
	v_mfma_f32_16x16x32_bf16 v[22:25], v[148:151], v[212:215], v[22:25]
	v_mfma_f32_16x16x32_bf16 v[14:17], v[156:159], v[212:215], v[14:17]
	v_mfma_f32_16x16x32_bf16 v[50:53], v[160:163], v[176:179], v[50:53]
	v_mfma_f32_16x16x32_bf16 v[42:45], v[168:171], v[176:179], v[42:45]
	v_mfma_f32_16x16x32_bf16 v[34:37], v[160:163], v[184:187], v[34:37]
	v_mfma_f32_16x16x32_bf16 v[26:29], v[168:171], v[184:187], v[26:29]
	v_mfma_f32_16x16x32_bf16 v[18:21], v[160:163], v[192:195], v[18:21]
	v_mfma_f32_16x16x32_bf16 v[10:13], v[168:171], v[192:195], v[10:13]
	v_mfma_f32_16x16x32_bf16 v[6:9], v[160:163], v[208:211], v[6:9]
	v_mfma_f32_16x16x32_bf16 v[2:5], v[168:171], v[208:211], v[2:5]
	v_mfma_f32_16x16x32_bf16 v[50:53], v[164:167], v[180:183], v[50:53]
	v_mfma_f32_16x16x32_bf16 v[42:45], v[172:175], v[180:183], v[42:45]
	v_mfma_f32_16x16x32_bf16 v[34:37], v[164:167], v[188:191], v[34:37]
	v_mfma_f32_16x16x32_bf16 v[26:29], v[172:175], v[188:191], v[26:29]
	v_mfma_f32_16x16x32_bf16 v[18:21], v[164:167], v[196:199], v[18:21]
	v_mfma_f32_16x16x32_bf16 v[10:13], v[172:175], v[196:199], v[10:13]
	v_mfma_f32_16x16x32_bf16 v[6:9], v[164:167], v[212:215], v[6:9]
	v_mfma_f32_16x16x32_bf16 v[2:5], v[172:175], v[212:215], v[2:5]
	s_barrier
	s_setprio 0
	s_branch .Lpeel_mid_7

.Lpeel_mid_7:
	v_add_u32_e32 v143, vcc_lo, v141
	ds_read_b128 v[144:147], v143
	ds_read_b128 v[148:151], v143 offset:1024
	ds_read_b128 v[152:155], v143 offset:2048
	ds_read_b128 v[156:159], v143 offset:3072
	v_add_u32_e32 v143, vcc_hi, v141
	ds_read_b128 v[160:163], v143
	ds_read_b128 v[164:167], v143 offset:1024
	ds_read_b128 v[168:171], v143 offset:2048
	ds_read_b128 v[172:175], v143 offset:3072
	s_mov_b32 m0, s39
	ds_read_b128 v[176:179], v142 offset:32768
	ds_read_b128 v[180:183], v142 offset:33792
	ds_read_b128 v[184:187], v142 offset:34816
	ds_read_b128 v[188:191], v142 offset:35840
	ds_read_b128 v[192:195], v142 offset:36864
	ds_read_b128 v[196:199], v142 offset:37888
	ds_read_b128 v[208:211], v142 offset:38912
	ds_read_b128 v[212:215], v142 offset:39936
	global_load_lds_dwordx4 v134, s[4:5]
	s_mov_b32 m0, s40
	s_nop 0
	global_load_lds_dwordx4 v132, s[4:5]
	s_waitcnt vmcnt(8)
	s_waitcnt lgkmcnt(0)
	s_setprio 1
	s_barrier
	v_mfma_f32_16x16x32_bf16 v[126:129], v[144:147], v[176:179], v[126:129]
	v_mfma_f32_16x16x32_bf16 v[122:125], v[152:155], v[176:179], v[122:125]
	v_mfma_f32_16x16x32_bf16 v[118:121], v[144:147], v[184:187], v[118:121]
	v_mfma_f32_16x16x32_bf16 v[110:113], v[152:155], v[184:187], v[110:113]
	v_mfma_f32_16x16x32_bf16 v[102:105], v[144:147], v[192:195], v[102:105]
	v_mfma_f32_16x16x32_bf16 v[94:97], v[152:155], v[192:195], v[94:97]
	v_mfma_f32_16x16x32_bf16 v[86:89], v[144:147], v[208:211], v[86:89]
	v_mfma_f32_16x16x32_bf16 v[78:81], v[152:155], v[208:211], v[78:81]
	v_mfma_f32_16x16x32_bf16 v[126:129], v[148:151], v[180:183], v[126:129]
	v_mfma_f32_16x16x32_bf16 v[122:125], v[156:159], v[180:183], v[122:125]
	v_mfma_f32_16x16x32_bf16 v[118:121], v[148:151], v[188:191], v[118:121]
	v_mfma_f32_16x16x32_bf16 v[110:113], v[156:159], v[188:191], v[110:113]
	v_mfma_f32_16x16x32_bf16 v[102:105], v[148:151], v[196:199], v[102:105]
	v_mfma_f32_16x16x32_bf16 v[94:97], v[156:159], v[196:199], v[94:97]
	v_mfma_f32_16x16x32_bf16 v[86:89], v[148:151], v[212:215], v[86:89]
	v_mfma_f32_16x16x32_bf16 v[78:81], v[156:159], v[212:215], v[78:81]
	v_mfma_f32_16x16x32_bf16 v[114:117], v[160:163], v[176:179], v[114:117]
	v_mfma_f32_16x16x32_bf16 v[106:109], v[168:171], v[176:179], v[106:109]
	v_mfma_f32_16x16x32_bf16 v[98:101], v[160:163], v[184:187], v[98:101]
	v_mfma_f32_16x16x32_bf16 v[90:93], v[168:171], v[184:187], v[90:93]
	v_mfma_f32_16x16x32_bf16 v[82:85], v[160:163], v[192:195], v[82:85]
	v_mfma_f32_16x16x32_bf16 v[74:77], v[168:171], v[192:195], v[74:77]
	v_mfma_f32_16x16x32_bf16 v[70:73], v[160:163], v[208:211], v[70:73]
	v_mfma_f32_16x16x32_bf16 v[66:69], v[168:171], v[208:211], v[66:69]
	v_mfma_f32_16x16x32_bf16 v[114:117], v[164:167], v[180:183], v[114:117]
	v_mfma_f32_16x16x32_bf16 v[106:109], v[172:175], v[180:183], v[106:109]
	v_mfma_f32_16x16x32_bf16 v[98:101], v[164:167], v[188:191], v[98:101]
	v_mfma_f32_16x16x32_bf16 v[90:93], v[172:175], v[188:191], v[90:93]
	v_mfma_f32_16x16x32_bf16 v[82:85], v[164:167], v[196:199], v[82:85]
	v_mfma_f32_16x16x32_bf16 v[74:77], v[172:175], v[196:199], v[74:77]
	v_mfma_f32_16x16x32_bf16 v[70:73], v[164:167], v[212:215], v[70:73]
	v_mfma_f32_16x16x32_bf16 v[66:69], v[172:175], v[212:215], v[66:69]
	s_barrier
	s_setprio 0
	s_mov_b32 m0, s61
	s_add_u32 s100, s26, 0x80
	s_addc_u32 s101, s27, 0
	ds_read_b128 v[176:179], v142 offset:49152
	ds_read_b128 v[180:183], v142 offset:50176
	ds_read_b128 v[184:187], v142 offset:51200
	ds_read_b128 v[188:191], v142 offset:52224
	ds_read_b128 v[192:195], v142 offset:53248
	ds_read_b128 v[196:199], v142 offset:54272
	ds_read_b128 v[208:211], v142 offset:55296
	ds_read_b128 v[212:215], v142 offset:56320
	global_load_lds_dwordx4 v202, s[100:101]
	s_add_u32 s100, s26, 0x80
	s_addc_u32 s101, s27, 0
	s_mov_b32 m0, s62
	s_nop 0
	global_load_lds_dwordx4 v130, s[100:101]
	s_mov_b32 m0, s55
	s_nop 0
	global_load_lds_dwordx4 v202, s[2:3]
	s_mov_b32 m0, s0
	s_nop 0
	global_load_lds_dwordx4 v130, s[2:3]
	s_add_u32 s100, s24, 0x80
	s_addc_u32 s101, s25, 0
	s_mov_b32 m0, s41
	s_nop 0
	global_load_lds_dwordx4 v134, s[100:101]
	s_add_u32 s100, s24, 0x80
	s_addc_u32 s101, s25, 0
	s_mov_b32 m0, s86
	s_nop 0
	global_load_lds_dwordx4 v132, s[100:101]
	s_waitcnt vmcnt(8)
	s_waitcnt lgkmcnt(0)
	s_setprio 1
	s_barrier
	v_mfma_f32_16x16x32_bf16 v[62:65], v[144:147], v[176:179], v[62:65]
	v_mfma_f32_16x16x32_bf16 v[58:61], v[152:155], v[176:179], v[58:61]
	v_mfma_f32_16x16x32_bf16 v[54:57], v[144:147], v[184:187], v[54:57]
	v_mfma_f32_16x16x32_bf16 v[46:49], v[152:155], v[184:187], v[46:49]
	v_mfma_f32_16x16x32_bf16 v[38:41], v[144:147], v[192:195], v[38:41]
	v_mfma_f32_16x16x32_bf16 v[30:33], v[152:155], v[192:195], v[30:33]
	v_mfma_f32_16x16x32_bf16 v[22:25], v[144:147], v[208:211], v[22:25]
	v_mfma_f32_16x16x32_bf16 v[14:17], v[152:155], v[208:211], v[14:17]
	v_mfma_f32_16x16x32_bf16 v[62:65], v[148:151], v[180:183], v[62:65]
	v_mfma_f32_16x16x32_bf16 v[58:61], v[156:159], v[180:183], v[58:61]
	v_mfma_f32_16x16x32_bf16 v[54:57], v[148:151], v[188:191], v[54:57]
	v_mfma_f32_16x16x32_bf16 v[46:49], v[156:159], v[188:191], v[46:49]
	v_mfma_f32_16x16x32_bf16 v[38:41], v[148:151], v[196:199], v[38:41]
	v_mfma_f32_16x16x32_bf16 v[30:33], v[156:159], v[196:199], v[30:33]
	v_mfma_f32_16x16x32_bf16 v[22:25], v[148:151], v[212:215], v[22:25]
	v_mfma_f32_16x16x32_bf16 v[14:17], v[156:159], v[212:215], v[14:17]
	v_mfma_f32_16x16x32_bf16 v[50:53], v[160:163], v[176:179], v[50:53]
	v_mfma_f32_16x16x32_bf16 v[42:45], v[168:171], v[176:179], v[42:45]
	v_mfma_f32_16x16x32_bf16 v[34:37], v[160:163], v[184:187], v[34:37]
	v_mfma_f32_16x16x32_bf16 v[26:29], v[168:171], v[184:187], v[26:29]
	v_mfma_f32_16x16x32_bf16 v[18:21], v[160:163], v[192:195], v[18:21]
	v_mfma_f32_16x16x32_bf16 v[10:13], v[168:171], v[192:195], v[10:13]
	v_mfma_f32_16x16x32_bf16 v[6:9], v[160:163], v[208:211], v[6:9]
	v_mfma_f32_16x16x32_bf16 v[2:5], v[168:171], v[208:211], v[2:5]
	v_mfma_f32_16x16x32_bf16 v[50:53], v[164:167], v[180:183], v[50:53]
	v_mfma_f32_16x16x32_bf16 v[42:45], v[172:175], v[180:183], v[42:45]
	v_mfma_f32_16x16x32_bf16 v[34:37], v[164:167], v[188:191], v[34:37]
	v_mfma_f32_16x16x32_bf16 v[26:29], v[172:175], v[188:191], v[26:29]
	v_mfma_f32_16x16x32_bf16 v[18:21], v[164:167], v[196:199], v[18:21]
	v_mfma_f32_16x16x32_bf16 v[10:13], v[172:175], v[196:199], v[10:13]
	v_mfma_f32_16x16x32_bf16 v[6:9], v[164:167], v[212:215], v[6:9]
	v_mfma_f32_16x16x32_bf16 v[2:5], v[172:175], v[212:215], v[2:5]
	s_barrier
	s_setprio 0
	s_andn2_b64 vcc, exec, s[22:23]
	s_mov_b64 s[2:3], -1
	s_mov_b64 s[22:23], 0
	s_mov_b64 s[4:5], 0x100
	s_cbranch_vccz .LBB0_1242
	s_mov_b32 s101, 0x80000001
	s_and_b64 vcc, exec, s[10:11]
	s_cbranch_vccz .LBB0_1245
	s_barrier

.LBB0_1359:
	v_readlane_b32 s16, v253, 28
	s_add_u32 s4, s8, 0x20080
	v_mov_b32_e32 v137, v203
	v_readlane_b32 s17, v253, 29
	s_addc_u32 s5, s9, 0
	s_add_i32 m0, s25, 0x18000
	v_lshl_add_u64 v[2:3], v[2:3], 0, s[80:81]
	v_lshl_add_u64 v[14:15], s[16:17], 0, v[136:137]
	v_mov_b32_e32 v133, v203
	s_waitcnt vmcnt(2)
	s_barrier
	global_load_lds_dwordx4 v[2:3], off
	v_lshl_add_u64 v[2:3], v[4:5], 0, s[80:81]
	s_add_i32 m0, s25, 0x1a000
	s_add_i32 s29, s25, 0x8000
	v_lshl_add_u64 v[16:17], s[16:17], 0, v[132:133]
	global_load_lds_dwordx4 v[2:3], off
	v_lshl_add_u64 v[2:3], v[14:15], 0, s[80:81]
	s_mov_b32 m0, s29
	s_add_i32 s30, s25, 0xa000
	global_load_lds_dwordx4 v[2:3], off
	v_lshl_add_u64 v[2:3], v[16:17], 0, s[80:81]
	s_mov_b32 m0, s30
	v_lshrrev_b32_e32 v18, 1, v12
	global_load_lds_dwordx4 v[2:3], off
	s_add_i32 m0, s25, 0x1c000
	v_lshl_add_u64 v[2:3], s[4:5], 0, v[134:135]
	global_load_lds_dwordx4 v[2:3], off
	v_lshl_add_u64 v[2:3], s[4:5], 0, v[130:131]
	s_add_i32 m0, s25, 0x1e000
	s_lshl_b32 s0, s0, 5
	global_load_lds_dwordx4 v[2:3], off
	v_and_b32_e32 v19, 24, v18
	s_and_b32 s0, s0, 0x60
	v_or_b32_e32 v3, s0, v19
	v_lshrrev_b32_e32 v144, 4, v3
	v_lshlrev_b32_e32 v3, 13, v10
	v_and_b32_e32 v3, 0xffffc000, v3
	v_lshl_add_u32 v3, v9, 10, v3
	v_and_b32_e32 v4, 1, v10
	v_lshl_or_b32 v3, v4, 6, v3
	v_and_b32_e32 v13, 15, v12
	v_lshlrev_b32_e32 v20, 1, v19
	v_lshlrev_b32_e32 v12, 2, v12
	v_lshl_add_u32 v138, v11, 1, v3
	v_lshlrev_b32_e32 v3, 13, v6
	v_lshl_or_b32 v142, s1, 6, v13
	v_lshl_or_b32 v13, v13, 6, v20
	s_lshl_b32 s1, s1, 13
	v_and_b32_e32 v12, 32, v12
	v_and_b32_e32 v3, 0xffffc000, v3
	v_bitop3_b32 v20, v13, s1, v12 bitop3:0xde
	s_lshl_b32 s1, s0, 7
	s_waitcnt vmcnt(6)
	v_lshl_add_u32 v3, v7, 10, v3
	v_and_b32_e32 v4, 1, v6
	v_bitop3_b32 v143, v13, s1, v12 bitop3:0xde
	v_add_u32_e32 v143, 0x10000, v143
	s_cmpk_lt_u32 s2, 0x100
	v_and_b32_e32 v2, 8, v18
	v_lshl_or_b32 v3, v4, 6, v3
	v_readlane_b32 s0, v253, 36
	s_cselect_b64 s[14:15], -1, 0
	v_or_b32_e32 v145, 8, v144
	v_mov_b32_e32 v139, v203
	v_lshl_add_u32 v140, v8, 1, v3
	v_mov_b32_e32 v141, v203
	s_mov_b32 s31, 0
	v_add_u32_e32 v146, 0, v20
	v_lshlrev_b32_e32 v202, 1, v2
	s_mov_b32 s35, s0
	s_mov_b32 s34, s56
	s_barrier
	v_readlane_b32 s1, v253, 37
	s_mov_b32 s101, 0
	s_branch .LBB0_1362

.LBB0_1362:
	s_add_i32 s31, s31, 1
	s_mul_i32 s4, s31, s96
	s_mov_b64 s[2:3], s[8:9]
	s_mov_b32 s8, s34
	s_mov_b32 s37, s34
	s_add_i32 s34, s4, s56
	s_cmpk_lt_i32 s34, 0x200
	s_mov_b32 s9, s35
	s_mov_b32 s36, s35
	s_cselect_b64 s[18:19], -1, 0
	s_ashr_i32 s35, s34, 2
	s_and_b64 s[4:5], s[18:19], exec
	s_cselect_b32 s8, s34, s8
	s_cselect_b32 s4, s35, s9
	s_ashr_i32 s9, s8, 31
	s_lshl_b64 s[8:9], s[8:9], 18
	s_mov_b64 s[0:1], s[16:17]
	s_add_u32 s16, s78, s8
	s_addc_u32 s17, s79, s9
	s_and_b64 s[8:9], s[18:19], exec
	s_cselect_b32 s38, s17, s1
	s_cselect_b32 s39, s16, s0
	s_ashr_i32 s5, s4, 31
	s_lshl_b64 s[4:5], s[4:5], 18
	s_add_u32 s8, s22, s4
	s_addc_u32 s9, s23, s5
	s_and_b64 s[4:5], s[18:19], exec
	s_cselect_b32 s40, s9, s3
	s_cselect_b32 s41, s8, s2
	s_add_u32 s20, s0, 0x20080
	s_addc_u32 s21, s1, 0
	s_add_u32 s49, s2, 0x100
	v_mov_b32_e32 v2, 0
	s_addc_u32 s58, s3, 0
	s_mov_b32 s59, -2
	v_mov_b32_e32 v3, v2
	v_pk_mov_b32 v[4:5], v[2:3], v[2:3] op_sel:[0,1]
	v_pk_mov_b32 v[6:7], v[2:3], v[2:3] op_sel:[0,1]
	v_pk_mov_b32 v[8:9], v[2:3], v[2:3] op_sel:[0,1]
	v_pk_mov_b32 v[18:19], v[2:3], v[2:3] op_sel:[0,1]
	v_pk_mov_b32 v[20:21], v[2:3], v[2:3] op_sel:[0,1]
	v_pk_mov_b32 v[22:23], v[2:3], v[2:3] op_sel:[0,1]
	v_pk_mov_b32 v[24:25], v[2:3], v[2:3] op_sel:[0,1]
	v_pk_mov_b32 v[34:35], v[2:3], v[2:3] op_sel:[0,1]
	v_pk_mov_b32 v[36:37], v[2:3], v[2:3] op_sel:[0,1]
	v_pk_mov_b32 v[38:39], v[2:3], v[2:3] op_sel:[0,1]
	v_pk_mov_b32 v[40:41], v[2:3], v[2:3] op_sel:[0,1]
	v_pk_mov_b32 v[50:51], v[2:3], v[2:3] op_sel:[0,1]
	v_pk_mov_b32 v[52:53], v[2:3], v[2:3] op_sel:[0,1]
	v_pk_mov_b32 v[54:55], v[2:3], v[2:3] op_sel:[0,1]
	v_pk_mov_b32 v[56:57], v[2:3], v[2:3] op_sel:[0,1]
	v_pk_mov_b32 v[10:11], v[2:3], v[2:3] op_sel:[0,1]
	v_pk_mov_b32 v[12:13], v[2:3], v[2:3] op_sel:[0,1]
	v_pk_mov_b32 v[14:15], v[2:3], v[2:3] op_sel:[0,1]
	v_pk_mov_b32 v[16:17], v[2:3], v[2:3] op_sel:[0,1]
	v_pk_mov_b32 v[26:27], v[2:3], v[2:3] op_sel:[0,1]
	v_pk_mov_b32 v[28:29], v[2:3], v[2:3] op_sel:[0,1]
	v_pk_mov_b32 v[30:31], v[2:3], v[2:3] op_sel:[0,1]
	v_pk_mov_b32 v[32:33], v[2:3], v[2:3] op_sel:[0,1]
	v_pk_mov_b32 v[42:43], v[2:3], v[2:3] op_sel:[0,1]
	v_pk_mov_b32 v[44:45], v[2:3], v[2:3] op_sel:[0,1]
	v_pk_mov_b32 v[46:47], v[2:3], v[2:3] op_sel:[0,1]
	v_pk_mov_b32 v[48:49], v[2:3], v[2:3] op_sel:[0,1]
	v_pk_mov_b32 v[58:59], v[2:3], v[2:3] op_sel:[0,1]
	v_pk_mov_b32 v[60:61], v[2:3], v[2:3] op_sel:[0,1]
	v_pk_mov_b32 v[62:63], v[2:3], v[2:3] op_sel:[0,1]
	v_pk_mov_b32 v[64:65], v[2:3], v[2:3] op_sel:[0,1]
	v_pk_mov_b32 v[66:67], v[2:3], v[2:3] op_sel:[0,1]
	v_pk_mov_b32 v[68:69], v[2:3], v[2:3] op_sel:[0,1]
	v_pk_mov_b32 v[70:71], v[2:3], v[2:3] op_sel:[0,1]
	v_pk_mov_b32 v[72:73], v[2:3], v[2:3] op_sel:[0,1]
	v_pk_mov_b32 v[82:83], v[2:3], v[2:3] op_sel:[0,1]
	v_pk_mov_b32 v[84:85], v[2:3], v[2:3] op_sel:[0,1]
	v_pk_mov_b32 v[86:87], v[2:3], v[2:3] op_sel:[0,1]
	v_pk_mov_b32 v[88:89], v[2:3], v[2:3] op_sel:[0,1]
	v_pk_mov_b32 v[98:99], v[2:3], v[2:3] op_sel:[0,1]
	v_pk_mov_b32 v[100:101], v[2:3], v[2:3] op_sel:[0,1]
	v_pk_mov_b32 v[102:103], v[2:3], v[2:3] op_sel:[0,1]
	v_pk_mov_b32 v[104:105], v[2:3], v[2:3] op_sel:[0,1]
	v_pk_mov_b32 v[114:115], v[2:3], v[2:3] op_sel:[0,1]
	v_pk_mov_b32 v[116:117], v[2:3], v[2:3] op_sel:[0,1]
	v_pk_mov_b32 v[118:119], v[2:3], v[2:3] op_sel:[0,1]
	v_pk_mov_b32 v[120:121], v[2:3], v[2:3] op_sel:[0,1]
	v_pk_mov_b32 v[74:75], v[2:3], v[2:3] op_sel:[0,1]
	v_pk_mov_b32 v[76:77], v[2:3], v[2:3] op_sel:[0,1]
	v_pk_mov_b32 v[78:79], v[2:3], v[2:3] op_sel:[0,1]
	v_pk_mov_b32 v[80:81], v[2:3], v[2:3] op_sel:[0,1]
	v_pk_mov_b32 v[90:91], v[2:3], v[2:3] op_sel:[0,1]
	v_pk_mov_b32 v[92:93], v[2:3], v[2:3] op_sel:[0,1]
	v_pk_mov_b32 v[94:95], v[2:3], v[2:3] op_sel:[0,1]
	v_pk_mov_b32 v[96:97], v[2:3], v[2:3] op_sel:[0,1]
	v_pk_mov_b32 v[106:107], v[2:3], v[2:3] op_sel:[0,1]
	v_pk_mov_b32 v[108:109], v[2:3], v[2:3] op_sel:[0,1]
	v_pk_mov_b32 v[110:111], v[2:3], v[2:3] op_sel:[0,1]
	v_pk_mov_b32 v[112:113], v[2:3], v[2:3] op_sel:[0,1]
	v_pk_mov_b32 v[122:123], v[2:3], v[2:3] op_sel:[0,1]
	v_pk_mov_b32 v[124:125], v[2:3], v[2:3] op_sel:[0,1]
	v_pk_mov_b32 v[126:127], v[2:3], v[2:3] op_sel:[0,1]
	v_pk_mov_b32 v[128:129], v[2:3], v[2:3] op_sel:[0,1]
	s_cmp_eq_u32 s101, 0x80000001
	s_cbranch_scc0 .LBB0_1363
	s_add_u32 s0, s20, 0xfffe0080
	s_addc_u32 s1, s21, -1
	s_add_i32 s33, 0, 0x10000
	s_cmp_eq_u32 s59, 4
	s_cselect_b32 s5, s38, s1
	s_cselect_b32 s4, s39, s0
	s_cselect_b32 s3, s40, s58
	s_cselect_b32 s2, s41, s49
	s_add_i32 s55, 0, 0x14000
	ds_read_b128 v[148:151], v143
	ds_read_b128 v[152:155], v143 offset:1024
	ds_read_b128 v[156:159], v143 offset:2048
	ds_read_b128 v[160:163], v143 offset:3072
	ds_read_b128 v[164:167], v143 offset:16384
	ds_read_b128 v[168:171], v143 offset:17408
	ds_read_b128 v[172:175], v143 offset:18432
	ds_read_b128 v[176:179], v143 offset:19456
	s_add_i32 m0, s25, 0xc000
	ds_read_b128 v[180:183], v146
	ds_read_b128 v[184:187], v146 offset:1024
	ds_read_b128 v[188:191], v146 offset:2048
	ds_read_b128 v[192:195], v146 offset:3072
	ds_read_b128 v[196:199], v146 offset:4096
	ds_read_b128 v[208:211], v146 offset:5120
	ds_read_b128 v[212:215], v146 offset:6144
	ds_read_b128 v[216:219], v146 offset:7168
	global_load_lds_dwordx4 v138, s[20:21]
	s_add_i32 m0, s25, 0xe000
	s_nop 0
	global_load_lds_dwordx4 v140, s[20:21]
	s_waitcnt vmcnt(24)
	s_waitcnt lgkmcnt(0)
	s_setprio 1
	s_barrier
	v_mfma_f32_16x16x32_bf16 v[126:129], v[148:151], v[180:183], v[126:129]
	v_mfma_f32_16x16x32_bf16 v[122:125], v[156:159], v[180:183], v[122:125]
	v_mfma_f32_16x16x32_bf16 v[110:113], v[148:151], v[188:191], v[110:113]
	v_mfma_f32_16x16x32_bf16 v[106:109], v[156:159], v[188:191], v[106:109]
	v_mfma_f32_16x16x32_bf16 v[94:97], v[148:151], v[196:199], v[94:97]
	v_mfma_f32_16x16x32_bf16 v[90:93], v[156:159], v[196:199], v[90:93]
	v_mfma_f32_16x16x32_bf16 v[78:81], v[148:151], v[212:215], v[78:81]
	v_mfma_f32_16x16x32_bf16 v[74:77], v[156:159], v[212:215], v[74:77]
	v_mfma_f32_16x16x32_bf16 v[126:129], v[152:155], v[184:187], v[126:129]
	v_mfma_f32_16x16x32_bf16 v[122:125], v[160:163], v[184:187], v[122:125]
	v_mfma_f32_16x16x32_bf16 v[110:113], v[152:155], v[192:195], v[110:113]
	v_mfma_f32_16x16x32_bf16 v[106:109], v[160:163], v[192:195], v[106:109]
	v_mfma_f32_16x16x32_bf16 v[94:97], v[152:155], v[208:211], v[94:97]
	v_mfma_f32_16x16x32_bf16 v[90:93], v[160:163], v[208:211], v[90:93]
	v_mfma_f32_16x16x32_bf16 v[78:81], v[152:155], v[216:219], v[78:81]
	v_mfma_f32_16x16x32_bf16 v[74:77], v[160:163], v[216:219], v[74:77]
	v_mfma_f32_16x16x32_bf16 v[118:121], v[164:167], v[180:183], v[118:121]
	v_mfma_f32_16x16x32_bf16 v[114:117], v[172:175], v[180:183], v[114:117]
	v_mfma_f32_16x16x32_bf16 v[102:105], v[164:167], v[188:191], v[102:105]
	v_mfma_f32_16x16x32_bf16 v[98:101], v[172:175], v[188:191], v[98:101]
	v_mfma_f32_16x16x32_bf16 v[86:89], v[164:167], v[196:199], v[86:89]
	v_mfma_f32_16x16x32_bf16 v[82:85], v[172:175], v[196:199], v[82:85]
	v_mfma_f32_16x16x32_bf16 v[70:73], v[164:167], v[212:215], v[70:73]
	v_mfma_f32_16x16x32_bf16 v[66:69], v[172:175], v[212:215], v[66:69]
	v_mfma_f32_16x16x32_bf16 v[118:121], v[168:171], v[184:187], v[118:121]
	v_mfma_f32_16x16x32_bf16 v[114:117], v[176:179], v[184:187], v[114:117]
	v_mfma_f32_16x16x32_bf16 v[102:105], v[168:171], v[192:195], v[102:105]
	v_mfma_f32_16x16x32_bf16 v[98:101], v[176:179], v[192:195], v[98:101]
	v_mfma_f32_16x16x32_bf16 v[86:89], v[168:171], v[208:211], v[86:89]
	v_mfma_f32_16x16x32_bf16 v[82:85], v[176:179], v[208:211], v[82:85]
	v_mfma_f32_16x16x32_bf16 v[70:73], v[168:171], v[216:219], v[70:73]
	v_mfma_f32_16x16x32_bf16 v[66:69], v[176:179], v[216:219], v[66:69]
	s_barrier
	s_setprio 0
	s_add_i32 s0, s33, s24
	s_mov_b32 m0, s0
	ds_read_b128 v[180:183], v146 offset:16384
	ds_read_b128 v[184:187], v146 offset:17408
	ds_read_b128 v[188:191], v146 offset:18432
	ds_read_b128 v[192:195], v146 offset:19456
	ds_read_b128 v[196:199], v146 offset:20480
	ds_read_b128 v[208:211], v146 offset:21504
	ds_read_b128 v[212:215], v146 offset:22528
	ds_read_b128 v[216:219], v146 offset:23552
	global_load_lds_dwordx4 v134, s[2:3]
	s_add_i32 m0, s0, 0x2000
	s_add_u32 s0, s2, 0x20000
	s_addc_u32 s1, s3, 0
	s_add_i32 s33, s55, s24
	global_load_lds_dwordx4 v130, s[2:3]
	s_mov_b32 m0, s33
	s_nop 0
	global_load_lds_dwordx4 v134, s[0:1]
	s_add_i32 m0, s33, 0x2000
	s_nop 0
	global_load_lds_dwordx4 v130, s[0:1]
	s_mov_b32 m0, s25
	s_nop 0
	global_load_lds_dwordx4 v136, s[4:5]
	s_mov_b32 m0, s26
	s_nop 0
	global_load_lds_dwordx4 v132, s[4:5]
	s_waitcnt vmcnt(24)
	s_waitcnt lgkmcnt(0)
	s_setprio 1
	s_barrier
	v_mfma_f32_16x16x32_bf16 v[62:65], v[148:151], v[180:183], v[62:65]
	v_mfma_f32_16x16x32_bf16 v[58:61], v[156:159], v[180:183], v[58:61]
	v_mfma_f32_16x16x32_bf16 v[46:49], v[148:151], v[188:191], v[46:49]
	v_mfma_f32_16x16x32_bf16 v[42:45], v[156:159], v[188:191], v[42:45]
	v_mfma_f32_16x16x32_bf16 v[30:33], v[148:151], v[196:199], v[30:33]
	v_mfma_f32_16x16x32_bf16 v[26:29], v[156:159], v[196:199], v[26:29]
	v_mfma_f32_16x16x32_bf16 v[14:17], v[148:151], v[212:215], v[14:17]
	v_mfma_f32_16x16x32_bf16 v[10:13], v[156:159], v[212:215], v[10:13]
	v_mfma_f32_16x16x32_bf16 v[62:65], v[152:155], v[184:187], v[62:65]
	v_mfma_f32_16x16x32_bf16 v[58:61], v[160:163], v[184:187], v[58:61]
	v_mfma_f32_16x16x32_bf16 v[46:49], v[152:155], v[192:195], v[46:49]
	v_mfma_f32_16x16x32_bf16 v[42:45], v[160:163], v[192:195], v[42:45]
	v_mfma_f32_16x16x32_bf16 v[30:33], v[152:155], v[208:211], v[30:33]
	v_mfma_f32_16x16x32_bf16 v[26:29], v[160:163], v[208:211], v[26:29]
	v_mfma_f32_16x16x32_bf16 v[14:17], v[152:155], v[216:219], v[14:17]
	v_mfma_f32_16x16x32_bf16 v[10:13], v[160:163], v[216:219], v[10:13]
	v_mfma_f32_16x16x32_bf16 v[54:57], v[164:167], v[180:183], v[54:57]
	v_mfma_f32_16x16x32_bf16 v[50:53], v[172:175], v[180:183], v[50:53]
	v_mfma_f32_16x16x32_bf16 v[38:41], v[164:167], v[188:191], v[38:41]
	v_mfma_f32_16x16x32_bf16 v[34:37], v[172:175], v[188:191], v[34:37]
	v_mfma_f32_16x16x32_bf16 v[22:25], v[164:167], v[196:199], v[22:25]
	v_mfma_f32_16x16x32_bf16 v[18:21], v[172:175], v[196:199], v[18:21]
	v_mfma_f32_16x16x32_bf16 v[6:9], v[164:167], v[212:215], v[6:9]
	v_mfma_f32_16x16x32_bf16 v[2:5], v[172:175], v[212:215], v[2:5]
	v_mfma_f32_16x16x32_bf16 v[54:57], v[168:171], v[184:187], v[54:57]
	v_mfma_f32_16x16x32_bf16 v[50:53], v[176:179], v[184:187], v[50:53]
	v_mfma_f32_16x16x32_bf16 v[38:41], v[168:171], v[192:195], v[38:41]
	v_mfma_f32_16x16x32_bf16 v[34:37], v[176:179], v[192:195], v[34:37]
	v_mfma_f32_16x16x32_bf16 v[22:25], v[168:171], v[208:211], v[22:25]
	v_mfma_f32_16x16x32_bf16 v[18:21], v[176:179], v[208:211], v[18:21]
	v_mfma_f32_16x16x32_bf16 v[6:9], v[168:171], v[216:219], v[6:9]
	v_mfma_f32_16x16x32_bf16 v[2:5], v[176:179], v[216:219], v[2:5]
	s_barrier
	s_setprio 0
	s_branch .Lpeel_mid_8

.Lpeel_mid_8:
	s_add_i32 s33, 0, 0x18000
	s_add_i32 s55, 0, 0x1c000
	ds_read_b128 v[148:151], v143 offset:32768
	ds_read_b128 v[152:155], v143 offset:33792
	ds_read_b128 v[156:159], v143 offset:34816
	ds_read_b128 v[160:163], v143 offset:35840
	ds_read_b128 v[164:167], v143 offset:49152
	ds_read_b128 v[168:171], v143 offset:50176
	ds_read_b128 v[172:175], v143 offset:51200
	ds_read_b128 v[176:179], v143 offset:52224
	s_add_u32 s0, s4, 0x20000
	s_addc_u32 s1, s5, 0
	s_mov_b32 m0, s27
	ds_read_b128 v[180:183], v146 offset:32768
	ds_read_b128 v[184:187], v146 offset:33792
	ds_read_b128 v[188:191], v146 offset:34816
	ds_read_b128 v[192:195], v146 offset:35840
	ds_read_b128 v[196:199], v146 offset:36864
	ds_read_b128 v[208:211], v146 offset:37888
	ds_read_b128 v[212:215], v146 offset:38912
	ds_read_b128 v[216:219], v146 offset:39936
	global_load_lds_dwordx4 v136, s[0:1]
	s_mov_b32 m0, s28
	s_nop 0
	global_load_lds_dwordx4 v132, s[0:1]
	s_waitcnt vmcnt(8)
	s_waitcnt lgkmcnt(0)
	s_setprio 1
	s_barrier
	v_mfma_f32_16x16x32_bf16 v[126:129], v[148:151], v[180:183], v[126:129]
	v_mfma_f32_16x16x32_bf16 v[122:125], v[156:159], v[180:183], v[122:125]
	v_mfma_f32_16x16x32_bf16 v[110:113], v[148:151], v[188:191], v[110:113]
	v_mfma_f32_16x16x32_bf16 v[106:109], v[156:159], v[188:191], v[106:109]
	v_mfma_f32_16x16x32_bf16 v[94:97], v[148:151], v[196:199], v[94:97]
	v_mfma_f32_16x16x32_bf16 v[90:93], v[156:159], v[196:199], v[90:93]
	v_mfma_f32_16x16x32_bf16 v[78:81], v[148:151], v[212:215], v[78:81]
	v_mfma_f32_16x16x32_bf16 v[74:77], v[156:159], v[212:215], v[74:77]
	v_mfma_f32_16x16x32_bf16 v[126:129], v[152:155], v[184:187], v[126:129]
	v_mfma_f32_16x16x32_bf16 v[122:125], v[160:163], v[184:187], v[122:125]
	v_mfma_f32_16x16x32_bf16 v[110:113], v[152:155], v[192:195], v[110:113]
	v_mfma_f32_16x16x32_bf16 v[106:109], v[160:163], v[192:195], v[106:109]
	v_mfma_f32_16x16x32_bf16 v[94:97], v[152:155], v[208:211], v[94:97]
	v_mfma_f32_16x16x32_bf16 v[90:93], v[160:163], v[208:211], v[90:93]
	v_mfma_f32_16x16x32_bf16 v[78:81], v[152:155], v[216:219], v[78:81]
	v_mfma_f32_16x16x32_bf16 v[74:77], v[160:163], v[216:219], v[74:77]
	v_mfma_f32_16x16x32_bf16 v[118:121], v[164:167], v[180:183], v[118:121]
	v_mfma_f32_16x16x32_bf16 v[114:117], v[172:175], v[180:183], v[114:117]
	v_mfma_f32_16x16x32_bf16 v[102:105], v[164:167], v[188:191], v[102:105]
	v_mfma_f32_16x16x32_bf16 v[98:101], v[172:175], v[188:191], v[98:101]
	v_mfma_f32_16x16x32_bf16 v[86:89], v[164:167], v[196:199], v[86:89]
	v_mfma_f32_16x16x32_bf16 v[82:85], v[172:175], v[196:199], v[82:85]
	v_mfma_f32_16x16x32_bf16 v[70:73], v[164:167], v[212:215], v[70:73]
	v_mfma_f32_16x16x32_bf16 v[66:69], v[172:175], v[212:215], v[66:69]
	v_mfma_f32_16x16x32_bf16 v[118:121], v[168:171], v[184:187], v[118:121]
	v_mfma_f32_16x16x32_bf16 v[114:117], v[176:179], v[184:187], v[114:117]
	v_mfma_f32_16x16x32_bf16 v[102:105], v[168:171], v[192:195], v[102:105]
	v_mfma_f32_16x16x32_bf16 v[98:101], v[176:179], v[192:195], v[98:101]
	v_mfma_f32_16x16x32_bf16 v[86:89], v[168:171], v[208:211], v[86:89]
	v_mfma_f32_16x16x32_bf16 v[82:85], v[176:179], v[208:211], v[82:85]
	v_mfma_f32_16x16x32_bf16 v[70:73], v[168:171], v[216:219], v[70:73]
	v_mfma_f32_16x16x32_bf16 v[66:69], v[176:179], v[216:219], v[66:69]
	s_barrier
	s_setprio 0
	s_add_i32 s0, s33, s24
	s_add_u32 s100, s2, 0x80
	s_addc_u32 s101, s3, 0
	s_mov_b32 m0, s0
	ds_read_b128 v[180:183], v146 offset:49152
	ds_read_b128 v[184:187], v146 offset:50176
	ds_read_b128 v[188:191], v146 offset:51200
	ds_read_b128 v[192:195], v146 offset:52224
	ds_read_b128 v[196:199], v146 offset:53248
	ds_read_b128 v[208:211], v146 offset:54272
	ds_read_b128 v[212:215], v146 offset:55296
	ds_read_b128 v[216:219], v146 offset:56320
	global_load_lds_dwordx4 v134, s[100:101]
	s_add_i32 m0, s0, 0x2000
	s_add_u32 s100, s2, 0x80
	s_addc_u32 s101, s3, 0
	s_add_u32 s0, s2, 0x20080
	s_addc_u32 s1, s3, 0
	s_add_i32 s2, s55, s24
	global_load_lds_dwordx4 v130, s[100:101]
	s_mov_b32 m0, s2
	s_nop 0
	global_load_lds_dwordx4 v134, s[0:1]
	s_add_i32 m0, s2, 0x2000
	s_nop 0
	global_load_lds_dwordx4 v130, s[0:1]
	s_add_u32 s100, s4, 0x80
	s_addc_u32 s101, s5, 0
	s_mov_b32 m0, s29
	s_nop 0
	global_load_lds_dwordx4 v136, s[100:101]
	s_add_u32 s100, s4, 0x80
	s_addc_u32 s101, s5, 0
	s_mov_b32 m0, s30
	s_nop 0
	global_load_lds_dwordx4 v132, s[100:101]
	s_waitcnt vmcnt(8)
	s_waitcnt lgkmcnt(0)
	s_setprio 1
	s_barrier
	v_mfma_f32_16x16x32_bf16 v[62:65], v[148:151], v[180:183], v[62:65]
	v_mfma_f32_16x16x32_bf16 v[58:61], v[156:159], v[180:183], v[58:61]
	v_mfma_f32_16x16x32_bf16 v[46:49], v[148:151], v[188:191], v[46:49]
	v_mfma_f32_16x16x32_bf16 v[42:45], v[156:159], v[188:191], v[42:45]
	v_mfma_f32_16x16x32_bf16 v[30:33], v[148:151], v[196:199], v[30:33]
	v_mfma_f32_16x16x32_bf16 v[26:29], v[156:159], v[196:199], v[26:29]
	v_mfma_f32_16x16x32_bf16 v[14:17], v[148:151], v[212:215], v[14:17]
	v_mfma_f32_16x16x32_bf16 v[10:13], v[156:159], v[212:215], v[10:13]
	v_mfma_f32_16x16x32_bf16 v[62:65], v[152:155], v[184:187], v[62:65]
	v_mfma_f32_16x16x32_bf16 v[58:61], v[160:163], v[184:187], v[58:61]
	v_mfma_f32_16x16x32_bf16 v[46:49], v[152:155], v[192:195], v[46:49]
	v_mfma_f32_16x16x32_bf16 v[42:45], v[160:163], v[192:195], v[42:45]
	v_mfma_f32_16x16x32_bf16 v[30:33], v[152:155], v[208:211], v[30:33]
	v_mfma_f32_16x16x32_bf16 v[26:29], v[160:163], v[208:211], v[26:29]
	v_mfma_f32_16x16x32_bf16 v[14:17], v[152:155], v[216:219], v[14:17]
	v_mfma_f32_16x16x32_bf16 v[10:13], v[160:163], v[216:219], v[10:13]
	v_mfma_f32_16x16x32_bf16 v[54:57], v[164:167], v[180:183], v[54:57]
	v_mfma_f32_16x16x32_bf16 v[50:53], v[172:175], v[180:183], v[50:53]
	v_mfma_f32_16x16x32_bf16 v[38:41], v[164:167], v[188:191], v[38:41]
	v_mfma_f32_16x16x32_bf16 v[34:37], v[172:175], v[188:191], v[34:37]
	v_mfma_f32_16x16x32_bf16 v[22:25], v[164:167], v[196:199], v[22:25]
	v_mfma_f32_16x16x32_bf16 v[18:21], v[172:175], v[196:199], v[18:21]
	v_mfma_f32_16x16x32_bf16 v[6:9], v[164:167], v[212:215], v[6:9]
	v_mfma_f32_16x16x32_bf16 v[2:5], v[172:175], v[212:215], v[2:5]
	v_mfma_f32_16x16x32_bf16 v[54:57], v[168:171], v[184:187], v[54:57]
	v_mfma_f32_16x16x32_bf16 v[50:53], v[176:179], v[184:187], v[50:53]
	v_mfma_f32_16x16x32_bf16 v[38:41], v[168:171], v[192:195], v[38:41]
	v_mfma_f32_16x16x32_bf16 v[34:37], v[176:179], v[192:195], v[34:37]
	v_mfma_f32_16x16x32_bf16 v[22:25], v[168:171], v[208:211], v[22:25]
	v_mfma_f32_16x16x32_bf16 v[18:21], v[176:179], v[208:211], v[18:21]
	v_mfma_f32_16x16x32_bf16 v[6:9], v[168:171], v[216:219], v[6:9]
	v_mfma_f32_16x16x32_bf16 v[2:5], v[176:179], v[216:219], v[2:5]
	s_barrier
	s_setprio 0
	s_add_i32 s59, s59, 2
	s_add_u32 s20, s20, 0x100
	s_addc_u32 s21, s21, 0
	s_add_u32 s49, s49, 0x100
	s_addc_u32 s58, s58, 0
	s_cmp_gt_u32 s59, 5
	s_cbranch_scc0 .LBB0_1363
	s_mov_b32 s101, 0x80000001
	s_and_b64 vcc, exec, s[14:15]
	s_cbranch_vccz .LBB0_1366
	s_barrier

.LBB0_1422:
	v_lshrrev_b32_e32 v18, 1, v16
	v_readlane_b32 s0, v254, 58
	v_and_b32_e32 v18, 24, v18
	v_readlane_b32 s1, v254, 59
	s_add_u32 s37, s0, 0x4000
	v_and_b32_e32 v17, 15, v16
	v_lshlrev_b32_e32 v19, 1, v18
	v_lshlrev_b32_e32 v16, 2, v16
	s_addc_u32 s38, s1, 0
	v_lshl_or_b32 v186, s10, 6, v17
	v_lshl_or_b32 v17, v17, 6, v19
	s_lshl_b32 s0, s10, 13
	v_and_b32_e32 v16, 32, v16
	v_bitop3_b32 v19, v17, s0, v16 bitop3:0xde
	s_lshl_b32 s0, s7, 5
	s_and_b32 s7, s0, 0x60
	s_add_i32 m0, s23, 0x18000
	v_lshl_add_u64 v[8:9], v[8:9], 0, s[80:81]
	s_lshl_b32 s0, s7, 7
	s_waitcnt vmcnt(2)
	s_barrier
	global_load_lds_dwordx4 v[8:9], off
	v_lshl_add_u64 v[6:7], v[6:7], 0, s[80:81]
	s_add_i32 m0, s23, 0x1a000
	s_add_i32 s39, s23, 0x8000
	s_add_i32 s40, s23, 0xa000
	v_bitop3_b32 v187, v17, s0, v16 bitop3:0xde
	v_add_u32_e32 v187, 0x10000, v187
	global_load_lds_dwordx4 v[6:7], off
	v_lshl_add_u64 v[2:3], v[2:3], 0, s[80:81]
	s_mov_b32 m0, s39
	s_add_u32 s0, s2, 0x80080
	global_load_lds_dwordx4 v[2:3], off
	v_lshl_add_u64 v[2:3], v[4:5], 0, s[80:81]
	s_mov_b32 m0, s40
	s_addc_u32 s1, s3, 0
	global_load_lds_dwordx4 v[2:3], off
	s_add_i32 m0, s23, 0x1c000
	v_lshl_add_u64 v[2:3], s[0:1], 0, v[202:203]
	global_load_lds_dwordx4 v[2:3], off
	v_lshl_add_u64 v[2:3], s[0:1], 0, v[162:163]
	s_add_i32 m0, s23, 0x1e000
	s_cmpk_lt_u32 s6, 0x100
	global_load_lds_dwordx4 v[2:3], off
	v_lshlrev_b32_e32 v2, 15, v14
	v_and_b32_e32 v2, 0xffff0000, v2
	v_lshl_add_u32 v2, v13, 12, v2
	v_and_b32_e32 v3, 1, v14
	v_lshl_or_b32 v2, v3, 6, v2
	v_lshl_add_u32 v168, v15, 1, v2
	v_lshlrev_b32_e32 v2, 15, v10
	v_and_b32_e32 v2, 0xffff0000, v2
	s_waitcnt vmcnt(6)
	v_lshl_add_u32 v2, v11, 12, v2
	v_and_b32_e32 v3, 1, v10
	v_lshl_or_b32 v2, v3, 6, v2
	s_cselect_b64 s[10:11], -1, 0
	v_or_b32_e32 v188, s7, v18
	v_mov_b32_e32 v169, v203
	v_lshl_add_u32 v170, v12, 1, v2
	v_mov_b32_e32 v171, v203
	s_mov_b32 s41, 0
	v_add_u32_e32 v189, 0, v19
	s_barrier
	s_mov_b32 s101, 0
	s_branch .LBB0_1425

.LBB0_1427:
	s_ashr_i32 s17, s16, 31
	s_lshl_b64 s[0:1], s[16:17], 20
	s_add_u32 s18, s64, s0
	s_addc_u32 s19, s65, s1
	s_and_b64 s[0:1], s[6:7], exec
	s_cselect_b32 s17, s19, s5
	s_cselect_b32 s49, s18, s4
	s_ashr_i32 s15, s14, 31
	s_lshl_b64 s[0:1], s[14:15], 20
	s_add_u32 s20, s28, s0
	s_addc_u32 s21, s29, s1
	s_and_b64 s[0:1], s[6:7], exec
	s_cselect_b32 s15, s21, s3
	s_cselect_b32 s58, s20, s2
	s_add_u32 s26, s4, 0x80080
	s_addc_u32 s27, s5, 0
	s_add_u32 s59, s2, 0x100
	v_mov_b32_e32 v2, 0
	s_addc_u32 s60, s3, 0
	s_mov_b32 s61, -2
	v_mov_b32_e32 v3, v2
	v_pk_mov_b32 v[4:5], v[2:3], v[2:3] op_sel:[0,1]
	v_pk_mov_b32 v[10:11], v[2:3], v[2:3] op_sel:[0,1]
	v_pk_mov_b32 v[12:13], v[2:3], v[2:3] op_sel:[0,1]
	v_pk_mov_b32 v[18:19], v[2:3], v[2:3] op_sel:[0,1]
	v_pk_mov_b32 v[20:21], v[2:3], v[2:3] op_sel:[0,1]
	v_pk_mov_b32 v[26:27], v[2:3], v[2:3] op_sel:[0,1]
	v_pk_mov_b32 v[28:29], v[2:3], v[2:3] op_sel:[0,1]
	v_pk_mov_b32 v[34:35], v[2:3], v[2:3] op_sel:[0,1]
	v_pk_mov_b32 v[36:37], v[2:3], v[2:3] op_sel:[0,1]
	v_pk_mov_b32 v[42:43], v[2:3], v[2:3] op_sel:[0,1]
	v_pk_mov_b32 v[44:45], v[2:3], v[2:3] op_sel:[0,1]
	v_pk_mov_b32 v[50:51], v[2:3], v[2:3] op_sel:[0,1]
	v_pk_mov_b32 v[52:53], v[2:3], v[2:3] op_sel:[0,1]
	v_pk_mov_b32 v[58:59], v[2:3], v[2:3] op_sel:[0,1]
	v_pk_mov_b32 v[60:61], v[2:3], v[2:3] op_sel:[0,1]
	v_pk_mov_b32 v[6:7], v[2:3], v[2:3] op_sel:[0,1]
	v_pk_mov_b32 v[8:9], v[2:3], v[2:3] op_sel:[0,1]
	v_pk_mov_b32 v[14:15], v[2:3], v[2:3] op_sel:[0,1]
	v_pk_mov_b32 v[16:17], v[2:3], v[2:3] op_sel:[0,1]
	v_pk_mov_b32 v[22:23], v[2:3], v[2:3] op_sel:[0,1]
	v_pk_mov_b32 v[24:25], v[2:3], v[2:3] op_sel:[0,1]
	v_pk_mov_b32 v[30:31], v[2:3], v[2:3] op_sel:[0,1]
	v_pk_mov_b32 v[32:33], v[2:3], v[2:3] op_sel:[0,1]
	v_pk_mov_b32 v[38:39], v[2:3], v[2:3] op_sel:[0,1]
	v_pk_mov_b32 v[40:41], v[2:3], v[2:3] op_sel:[0,1]
	v_pk_mov_b32 v[46:47], v[2:3], v[2:3] op_sel:[0,1]
	v_pk_mov_b32 v[48:49], v[2:3], v[2:3] op_sel:[0,1]
	v_pk_mov_b32 v[54:55], v[2:3], v[2:3] op_sel:[0,1]
	v_pk_mov_b32 v[56:57], v[2:3], v[2:3] op_sel:[0,1]
	v_pk_mov_b32 v[62:63], v[2:3], v[2:3] op_sel:[0,1]
	v_pk_mov_b32 v[64:65], v[2:3], v[2:3] op_sel:[0,1]
	v_pk_mov_b32 v[66:67], v[2:3], v[2:3] op_sel:[0,1]
	v_pk_mov_b32 v[68:69], v[2:3], v[2:3] op_sel:[0,1]
	v_pk_mov_b32 v[74:75], v[2:3], v[2:3] op_sel:[0,1]
	v_pk_mov_b32 v[76:77], v[2:3], v[2:3] op_sel:[0,1]
	v_pk_mov_b32 v[82:83], v[2:3], v[2:3] op_sel:[0,1]
	v_pk_mov_b32 v[84:85], v[2:3], v[2:3] op_sel:[0,1]
	v_pk_mov_b32 v[90:91], v[2:3], v[2:3] op_sel:[0,1]
	v_pk_mov_b32 v[92:93], v[2:3], v[2:3] op_sel:[0,1]
	v_pk_mov_b32 v[98:99], v[2:3], v[2:3] op_sel:[0,1]
	v_pk_mov_b32 v[100:101], v[2:3], v[2:3] op_sel:[0,1]
	v_pk_mov_b32 v[106:107], v[2:3], v[2:3] op_sel:[0,1]
	v_pk_mov_b32 v[108:109], v[2:3], v[2:3] op_sel:[0,1]
	v_pk_mov_b32 v[114:115], v[2:3], v[2:3] op_sel:[0,1]
	v_pk_mov_b32 v[116:117], v[2:3], v[2:3] op_sel:[0,1]
	v_pk_mov_b32 v[122:123], v[2:3], v[2:3] op_sel:[0,1]
	v_pk_mov_b32 v[124:125], v[2:3], v[2:3] op_sel:[0,1]
	v_pk_mov_b32 v[70:71], v[2:3], v[2:3] op_sel:[0,1]
	v_pk_mov_b32 v[72:73], v[2:3], v[2:3] op_sel:[0,1]
	v_pk_mov_b32 v[78:79], v[2:3], v[2:3] op_sel:[0,1]
	v_pk_mov_b32 v[80:81], v[2:3], v[2:3] op_sel:[0,1]
	v_pk_mov_b32 v[86:87], v[2:3], v[2:3] op_sel:[0,1]
	v_pk_mov_b32 v[88:89], v[2:3], v[2:3] op_sel:[0,1]
	v_pk_mov_b32 v[94:95], v[2:3], v[2:3] op_sel:[0,1]
	v_pk_mov_b32 v[96:97], v[2:3], v[2:3] op_sel:[0,1]
	v_pk_mov_b32 v[102:103], v[2:3], v[2:3] op_sel:[0,1]
	v_pk_mov_b32 v[104:105], v[2:3], v[2:3] op_sel:[0,1]
	v_pk_mov_b32 v[110:111], v[2:3], v[2:3] op_sel:[0,1]
	v_pk_mov_b32 v[112:113], v[2:3], v[2:3] op_sel:[0,1]
	v_pk_mov_b32 v[118:119], v[2:3], v[2:3] op_sel:[0,1]
	v_pk_mov_b32 v[120:121], v[2:3], v[2:3] op_sel:[0,1]
	v_pk_mov_b32 v[130:131], v[2:3], v[2:3] op_sel:[0,1]
	v_pk_mov_b32 v[132:133], v[2:3], v[2:3] op_sel:[0,1]
	s_cmp_eq_u32 s101, 0x80000001
	s_cbranch_scc0 .LBB0_1428
	s_add_u32 s0, s26, 0xfff80080
	s_addc_u32 s1, s27, -1
	s_add_i32 s33, 0, 0x10000
	s_cmp_eq_u32 s61, 28
	s_cselect_b32 s5, s17, s1
	s_cselect_b32 s4, s49, s0
	s_cselect_b32 s3, s15, s60
	s_cselect_b32 s2, s58, s59
	s_add_i32 s55, 0, 0x14000
	ds_read_b128 v[126:129], v187
	ds_read_b128 v[134:137], v187 offset:1024
	ds_read_b128 v[138:141], v187 offset:2048
	ds_read_b128 v[142:145], v187 offset:3072
	ds_read_b128 v[146:149], v187 offset:16384
	ds_read_b128 v[150:153], v187 offset:17408
	ds_read_b128 v[154:157], v187 offset:18432
	ds_read_b128 v[158:161], v187 offset:19456
	s_add_i32 m0, s23, 0xc000
	ds_read_b128 v[172:175], v189
	ds_read_b128 v[176:179], v189 offset:1024
	ds_read_b128 v[180:183], v189 offset:2048
	ds_read_b128 v[190:193], v189 offset:3072
	ds_read_b128 v[194:197], v189 offset:4096
	ds_read_b128 v[198:201], v189 offset:5120
	ds_read_b128 v[208:211], v189 offset:6144
	ds_read_b128 v[212:215], v189 offset:7168
	global_load_lds_dwordx4 v168, s[26:27]
	s_add_i32 m0, s23, 0xe000
	s_nop 0
	global_load_lds_dwordx4 v170, s[26:27]
	s_waitcnt vmcnt(16)
	s_waitcnt lgkmcnt(0)
	s_setprio 1
	s_barrier
	v_mfma_f32_16x16x32_bf16 v[130:133], v[126:129], v[172:175], v[130:133]
	v_mfma_f32_16x16x32_bf16 v[118:121], v[138:141], v[172:175], v[118:121]
	v_mfma_f32_16x16x32_bf16 v[110:113], v[126:129], v[180:183], v[110:113]
	v_mfma_f32_16x16x32_bf16 v[102:105], v[138:141], v[180:183], v[102:105]
	v_mfma_f32_16x16x32_bf16 v[94:97], v[126:129], v[194:197], v[94:97]
	v_mfma_f32_16x16x32_bf16 v[86:89], v[138:141], v[194:197], v[86:89]
	v_mfma_f32_16x16x32_bf16 v[78:81], v[126:129], v[208:211], v[78:81]
	v_mfma_f32_16x16x32_bf16 v[70:73], v[138:141], v[208:211], v[70:73]
	v_mfma_f32_16x16x32_bf16 v[130:133], v[134:137], v[176:179], v[130:133]
	v_mfma_f32_16x16x32_bf16 v[118:121], v[142:145], v[176:179], v[118:121]
	v_mfma_f32_16x16x32_bf16 v[110:113], v[134:137], v[190:193], v[110:113]
	v_mfma_f32_16x16x32_bf16 v[102:105], v[142:145], v[190:193], v[102:105]
	v_mfma_f32_16x16x32_bf16 v[94:97], v[134:137], v[198:201], v[94:97]
	v_mfma_f32_16x16x32_bf16 v[86:89], v[142:145], v[198:201], v[86:89]
	v_mfma_f32_16x16x32_bf16 v[78:81], v[134:137], v[212:215], v[78:81]
	v_mfma_f32_16x16x32_bf16 v[70:73], v[142:145], v[212:215], v[70:73]
	v_mfma_f32_16x16x32_bf16 v[122:125], v[146:149], v[172:175], v[122:125]
	v_mfma_f32_16x16x32_bf16 v[114:117], v[154:157], v[172:175], v[114:117]
	v_mfma_f32_16x16x32_bf16 v[106:109], v[146:149], v[180:183], v[106:109]
	v_mfma_f32_16x16x32_bf16 v[98:101], v[154:157], v[180:183], v[98:101]
	v_mfma_f32_16x16x32_bf16 v[90:93], v[146:149], v[194:197], v[90:93]
	v_mfma_f32_16x16x32_bf16 v[82:85], v[154:157], v[194:197], v[82:85]
	v_mfma_f32_16x16x32_bf16 v[74:77], v[146:149], v[208:211], v[74:77]
	v_mfma_f32_16x16x32_bf16 v[66:69], v[154:157], v[208:211], v[66:69]
	v_mfma_f32_16x16x32_bf16 v[122:125], v[150:153], v[176:179], v[122:125]
	v_mfma_f32_16x16x32_bf16 v[114:117], v[158:161], v[176:179], v[114:117]
	v_mfma_f32_16x16x32_bf16 v[106:109], v[150:153], v[190:193], v[106:109]
	v_mfma_f32_16x16x32_bf16 v[98:101], v[158:161], v[190:193], v[98:101]
	v_mfma_f32_16x16x32_bf16 v[90:93], v[150:153], v[198:201], v[90:93]
	v_mfma_f32_16x16x32_bf16 v[82:85], v[158:161], v[198:201], v[82:85]
	v_mfma_f32_16x16x32_bf16 v[74:77], v[150:153], v[212:215], v[74:77]
	v_mfma_f32_16x16x32_bf16 v[66:69], v[158:161], v[212:215], v[66:69]
	s_barrier
	s_setprio 0
	s_add_i32 s0, s33, s34
	s_mov_b32 m0, s0
	ds_read_b128 v[172:175], v189 offset:16384
	ds_read_b128 v[176:179], v189 offset:17408
	ds_read_b128 v[180:183], v189 offset:18432
	ds_read_b128 v[190:193], v189 offset:19456
	ds_read_b128 v[194:197], v189 offset:20480
	ds_read_b128 v[198:201], v189 offset:21504
	ds_read_b128 v[208:211], v189 offset:22528
	ds_read_b128 v[212:215], v189 offset:23552
	global_load_lds_dwordx4 v202, s[2:3]
	s_add_i32 m0, s0, 0x2000
	s_add_u32 s0, s2, 0x80000
	s_addc_u32 s1, s3, 0
	s_add_i32 s33, s55, s34
	global_load_lds_dwordx4 v162, s[2:3]
	s_mov_b32 m0, s33
	s_nop 0
	global_load_lds_dwordx4 v202, s[0:1]
	s_add_i32 m0, s33, 0x2000
	s_nop 0
	global_load_lds_dwordx4 v162, s[0:1]
	s_mov_b32 m0, s23
	s_nop 0
	global_load_lds_dwordx4 v166, s[4:5]
	s_mov_b32 m0, s25
	s_nop 0
	global_load_lds_dwordx4 v164, s[4:5]
	s_waitcnt vmcnt(16)
	s_waitcnt lgkmcnt(0)
	s_setprio 1
	s_barrier
	v_mfma_f32_16x16x32_bf16 v[62:65], v[126:129], v[172:175], v[62:65]
	v_mfma_f32_16x16x32_bf16 v[54:57], v[138:141], v[172:175], v[54:57]
	v_mfma_f32_16x16x32_bf16 v[46:49], v[126:129], v[180:183], v[46:49]
	v_mfma_f32_16x16x32_bf16 v[38:41], v[138:141], v[180:183], v[38:41]
	v_mfma_f32_16x16x32_bf16 v[30:33], v[126:129], v[194:197], v[30:33]
	v_mfma_f32_16x16x32_bf16 v[22:25], v[138:141], v[194:197], v[22:25]
	v_mfma_f32_16x16x32_bf16 v[14:17], v[126:129], v[208:211], v[14:17]
	v_mfma_f32_16x16x32_bf16 v[6:9], v[138:141], v[208:211], v[6:9]
	v_mfma_f32_16x16x32_bf16 v[62:65], v[134:137], v[176:179], v[62:65]
	v_mfma_f32_16x16x32_bf16 v[54:57], v[142:145], v[176:179], v[54:57]
	v_mfma_f32_16x16x32_bf16 v[46:49], v[134:137], v[190:193], v[46:49]
	v_mfma_f32_16x16x32_bf16 v[38:41], v[142:145], v[190:193], v[38:41]
	v_mfma_f32_16x16x32_bf16 v[30:33], v[134:137], v[198:201], v[30:33]
	v_mfma_f32_16x16x32_bf16 v[22:25], v[142:145], v[198:201], v[22:25]
	v_mfma_f32_16x16x32_bf16 v[14:17], v[134:137], v[212:215], v[14:17]
	v_mfma_f32_16x16x32_bf16 v[6:9], v[142:145], v[212:215], v[6:9]
	v_mfma_f32_16x16x32_bf16 v[58:61], v[146:149], v[172:175], v[58:61]
	v_mfma_f32_16x16x32_bf16 v[50:53], v[154:157], v[172:175], v[50:53]
	v_mfma_f32_16x16x32_bf16 v[42:45], v[146:149], v[180:183], v[42:45]
	v_mfma_f32_16x16x32_bf16 v[34:37], v[154:157], v[180:183], v[34:37]
	v_mfma_f32_16x16x32_bf16 v[26:29], v[146:149], v[194:197], v[26:29]
	v_mfma_f32_16x16x32_bf16 v[18:21], v[154:157], v[194:197], v[18:21]
	v_mfma_f32_16x16x32_bf16 v[10:13], v[146:149], v[208:211], v[10:13]
	v_mfma_f32_16x16x32_bf16 v[2:5], v[154:157], v[208:211], v[2:5]
	v_mfma_f32_16x16x32_bf16 v[58:61], v[150:153], v[176:179], v[58:61]
	v_mfma_f32_16x16x32_bf16 v[50:53], v[158:161], v[176:179], v[50:53]
	v_mfma_f32_16x16x32_bf16 v[42:45], v[150:153], v[190:193], v[42:45]
	v_mfma_f32_16x16x32_bf16 v[34:37], v[158:161], v[190:193], v[34:37]
	v_mfma_f32_16x16x32_bf16 v[26:29], v[150:153], v[198:201], v[26:29]
	v_mfma_f32_16x16x32_bf16 v[18:21], v[158:161], v[198:201], v[18:21]
	v_mfma_f32_16x16x32_bf16 v[10:13], v[150:153], v[212:215], v[10:13]
	v_mfma_f32_16x16x32_bf16 v[2:5], v[158:161], v[212:215], v[2:5]
	s_barrier
	s_setprio 0
	s_branch .Lpeel_mid_9

.Lpeel_mid_9:
	s_add_i32 s33, 0, 0x18000
	s_add_i32 s55, 0, 0x1c000
	ds_read_b128 v[126:129], v187 offset:32768
	ds_read_b128 v[134:137], v187 offset:33792
	ds_read_b128 v[138:141], v187 offset:34816
	ds_read_b128 v[142:145], v187 offset:35840
	ds_read_b128 v[146:149], v187 offset:49152
	ds_read_b128 v[150:153], v187 offset:50176
	ds_read_b128 v[154:157], v187 offset:51200
	ds_read_b128 v[158:161], v187 offset:52224
	s_add_u32 s0, s4, 0x80000
	s_addc_u32 s1, s5, 0
	s_mov_b32 m0, s35
	ds_read_b128 v[172:175], v189 offset:32768
	ds_read_b128 v[176:179], v189 offset:33792
	ds_read_b128 v[180:183], v189 offset:34816
	ds_read_b128 v[190:193], v189 offset:35840
	ds_read_b128 v[194:197], v189 offset:36864
	ds_read_b128 v[198:201], v189 offset:37888
	ds_read_b128 v[208:211], v189 offset:38912
	ds_read_b128 v[212:215], v189 offset:39936
	global_load_lds_dwordx4 v166, s[0:1]
	s_mov_b32 m0, s36
	s_nop 0
	global_load_lds_dwordx4 v164, s[0:1]
	s_waitcnt vmcnt(8)
	s_waitcnt lgkmcnt(0)
	s_setprio 1
	s_barrier
	v_mfma_f32_16x16x32_bf16 v[130:133], v[126:129], v[172:175], v[130:133]
	v_mfma_f32_16x16x32_bf16 v[118:121], v[138:141], v[172:175], v[118:121]
	v_mfma_f32_16x16x32_bf16 v[110:113], v[126:129], v[180:183], v[110:113]
	v_mfma_f32_16x16x32_bf16 v[102:105], v[138:141], v[180:183], v[102:105]
	v_mfma_f32_16x16x32_bf16 v[94:97], v[126:129], v[194:197], v[94:97]
	v_mfma_f32_16x16x32_bf16 v[86:89], v[138:141], v[194:197], v[86:89]
	v_mfma_f32_16x16x32_bf16 v[78:81], v[126:129], v[208:211], v[78:81]
	v_mfma_f32_16x16x32_bf16 v[70:73], v[138:141], v[208:211], v[70:73]
	v_mfma_f32_16x16x32_bf16 v[130:133], v[134:137], v[176:179], v[130:133]
	v_mfma_f32_16x16x32_bf16 v[118:121], v[142:145], v[176:179], v[118:121]
	v_mfma_f32_16x16x32_bf16 v[110:113], v[134:137], v[190:193], v[110:113]
	v_mfma_f32_16x16x32_bf16 v[102:105], v[142:145], v[190:193], v[102:105]
	v_mfma_f32_16x16x32_bf16 v[94:97], v[134:137], v[198:201], v[94:97]
	v_mfma_f32_16x16x32_bf16 v[86:89], v[142:145], v[198:201], v[86:89]
	v_mfma_f32_16x16x32_bf16 v[78:81], v[134:137], v[212:215], v[78:81]
	v_mfma_f32_16x16x32_bf16 v[70:73], v[142:145], v[212:215], v[70:73]
	v_mfma_f32_16x16x32_bf16 v[122:125], v[146:149], v[172:175], v[122:125]
	v_mfma_f32_16x16x32_bf16 v[114:117], v[154:157], v[172:175], v[114:117]
	v_mfma_f32_16x16x32_bf16 v[106:109], v[146:149], v[180:183], v[106:109]
	v_mfma_f32_16x16x32_bf16 v[98:101], v[154:157], v[180:183], v[98:101]
	v_mfma_f32_16x16x32_bf16 v[90:93], v[146:149], v[194:197], v[90:93]
	v_mfma_f32_16x16x32_bf16 v[82:85], v[154:157], v[194:197], v[82:85]
	v_mfma_f32_16x16x32_bf16 v[74:77], v[146:149], v[208:211], v[74:77]
	v_mfma_f32_16x16x32_bf16 v[66:69], v[154:157], v[208:211], v[66:69]
	v_mfma_f32_16x16x32_bf16 v[122:125], v[150:153], v[176:179], v[122:125]
	v_mfma_f32_16x16x32_bf16 v[114:117], v[158:161], v[176:179], v[114:117]
	v_mfma_f32_16x16x32_bf16 v[106:109], v[150:153], v[190:193], v[106:109]
	v_mfma_f32_16x16x32_bf16 v[98:101], v[158:161], v[190:193], v[98:101]
	v_mfma_f32_16x16x32_bf16 v[90:93], v[150:153], v[198:201], v[90:93]
	v_mfma_f32_16x16x32_bf16 v[82:85], v[158:161], v[198:201], v[82:85]
	v_mfma_f32_16x16x32_bf16 v[74:77], v[150:153], v[212:215], v[74:77]
	v_mfma_f32_16x16x32_bf16 v[66:69], v[158:161], v[212:215], v[66:69]
	s_barrier
	s_setprio 0
	s_add_i32 s0, s33, s34
	s_add_u32 s100, s2, 0x80
	s_addc_u32 s101, s3, 0
	s_mov_b32 m0, s0
	ds_read_b128 v[172:175], v189 offset:49152
	ds_read_b128 v[176:179], v189 offset:50176
	ds_read_b128 v[180:183], v189 offset:51200
	ds_read_b128 v[190:193], v189 offset:52224
	ds_read_b128 v[194:197], v189 offset:53248
	ds_read_b128 v[198:201], v189 offset:54272
	ds_read_b128 v[208:211], v189 offset:55296
	ds_read_b128 v[212:215], v189 offset:56320
	global_load_lds_dwordx4 v202, s[100:101]
	s_add_i32 m0, s0, 0x2000
	s_add_u32 s100, s2, 0x80
	s_addc_u32 s101, s3, 0
	s_add_u32 s0, s2, 0x80080
	s_addc_u32 s1, s3, 0
	s_add_i32 s2, s55, s34
	global_load_lds_dwordx4 v162, s[100:101]
	s_mov_b32 m0, s2
	s_nop 0
	global_load_lds_dwordx4 v202, s[0:1]
	s_add_i32 m0, s2, 0x2000
	s_nop 0
	global_load_lds_dwordx4 v162, s[0:1]
	s_add_u32 s100, s4, 0x80
	s_addc_u32 s101, s5, 0
	s_mov_b32 m0, s39
	s_nop 0
	global_load_lds_dwordx4 v166, s[100:101]
	s_add_u32 s100, s4, 0x80
	s_addc_u32 s101, s5, 0
	s_mov_b32 m0, s40
	s_nop 0
	global_load_lds_dwordx4 v164, s[100:101]
	s_waitcnt vmcnt(8)
	s_waitcnt lgkmcnt(0)
	s_setprio 1
	s_barrier
	v_mfma_f32_16x16x32_bf16 v[62:65], v[126:129], v[172:175], v[62:65]
	v_mfma_f32_16x16x32_bf16 v[54:57], v[138:141], v[172:175], v[54:57]
	v_mfma_f32_16x16x32_bf16 v[46:49], v[126:129], v[180:183], v[46:49]
	v_mfma_f32_16x16x32_bf16 v[38:41], v[138:141], v[180:183], v[38:41]
	v_mfma_f32_16x16x32_bf16 v[30:33], v[126:129], v[194:197], v[30:33]
	v_mfma_f32_16x16x32_bf16 v[22:25], v[138:141], v[194:197], v[22:25]
	v_mfma_f32_16x16x32_bf16 v[14:17], v[126:129], v[208:211], v[14:17]
	v_mfma_f32_16x16x32_bf16 v[6:9], v[138:141], v[208:211], v[6:9]
	v_mfma_f32_16x16x32_bf16 v[62:65], v[134:137], v[176:179], v[62:65]
	v_mfma_f32_16x16x32_bf16 v[54:57], v[142:145], v[176:179], v[54:57]
	v_mfma_f32_16x16x32_bf16 v[46:49], v[134:137], v[190:193], v[46:49]
	v_mfma_f32_16x16x32_bf16 v[38:41], v[142:145], v[190:193], v[38:41]
	v_mfma_f32_16x16x32_bf16 v[30:33], v[134:137], v[198:201], v[30:33]
	v_mfma_f32_16x16x32_bf16 v[22:25], v[142:145], v[198:201], v[22:25]
	v_mfma_f32_16x16x32_bf16 v[14:17], v[134:137], v[212:215], v[14:17]
	v_mfma_f32_16x16x32_bf16 v[6:9], v[142:145], v[212:215], v[6:9]
	v_mfma_f32_16x16x32_bf16 v[58:61], v[146:149], v[172:175], v[58:61]
	v_mfma_f32_16x16x32_bf16 v[50:53], v[154:157], v[172:175], v[50:53]
	v_mfma_f32_16x16x32_bf16 v[42:45], v[146:149], v[180:183], v[42:45]
	v_mfma_f32_16x16x32_bf16 v[34:37], v[154:157], v[180:183], v[34:37]
	v_mfma_f32_16x16x32_bf16 v[26:29], v[146:149], v[194:197], v[26:29]
	v_mfma_f32_16x16x32_bf16 v[18:21], v[154:157], v[194:197], v[18:21]
	v_mfma_f32_16x16x32_bf16 v[10:13], v[146:149], v[208:211], v[10:13]
	v_mfma_f32_16x16x32_bf16 v[2:5], v[154:157], v[208:211], v[2:5]
	v_mfma_f32_16x16x32_bf16 v[58:61], v[150:153], v[176:179], v[58:61]
	v_mfma_f32_16x16x32_bf16 v[50:53], v[158:161], v[176:179], v[50:53]
	v_mfma_f32_16x16x32_bf16 v[42:45], v[150:153], v[190:193], v[42:45]
	v_mfma_f32_16x16x32_bf16 v[34:37], v[158:161], v[190:193], v[34:37]
	v_mfma_f32_16x16x32_bf16 v[26:29], v[150:153], v[198:201], v[26:29]
	v_mfma_f32_16x16x32_bf16 v[18:21], v[158:161], v[198:201], v[18:21]
	v_mfma_f32_16x16x32_bf16 v[10:13], v[150:153], v[212:215], v[10:13]
	v_mfma_f32_16x16x32_bf16 v[2:5], v[158:161], v[212:215], v[2:5]
	s_barrier
	s_setprio 0
	s_add_i32 s61, s61, 2
	s_add_u32 s26, s26, 0x100
	s_addc_u32 s27, s27, 0
	s_add_u32 s59, s59, 0x100
	s_addc_u32 s60, s60, 0
	s_cmp_gt_u32 s61, 29
	s_cbranch_scc0 .LBB0_1428
	s_mov_b32 s101, 0x80000001
	s_and_b64 vcc, exec, s[10:11]
	s_cbranch_vccz .LBB0_1431
	s_barrier

.LBB0_1704:
	v_readlane_b32 s8, v254, 58
	v_readlane_b32 s9, v254, 59
	s_add_u32 s31, s8, 0xa000
	v_lshrrev_b32_e32 v20, 1, v14
	v_readlane_b32 s4, v253, 52
	s_addc_u32 s34, s9, 0
	v_and_b32_e32 v20, 24, v20
	s_lshl_b32 s0, s0, 5
	v_mov_b32_e32 v213, v203
	v_readlane_b32 s5, v253, 53
	v_and_b32_e32 v15, 15, v14
	v_lshlrev_b32_e32 v21, 1, v20
	v_lshlrev_b32_e32 v14, 2, v14
	s_and_b32 s3, s0, 0x60
	s_add_i32 m0, s27, 0x18000
	v_lshl_add_u64 v[2:3], v[2:3], 0, s[80:81]
	v_lshl_add_u64 v[16:17], s[4:5], 0, v[212:213]
	v_mov_b32_e32 v211, v203
	v_lshl_or_b32 v204, s1, 6, v15
	v_lshl_or_b32 v15, v15, 6, v21
	s_lshl_b32 s1, s1, 13
	v_and_b32_e32 v14, 32, v14
	s_lshl_b32 s0, s3, 7
	s_waitcnt vmcnt(2)
	s_barrier
	global_load_lds_dwordx4 v[2:3], off
	v_lshl_add_u64 v[2:3], v[4:5], 0, s[80:81]
	s_add_i32 m0, s27, 0x1a000
	s_add_i32 s35, s27, 0x8000
	s_add_i32 s36, s27, 0xa000
	v_lshl_add_u64 v[18:19], s[4:5], 0, v[210:211]
	v_bitop3_b32 v205, v15, s0, v14 bitop3:0xde
	v_add_u32_e32 v205, 0x10000, v205
	global_load_lds_dwordx4 v[2:3], off
	v_lshl_add_u64 v[2:3], v[16:17], 0, s[80:81]
	s_mov_b32 m0, s35
	s_add_u32 s0, s18, 0x160080
	v_bitop3_b32 v21, v15, s1, v14 bitop3:0xde
	global_load_lds_dwordx4 v[2:3], off
	v_lshl_add_u64 v[2:3], v[18:19], 0, s[80:81]
	s_mov_b32 m0, s36
	s_addc_u32 s1, s19, 0
	global_load_lds_dwordx4 v[2:3], off
	s_add_i32 m0, s27, 0x1c000
	v_lshl_add_u64 v[2:3], s[0:1], 0, v[202:203]
	global_load_lds_dwordx4 v[2:3], off
	v_lshl_add_u64 v[2:3], s[0:1], 0, v[208:209]
	s_add_i32 m0, s27, 0x1e000
	v_or_b32_e32 v238, s3, v20
	global_load_lds_dwordx4 v[2:3], off
	s_movk_i32 s3, 0x1600
	s_cmpk_lt_u32 s2, 0x100
	v_lshrrev_b32_e32 v3, 1, v11
	v_mul_lo_u32 v2, v10, s3
	s_mov_b32 s2, 0x16000
	v_mad_u64_u32 v[2:3], s[0:1], v3, s2, v[2:3]
	v_or_b32_e32 v2, v2, v12
	v_add_lshl_u32 v2, v2, v13, 1
	v_mov_b32_e32 v3, v203
	s_mov_b64 s[8:9], 0x160080
	v_lshl_add_u64 v[214:215], v[2:3], 0, s[8:9]
	v_lshrrev_b32_e32 v3, 1, v6
	v_mul_lo_u32 v2, v7, s3
	v_mad_u64_u32 v[2:3], s[0:1], v3, s2, v[2:3]
	s_waitcnt vmcnt(6)
	v_or_b32_e32 v2, v2, v8
	v_add_lshl_u32 v2, v2, v9, 1
	v_mov_b32_e32 v3, v203
	v_readlane_b32 s0, v253, 50
	s_cselect_b64 s[14:15], -1, 0
	v_lshl_add_u64 v[216:217], v[2:3], 0, s[8:9]
	s_mov_b32 s37, 0
	v_add_u32_e32 v239, 0, v21
	v_readlane_b32 s41, v254, 44
	s_mov_b32 s40, s0
	s_barrier
	v_readlane_b32 s1, v253, 51
	s_mov_b32 s101, 0
	s_branch .LBB0_1707

.LBB0_1717:
	s_add_u32 s49, s18, 0x100
	v_mov_b32_e32 v2, 0
	s_addc_u32 s58, s19, 0
	s_mov_b32 s59, -2
	v_mov_b32_e32 v3, v2
	v_pk_mov_b32 v[4:5], v[2:3], v[2:3] op_sel:[0,1]
	v_pk_mov_b32 v[6:7], v[2:3], v[2:3] op_sel:[0,1]
	v_pk_mov_b32 v[8:9], v[2:3], v[2:3] op_sel:[0,1]
	v_pk_mov_b32 v[18:19], v[2:3], v[2:3] op_sel:[0,1]
	v_pk_mov_b32 v[20:21], v[2:3], v[2:3] op_sel:[0,1]
	v_pk_mov_b32 v[22:23], v[2:3], v[2:3] op_sel:[0,1]
	v_pk_mov_b32 v[24:25], v[2:3], v[2:3] op_sel:[0,1]
	v_pk_mov_b32 v[34:35], v[2:3], v[2:3] op_sel:[0,1]
	v_pk_mov_b32 v[36:37], v[2:3], v[2:3] op_sel:[0,1]
	v_pk_mov_b32 v[38:39], v[2:3], v[2:3] op_sel:[0,1]
	v_pk_mov_b32 v[40:41], v[2:3], v[2:3] op_sel:[0,1]
	v_pk_mov_b32 v[50:51], v[2:3], v[2:3] op_sel:[0,1]
	v_pk_mov_b32 v[52:53], v[2:3], v[2:3] op_sel:[0,1]
	v_pk_mov_b32 v[54:55], v[2:3], v[2:3] op_sel:[0,1]
	v_pk_mov_b32 v[56:57], v[2:3], v[2:3] op_sel:[0,1]
	v_pk_mov_b32 v[10:11], v[2:3], v[2:3] op_sel:[0,1]
	v_pk_mov_b32 v[12:13], v[2:3], v[2:3] op_sel:[0,1]
	v_pk_mov_b32 v[14:15], v[2:3], v[2:3] op_sel:[0,1]
	v_pk_mov_b32 v[16:17], v[2:3], v[2:3] op_sel:[0,1]
	v_pk_mov_b32 v[26:27], v[2:3], v[2:3] op_sel:[0,1]
	v_pk_mov_b32 v[28:29], v[2:3], v[2:3] op_sel:[0,1]
	v_pk_mov_b32 v[30:31], v[2:3], v[2:3] op_sel:[0,1]
	v_pk_mov_b32 v[32:33], v[2:3], v[2:3] op_sel:[0,1]
	v_pk_mov_b32 v[42:43], v[2:3], v[2:3] op_sel:[0,1]
	v_pk_mov_b32 v[44:45], v[2:3], v[2:3] op_sel:[0,1]
	v_pk_mov_b32 v[46:47], v[2:3], v[2:3] op_sel:[0,1]
	v_pk_mov_b32 v[48:49], v[2:3], v[2:3] op_sel:[0,1]
	v_pk_mov_b32 v[58:59], v[2:3], v[2:3] op_sel:[0,1]
	v_pk_mov_b32 v[60:61], v[2:3], v[2:3] op_sel:[0,1]
	v_pk_mov_b32 v[62:63], v[2:3], v[2:3] op_sel:[0,1]
	v_pk_mov_b32 v[64:65], v[2:3], v[2:3] op_sel:[0,1]
	v_pk_mov_b32 v[66:67], v[2:3], v[2:3] op_sel:[0,1]
	v_pk_mov_b32 v[68:69], v[2:3], v[2:3] op_sel:[0,1]
	v_pk_mov_b32 v[70:71], v[2:3], v[2:3] op_sel:[0,1]
	v_pk_mov_b32 v[72:73], v[2:3], v[2:3] op_sel:[0,1]
	v_pk_mov_b32 v[90:91], v[2:3], v[2:3] op_sel:[0,1]
	v_pk_mov_b32 v[92:93], v[2:3], v[2:3] op_sel:[0,1]
	v_pk_mov_b32 v[102:103], v[2:3], v[2:3] op_sel:[0,1]
	v_pk_mov_b32 v[104:105], v[2:3], v[2:3] op_sel:[0,1]
	v_pk_mov_b32 v[122:123], v[2:3], v[2:3] op_sel:[0,1]
	v_pk_mov_b32 v[124:125], v[2:3], v[2:3] op_sel:[0,1]
	v_pk_mov_b32 v[130:131], v[2:3], v[2:3] op_sel:[0,1]
	v_pk_mov_b32 v[132:133], v[2:3], v[2:3] op_sel:[0,1]
	v_pk_mov_b32 v[150:151], v[2:3], v[2:3] op_sel:[0,1]
	v_pk_mov_b32 v[152:153], v[2:3], v[2:3] op_sel:[0,1]
	v_pk_mov_b32 v[154:155], v[2:3], v[2:3] op_sel:[0,1]
	v_pk_mov_b32 v[156:157], v[2:3], v[2:3] op_sel:[0,1]
	v_pk_mov_b32 v[74:75], v[2:3], v[2:3] op_sel:[0,1]
	v_pk_mov_b32 v[76:77], v[2:3], v[2:3] op_sel:[0,1]
	v_pk_mov_b32 v[86:87], v[2:3], v[2:3] op_sel:[0,1]
	v_pk_mov_b32 v[88:89], v[2:3], v[2:3] op_sel:[0,1]
	v_pk_mov_b32 v[114:115], v[2:3], v[2:3] op_sel:[0,1]
	v_pk_mov_b32 v[116:117], v[2:3], v[2:3] op_sel:[0,1]
	v_pk_mov_b32 v[118:119], v[2:3], v[2:3] op_sel:[0,1]
	v_pk_mov_b32 v[120:121], v[2:3], v[2:3] op_sel:[0,1]
	v_pk_mov_b32 v[138:139], v[2:3], v[2:3] op_sel:[0,1]
	v_pk_mov_b32 v[140:141], v[2:3], v[2:3] op_sel:[0,1]
	v_pk_mov_b32 v[142:143], v[2:3], v[2:3] op_sel:[0,1]
	v_pk_mov_b32 v[144:145], v[2:3], v[2:3] op_sel:[0,1]
	v_pk_mov_b32 v[162:163], v[2:3], v[2:3] op_sel:[0,1]
	v_pk_mov_b32 v[164:165], v[2:3], v[2:3] op_sel:[0,1]
	v_pk_mov_b32 v[170:171], v[2:3], v[2:3] op_sel:[0,1]
	v_pk_mov_b32 v[172:173], v[2:3], v[2:3] op_sel:[0,1]
	s_cmp_eq_u32 s101, 0x80000001
	s_cbranch_scc0 .LBB0_1718
	s_add_u32 s18, s4, 0x100
	s_addc_u32 s19, s5, 0
	s_add_i32 s0, 0, 0x10000
	s_cmpk_eq_i32 s59, 0x54
	s_cselect_b32 s23, s9, s19
	s_cselect_b32 s22, s8, s18
	s_cselect_b32 s21, s17, s58
	s_cselect_b32 s20, s16, s49
	s_add_i32 s33, 0, 0x14000
	ds_read_b128 v[78:81], v205
	ds_read_b128 v[82:85], v205 offset:1024
	ds_read_b128 v[94:97], v205 offset:2048
	ds_read_b128 v[98:101], v205 offset:3072
	ds_read_b128 v[106:109], v205 offset:16384
	ds_read_b128 v[110:113], v205 offset:17408
	ds_read_b128 v[126:129], v205 offset:18432
	ds_read_b128 v[134:137], v205 offset:19456
	s_add_i32 m0, s27, 0xc000
	ds_read_b128 v[146:149], v239
	ds_read_b128 v[158:161], v239 offset:1024
	ds_read_b128 v[166:169], v239 offset:2048
	ds_read_b128 v[174:177], v239 offset:3072
	ds_read_b128 v[178:181], v239 offset:4096
	ds_read_b128 v[182:185], v239 offset:5120
	ds_read_b128 v[186:189], v239 offset:6144
	ds_read_b128 v[190:193], v239 offset:7168
	global_load_lds_dwordx4 v214, s[4:5]
	s_add_i32 m0, s27, 0xe000
	s_nop 0
	global_load_lds_dwordx4 v216, s[4:5]
	s_waitcnt vmcnt(24)
	s_waitcnt lgkmcnt(0)
	s_setprio 1
	s_barrier
	v_mfma_f32_16x16x32_bf16 v[170:173], v[78:81], v[146:149], v[170:173]
	v_mfma_f32_16x16x32_bf16 v[162:165], v[94:97], v[146:149], v[162:165]
	v_mfma_f32_16x16x32_bf16 v[142:145], v[78:81], v[166:169], v[142:145]
	v_mfma_f32_16x16x32_bf16 v[138:141], v[94:97], v[166:169], v[138:141]
	v_mfma_f32_16x16x32_bf16 v[118:121], v[78:81], v[178:181], v[118:121]
	v_mfma_f32_16x16x32_bf16 v[114:117], v[94:97], v[178:181], v[114:117]
	v_mfma_f32_16x16x32_bf16 v[86:89], v[78:81], v[186:189], v[86:89]
	v_mfma_f32_16x16x32_bf16 v[74:77], v[94:97], v[186:189], v[74:77]
	v_mfma_f32_16x16x32_bf16 v[170:173], v[82:85], v[158:161], v[170:173]
	v_mfma_f32_16x16x32_bf16 v[162:165], v[98:101], v[158:161], v[162:165]
	v_mfma_f32_16x16x32_bf16 v[142:145], v[82:85], v[174:177], v[142:145]
	v_mfma_f32_16x16x32_bf16 v[138:141], v[98:101], v[174:177], v[138:141]
	v_mfma_f32_16x16x32_bf16 v[118:121], v[82:85], v[182:185], v[118:121]
	v_mfma_f32_16x16x32_bf16 v[114:117], v[98:101], v[182:185], v[114:117]
	v_mfma_f32_16x16x32_bf16 v[86:89], v[82:85], v[190:193], v[86:89]
	v_mfma_f32_16x16x32_bf16 v[74:77], v[98:101], v[190:193], v[74:77]
	v_mfma_f32_16x16x32_bf16 v[154:157], v[106:109], v[146:149], v[154:157]
	v_mfma_f32_16x16x32_bf16 v[130:133], v[106:109], v[166:169], v[130:133]
	v_mfma_f32_16x16x32_bf16 v[122:125], v[126:129], v[166:169], v[122:125]
	v_mfma_f32_16x16x32_bf16 v[102:105], v[106:109], v[178:181], v[102:105]
	v_mfma_f32_16x16x32_bf16 v[90:93], v[126:129], v[178:181], v[90:93]
	v_mfma_f32_16x16x32_bf16 v[70:73], v[106:109], v[186:189], v[70:73]
	v_mfma_f32_16x16x32_bf16 v[66:69], v[126:129], v[186:189], v[66:69]
	v_mfma_f32_16x16x32_bf16 v[154:157], v[110:113], v[158:161], v[154:157]
	v_mfma_f32_16x16x32_bf16 v[146:149], v[126:129], v[146:149], v[150:153]
	v_mfma_f32_16x16x32_bf16 v[130:133], v[110:113], v[174:177], v[130:133]
	v_mfma_f32_16x16x32_bf16 v[122:125], v[134:137], v[174:177], v[122:125]
	v_mfma_f32_16x16x32_bf16 v[102:105], v[110:113], v[182:185], v[102:105]
	v_mfma_f32_16x16x32_bf16 v[90:93], v[134:137], v[182:185], v[90:93]
	v_mfma_f32_16x16x32_bf16 v[70:73], v[110:113], v[190:193], v[70:73]
	v_mfma_f32_16x16x32_bf16 v[66:69], v[134:137], v[190:193], v[66:69]
	v_mfma_f32_16x16x32_bf16 v[146:149], v[134:137], v[158:161], v[146:149]
	s_barrier
	s_setprio 0
	s_add_i32 s0, s0, s26
	s_mov_b32 m0, s0
	ds_read_b128 v[150:153], v239 offset:16384
	ds_read_b128 v[158:161], v239 offset:17408
	ds_read_b128 v[166:169], v239 offset:18432
	ds_read_b128 v[174:177], v239 offset:19456
	ds_read_b128 v[178:181], v239 offset:20480
	ds_read_b128 v[182:185], v239 offset:21504
	ds_read_b128 v[186:189], v239 offset:22528
	ds_read_b128 v[190:193], v239 offset:23552
	global_load_lds_dwordx4 v202, s[20:21]
	s_add_i32 m0, s0, 0x2000
	s_add_u32 s0, s20, 0x160000
	s_addc_u32 s1, s21, 0
	s_add_i32 s4, s33, s26
	global_load_lds_dwordx4 v208, s[20:21]
	s_mov_b32 m0, s4
	s_nop 0
	global_load_lds_dwordx4 v202, s[0:1]
	s_add_i32 m0, s4, 0x2000
	s_nop 0
	global_load_lds_dwordx4 v208, s[0:1]
	s_mov_b32 m0, s27
	s_nop 0
	global_load_lds_dwordx4 v212, s[22:23]
	s_mov_b32 m0, s28
	s_nop 0
	global_load_lds_dwordx4 v210, s[22:23]
	s_waitcnt vmcnt(24)
	s_waitcnt lgkmcnt(0)
	s_setprio 1
	s_barrier
	v_mfma_f32_16x16x32_bf16 v[62:65], v[78:81], v[150:153], v[62:65]
	v_mfma_f32_16x16x32_bf16 v[58:61], v[94:97], v[150:153], v[58:61]
	v_mfma_f32_16x16x32_bf16 v[46:49], v[78:81], v[166:169], v[46:49]
	v_mfma_f32_16x16x32_bf16 v[42:45], v[94:97], v[166:169], v[42:45]
	v_mfma_f32_16x16x32_bf16 v[30:33], v[78:81], v[178:181], v[30:33]
	v_mfma_f32_16x16x32_bf16 v[26:29], v[94:97], v[178:181], v[26:29]
	v_mfma_f32_16x16x32_bf16 v[14:17], v[78:81], v[186:189], v[14:17]
	v_mfma_f32_16x16x32_bf16 v[10:13], v[94:97], v[186:189], v[10:13]
	v_mfma_f32_16x16x32_bf16 v[62:65], v[82:85], v[158:161], v[62:65]
	v_mfma_f32_16x16x32_bf16 v[58:61], v[98:101], v[158:161], v[58:61]
	v_mfma_f32_16x16x32_bf16 v[46:49], v[82:85], v[174:177], v[46:49]
	v_mfma_f32_16x16x32_bf16 v[42:45], v[98:101], v[174:177], v[42:45]
	v_mfma_f32_16x16x32_bf16 v[30:33], v[82:85], v[182:185], v[30:33]
	v_mfma_f32_16x16x32_bf16 v[26:29], v[98:101], v[182:185], v[26:29]
	v_mfma_f32_16x16x32_bf16 v[14:17], v[82:85], v[190:193], v[14:17]
	v_mfma_f32_16x16x32_bf16 v[10:13], v[98:101], v[190:193], v[10:13]
	v_mfma_f32_16x16x32_bf16 v[54:57], v[106:109], v[150:153], v[54:57]
	v_mfma_f32_16x16x32_bf16 v[50:53], v[126:129], v[150:153], v[50:53]
	v_mfma_f32_16x16x32_bf16 v[38:41], v[106:109], v[166:169], v[38:41]
	v_mfma_f32_16x16x32_bf16 v[34:37], v[126:129], v[166:169], v[34:37]
	v_mfma_f32_16x16x32_bf16 v[22:25], v[106:109], v[178:181], v[22:25]
	v_mfma_f32_16x16x32_bf16 v[18:21], v[126:129], v[178:181], v[18:21]
	v_mfma_f32_16x16x32_bf16 v[6:9], v[106:109], v[186:189], v[6:9]
	v_mfma_f32_16x16x32_bf16 v[2:5], v[126:129], v[186:189], v[2:5]
	v_mfma_f32_16x16x32_bf16 v[54:57], v[110:113], v[158:161], v[54:57]
	v_mfma_f32_16x16x32_bf16 v[50:53], v[134:137], v[158:161], v[50:53]
	v_mfma_f32_16x16x32_bf16 v[38:41], v[110:113], v[174:177], v[38:41]
	v_mfma_f32_16x16x32_bf16 v[34:37], v[134:137], v[174:177], v[34:37]
	v_mfma_f32_16x16x32_bf16 v[22:25], v[110:113], v[182:185], v[22:25]
	v_mfma_f32_16x16x32_bf16 v[18:21], v[134:137], v[182:185], v[18:21]
	v_mfma_f32_16x16x32_bf16 v[6:9], v[110:113], v[190:193], v[6:9]
	v_mfma_f32_16x16x32_bf16 v[2:5], v[134:137], v[190:193], v[2:5]
	s_barrier
	s_setprio 0
	s_branch .Lpeel_mid_11

.Lpeel_mid_11:
	s_add_i32 s4, 0, 0x18000
	s_add_i32 s5, 0, 0x1c000
	ds_read_b128 v[78:81], v205 offset:32768
	ds_read_b128 v[82:85], v205 offset:33792
	ds_read_b128 v[94:97], v205 offset:34816
	ds_read_b128 v[98:101], v205 offset:35840
	ds_read_b128 v[106:109], v205 offset:49152
	ds_read_b128 v[110:113], v205 offset:50176
	ds_read_b128 v[126:129], v205 offset:51200
	ds_read_b128 v[134:137], v205 offset:52224
	s_add_u32 s0, s22, 0x160000
	s_addc_u32 s1, s23, 0
	s_mov_b32 m0, s29
	ds_read_b128 v[150:153], v239 offset:32768
	ds_read_b128 v[158:161], v239 offset:33792
	ds_read_b128 v[166:169], v239 offset:34816
	ds_read_b128 v[174:177], v239 offset:35840
	ds_read_b128 v[178:181], v239 offset:36864
	ds_read_b128 v[182:185], v239 offset:37888
	ds_read_b128 v[186:189], v239 offset:38912
	ds_read_b128 v[190:193], v239 offset:39936
	global_load_lds_dwordx4 v212, s[0:1]
	s_mov_b32 m0, s30
	s_nop 0
	global_load_lds_dwordx4 v210, s[0:1]
	s_waitcnt vmcnt(8)
	s_waitcnt lgkmcnt(0)
	s_setprio 1
	s_barrier
	v_mfma_f32_16x16x32_bf16 v[170:173], v[78:81], v[150:153], v[170:173]
	v_mfma_f32_16x16x32_bf16 v[162:165], v[94:97], v[150:153], v[162:165]
	v_mfma_f32_16x16x32_bf16 v[142:145], v[78:81], v[166:169], v[142:145]
	v_mfma_f32_16x16x32_bf16 v[138:141], v[94:97], v[166:169], v[138:141]
	v_mfma_f32_16x16x32_bf16 v[118:121], v[78:81], v[178:181], v[118:121]
	v_mfma_f32_16x16x32_bf16 v[114:117], v[94:97], v[178:181], v[114:117]
	v_mfma_f32_16x16x32_bf16 v[86:89], v[78:81], v[186:189], v[86:89]
	v_mfma_f32_16x16x32_bf16 v[74:77], v[94:97], v[186:189], v[74:77]
	v_mfma_f32_16x16x32_bf16 v[170:173], v[82:85], v[158:161], v[170:173]
	v_mfma_f32_16x16x32_bf16 v[162:165], v[98:101], v[158:161], v[162:165]
	v_mfma_f32_16x16x32_bf16 v[142:145], v[82:85], v[174:177], v[142:145]
	v_mfma_f32_16x16x32_bf16 v[138:141], v[98:101], v[174:177], v[138:141]
	v_mfma_f32_16x16x32_bf16 v[118:121], v[82:85], v[182:185], v[118:121]
	v_mfma_f32_16x16x32_bf16 v[114:117], v[98:101], v[182:185], v[114:117]
	v_mfma_f32_16x16x32_bf16 v[86:89], v[82:85], v[190:193], v[86:89]
	v_mfma_f32_16x16x32_bf16 v[74:77], v[98:101], v[190:193], v[74:77]
	v_mfma_f32_16x16x32_bf16 v[154:157], v[106:109], v[150:153], v[154:157]
	v_mfma_f32_16x16x32_bf16 v[146:149], v[126:129], v[150:153], v[146:149]
	v_mfma_f32_16x16x32_bf16 v[130:133], v[106:109], v[166:169], v[130:133]
	v_mfma_f32_16x16x32_bf16 v[122:125], v[126:129], v[166:169], v[122:125]
	v_mfma_f32_16x16x32_bf16 v[102:105], v[106:109], v[178:181], v[102:105]
	v_mfma_f32_16x16x32_bf16 v[90:93], v[126:129], v[178:181], v[90:93]
	v_mfma_f32_16x16x32_bf16 v[70:73], v[106:109], v[186:189], v[70:73]
	v_mfma_f32_16x16x32_bf16 v[66:69], v[126:129], v[186:189], v[66:69]
	v_mfma_f32_16x16x32_bf16 v[154:157], v[110:113], v[158:161], v[154:157]
	v_mfma_f32_16x16x32_bf16 v[150:153], v[134:137], v[158:161], v[146:149]
	v_mfma_f32_16x16x32_bf16 v[130:133], v[110:113], v[174:177], v[130:133]
	v_mfma_f32_16x16x32_bf16 v[122:125], v[134:137], v[174:177], v[122:125]
	v_mfma_f32_16x16x32_bf16 v[102:105], v[110:113], v[182:185], v[102:105]
	v_mfma_f32_16x16x32_bf16 v[90:93], v[134:137], v[182:185], v[90:93]
	v_mfma_f32_16x16x32_bf16 v[70:73], v[110:113], v[190:193], v[70:73]
	v_mfma_f32_16x16x32_bf16 v[66:69], v[134:137], v[190:193], v[66:69]
	s_barrier
	s_setprio 0
	s_add_i32 s0, s4, s26
	s_add_u32 s100, s20, 0x80
	s_addc_u32 s101, s21, 0
	s_mov_b32 m0, s0
	ds_read_b128 v[146:149], v239 offset:49152
	ds_read_b128 v[158:161], v239 offset:50176
	ds_read_b128 v[166:169], v239 offset:51200
	ds_read_b128 v[174:177], v239 offset:52224
	ds_read_b128 v[178:181], v239 offset:53248
	ds_read_b128 v[182:185], v239 offset:54272
	ds_read_b128 v[186:189], v239 offset:55296
	ds_read_b128 v[190:193], v239 offset:56320
	global_load_lds_dwordx4 v202, s[100:101]
	s_add_i32 m0, s0, 0x2000
	s_add_u32 s100, s20, 0x80
	s_addc_u32 s101, s21, 0
	s_add_u32 s0, s20, 0x160080
	s_addc_u32 s1, s21, 0
	s_add_i32 s4, s5, s26
	global_load_lds_dwordx4 v208, s[100:101]
	s_mov_b32 m0, s4
	s_nop 0
	global_load_lds_dwordx4 v202, s[0:1]
	s_add_i32 m0, s4, 0x2000
	s_nop 0
	global_load_lds_dwordx4 v208, s[0:1]
	s_add_u32 s100, s22, 0x80
	s_addc_u32 s101, s23, 0
	s_mov_b32 m0, s35
	s_nop 0
	global_load_lds_dwordx4 v212, s[100:101]
	s_add_u32 s100, s22, 0x80
	s_addc_u32 s101, s23, 0
	s_mov_b32 m0, s36
	s_nop 0
	global_load_lds_dwordx4 v210, s[100:101]
	s_waitcnt vmcnt(8)
	s_waitcnt lgkmcnt(0)
	s_setprio 1
	s_barrier
	v_mfma_f32_16x16x32_bf16 v[62:65], v[78:81], v[146:149], v[62:65]
	v_mfma_f32_16x16x32_bf16 v[58:61], v[94:97], v[146:149], v[58:61]
	v_mfma_f32_16x16x32_bf16 v[46:49], v[78:81], v[166:169], v[46:49]
	v_mfma_f32_16x16x32_bf16 v[42:45], v[94:97], v[166:169], v[42:45]
	v_mfma_f32_16x16x32_bf16 v[30:33], v[78:81], v[178:181], v[30:33]
	v_mfma_f32_16x16x32_bf16 v[26:29], v[94:97], v[178:181], v[26:29]
	v_mfma_f32_16x16x32_bf16 v[14:17], v[78:81], v[186:189], v[14:17]
	v_mfma_f32_16x16x32_bf16 v[10:13], v[94:97], v[186:189], v[10:13]
	v_mfma_f32_16x16x32_bf16 v[62:65], v[82:85], v[158:161], v[62:65]
	v_mfma_f32_16x16x32_bf16 v[58:61], v[98:101], v[158:161], v[58:61]
	v_mfma_f32_16x16x32_bf16 v[46:49], v[82:85], v[174:177], v[46:49]
	v_mfma_f32_16x16x32_bf16 v[42:45], v[98:101], v[174:177], v[42:45]
	v_mfma_f32_16x16x32_bf16 v[30:33], v[82:85], v[182:185], v[30:33]
	v_mfma_f32_16x16x32_bf16 v[26:29], v[98:101], v[182:185], v[26:29]
	v_mfma_f32_16x16x32_bf16 v[14:17], v[82:85], v[190:193], v[14:17]
	v_mfma_f32_16x16x32_bf16 v[10:13], v[98:101], v[190:193], v[10:13]
	v_mfma_f32_16x16x32_bf16 v[54:57], v[106:109], v[146:149], v[54:57]
	v_mfma_f32_16x16x32_bf16 v[50:53], v[126:129], v[146:149], v[50:53]
	v_mfma_f32_16x16x32_bf16 v[38:41], v[106:109], v[166:169], v[38:41]
	v_mfma_f32_16x16x32_bf16 v[34:37], v[126:129], v[166:169], v[34:37]
	v_mfma_f32_16x16x32_bf16 v[22:25], v[106:109], v[178:181], v[22:25]
	v_mfma_f32_16x16x32_bf16 v[18:21], v[126:129], v[178:181], v[18:21]
	v_mfma_f32_16x16x32_bf16 v[6:9], v[106:109], v[186:189], v[6:9]
	v_mfma_f32_16x16x32_bf16 v[2:5], v[126:129], v[186:189], v[2:5]
	v_mfma_f32_16x16x32_bf16 v[54:57], v[110:113], v[158:161], v[54:57]
	v_mfma_f32_16x16x32_bf16 v[50:53], v[134:137], v[158:161], v[50:53]
	v_mfma_f32_16x16x32_bf16 v[38:41], v[110:113], v[174:177], v[38:41]
	v_mfma_f32_16x16x32_bf16 v[34:37], v[134:137], v[174:177], v[34:37]
	v_mfma_f32_16x16x32_bf16 v[22:25], v[110:113], v[182:185], v[22:25]
	v_mfma_f32_16x16x32_bf16 v[18:21], v[134:137], v[182:185], v[18:21]
	v_mfma_f32_16x16x32_bf16 v[6:9], v[110:113], v[190:193], v[6:9]
	v_mfma_f32_16x16x32_bf16 v[2:5], v[134:137], v[190:193], v[2:5]
	s_barrier
	s_setprio 0
	s_add_i32 s59, s59, 2
	s_add_u32 s49, s49, 0x100
	s_addc_u32 s58, s58, 0
	s_cmpk_gt_u32 s59, 0x55
	s_mov_b64 s[4:5], s[18:19]
	s_cbranch_scc0 .LBB0_1718
	s_mov_b32 s101, 0x80000001
	s_and_b64 vcc, exec, s[14:15]
	s_cbranch_vccz .LBB0_1721
	s_barrier
